# MFMA block tails: s_barrier issued before s_setprio 0 (arrival signalled one issue slot earlier) in all GEMM K-loops
# speedup vs baseline: 1.0069x; 1.0023x over previous
.LBB0_179:
	ds_read_b128 v[144:147], v153
	ds_read_b128 v[156:159], v153 offset:1024
	ds_read_b128 v[162:165], v153 offset:2048
	ds_read_b128 v[166:169], v153 offset:3072
	ds_read_b128 v[170:173], v154
	ds_read_b128 v[174:177], v154 offset:1024
	ds_read_b128 v[178:181], v154 offset:2048
	ds_read_b128 v[182:185], v154 offset:3072
	s_add_u32 s70, s68, 0xfff80080
	s_addc_u32 s71, s69, -1
	s_cmp_eq_u32 s88, 28
	s_cselect_b32 s73, s1, s71
	s_cselect_b32 s72, s3, s70
	s_cselect_b32 s71, s59, s87
	s_cselect_b32 s70, s61, s86
	v_lshl_add_u64 v[148:149], s[68:69], 0, v[136:137]
	s_add_i32 m0, s29, 0xc000
	ds_read_b128 v[186:189], v155
	ds_read_b128 v[190:193], v155 offset:1024
	ds_read_b128 v[194:197], v155 offset:2048
	ds_read_b128 v[198:201], v155 offset:3072
	ds_read_b128 v[202:205], v155 offset:4096
	ds_read_b128 v[206:209], v155 offset:5120
	ds_read_b128 v[214:217], v155 offset:6144
	ds_read_b128 v[218:221], v155 offset:7168
	global_load_lds_dwordx4 v[148:149], off
	v_lshl_add_u64 v[148:149], s[68:69], 0, v[138:139]
	s_add_i32 m0, s29, 0xe000
	s_nop 0
	global_load_lds_dwordx4 v[148:149], off
	s_waitcnt vmcnt(8)
	s_waitcnt lgkmcnt(0)
	s_setprio 1
	s_barrier
	v_mfma_f32_16x16x32_bf16 v[124:127], v[144:147], v[186:189], v[124:127]
	v_mfma_f32_16x16x32_bf16 v[120:123], v[162:165], v[186:189], v[120:123]
	v_mfma_f32_16x16x32_bf16 v[108:111], v[144:147], v[194:197], v[108:111]
	v_mfma_f32_16x16x32_bf16 v[104:107], v[162:165], v[194:197], v[104:107]
	v_mfma_f32_16x16x32_bf16 v[92:95], v[144:147], v[202:205], v[92:95]
	v_mfma_f32_16x16x32_bf16 v[88:91], v[162:165], v[202:205], v[88:91]
	v_mfma_f32_16x16x32_bf16 v[76:79], v[144:147], v[214:217], v[76:79]
	v_mfma_f32_16x16x32_bf16 v[72:75], v[162:165], v[214:217], v[72:75]
	v_mfma_f32_16x16x32_bf16 v[124:127], v[156:159], v[190:193], v[124:127]
	v_mfma_f32_16x16x32_bf16 v[120:123], v[166:169], v[190:193], v[120:123]
	v_mfma_f32_16x16x32_bf16 v[108:111], v[156:159], v[198:201], v[108:111]
	v_mfma_f32_16x16x32_bf16 v[104:107], v[166:169], v[198:201], v[104:107]
	v_mfma_f32_16x16x32_bf16 v[92:95], v[156:159], v[206:209], v[92:95]
	v_mfma_f32_16x16x32_bf16 v[88:91], v[166:169], v[206:209], v[88:91]
	v_mfma_f32_16x16x32_bf16 v[76:79], v[156:159], v[218:221], v[76:79]
	v_mfma_f32_16x16x32_bf16 v[72:75], v[166:169], v[218:221], v[72:75]
	s_setprio 0
	s_setprio 1
	v_mfma_f32_16x16x32_bf16 v[116:119], v[170:173], v[186:189], v[116:119]
	v_mfma_f32_16x16x32_bf16 v[112:115], v[178:181], v[186:189], v[112:115]
	v_mfma_f32_16x16x32_bf16 v[100:103], v[170:173], v[194:197], v[100:103]
	v_mfma_f32_16x16x32_bf16 v[96:99], v[178:181], v[194:197], v[96:99]
	v_mfma_f32_16x16x32_bf16 v[84:87], v[170:173], v[202:205], v[84:87]
	v_mfma_f32_16x16x32_bf16 v[80:83], v[178:181], v[202:205], v[80:83]
	v_mfma_f32_16x16x32_bf16 v[68:71], v[170:173], v[214:217], v[68:71]
	v_mfma_f32_16x16x32_bf16 v[64:67], v[178:181], v[214:217], v[64:67]
	v_mfma_f32_16x16x32_bf16 v[116:119], v[174:177], v[190:193], v[116:119]
	v_mfma_f32_16x16x32_bf16 v[112:115], v[182:185], v[190:193], v[112:115]
	v_mfma_f32_16x16x32_bf16 v[100:103], v[174:177], v[198:201], v[100:103]
	v_mfma_f32_16x16x32_bf16 v[96:99], v[182:185], v[198:201], v[96:99]
	v_mfma_f32_16x16x32_bf16 v[84:87], v[174:177], v[206:209], v[84:87]
	v_mfma_f32_16x16x32_bf16 v[80:83], v[182:185], v[206:209], v[80:83]
	v_mfma_f32_16x16x32_bf16 v[68:71], v[174:177], v[218:221], v[68:71]
	v_mfma_f32_16x16x32_bf16 v[64:67], v[182:185], v[218:221], v[64:67]
	s_barrier
	s_setprio 0
	s_add_i32 s89, s79, s28
	v_lshl_add_u64 v[148:149], s[70:71], 0, v[132:133]
	s_mov_b32 m0, s89
	ds_read_b128 v[186:189], v155 offset:16384
	ds_read_b128 v[190:193], v155 offset:17408
	ds_read_b128 v[194:197], v155 offset:18432
	ds_read_b128 v[198:201], v155 offset:19456
	ds_read_b128 v[202:205], v155 offset:20480
	ds_read_b128 v[206:209], v155 offset:21504
	ds_read_b128 v[214:217], v155 offset:22528
	ds_read_b128 v[218:221], v155 offset:23552
	global_load_lds_dwordx4 v[148:149], off
	s_add_i32 m0, s89, 0x2000
	s_add_u32 s90, s70, 0x80000
	v_lshl_add_u64 v[210:211], s[70:71], 0, v[128:129]
	s_addc_u32 s91, s71, 0
	s_add_i32 s89, s80, s28
	global_load_lds_dwordx4 v[210:211], off
	v_lshl_add_u64 v[222:223], s[90:91], 0, v[132:133]
	s_mov_b32 m0, s89
	v_lshl_add_u64 v[224:225], s[72:73], 0, v[130:131]
	global_load_lds_dwordx4 v[222:223], off
	v_lshl_add_u64 v[222:223], s[90:91], 0, v[128:129]
	s_add_i32 m0, s89, 0x2000
	s_nop 0
	global_load_lds_dwordx4 v[222:223], off
	v_lshl_add_u64 v[222:223], s[72:73], 0, v[134:135]
	s_mov_b32 m0, s29
	s_nop 0
	global_load_lds_dwordx4 v[222:223], off
	s_mov_b32 m0, s30
	s_nop 0
	global_load_lds_dwordx4 v[224:225], off
	s_waitcnt vmcnt(8)
	s_waitcnt lgkmcnt(0)
	s_setprio 1
	s_barrier
	v_mfma_f32_16x16x32_bf16 v[60:63], v[144:147], v[186:189], v[60:63]
	v_mfma_f32_16x16x32_bf16 v[56:59], v[162:165], v[186:189], v[56:59]
	v_mfma_f32_16x16x32_bf16 v[44:47], v[144:147], v[194:197], v[44:47]
	v_mfma_f32_16x16x32_bf16 v[40:43], v[162:165], v[194:197], v[40:43]
	v_mfma_f32_16x16x32_bf16 v[28:31], v[144:147], v[202:205], v[28:31]
	v_mfma_f32_16x16x32_bf16 v[24:27], v[162:165], v[202:205], v[24:27]
	v_mfma_f32_16x16x32_bf16 v[12:15], v[144:147], v[214:217], v[12:15]
	v_mfma_f32_16x16x32_bf16 v[8:11], v[162:165], v[214:217], v[8:11]
	v_mfma_f32_16x16x32_bf16 v[60:63], v[156:159], v[190:193], v[60:63]
	v_mfma_f32_16x16x32_bf16 v[56:59], v[166:169], v[190:193], v[56:59]
	v_mfma_f32_16x16x32_bf16 v[44:47], v[156:159], v[198:201], v[44:47]
	v_mfma_f32_16x16x32_bf16 v[40:43], v[166:169], v[198:201], v[40:43]
	v_mfma_f32_16x16x32_bf16 v[28:31], v[156:159], v[206:209], v[28:31]
	v_mfma_f32_16x16x32_bf16 v[24:27], v[166:169], v[206:209], v[24:27]
	v_mfma_f32_16x16x32_bf16 v[12:15], v[156:159], v[218:221], v[12:15]
	v_mfma_f32_16x16x32_bf16 v[8:11], v[166:169], v[218:221], v[8:11]
	s_setprio 0
	s_setprio 1
	v_mfma_f32_16x16x32_bf16 v[52:55], v[170:173], v[186:189], v[52:55]
	v_mfma_f32_16x16x32_bf16 v[48:51], v[178:181], v[186:189], v[48:51]
	v_mfma_f32_16x16x32_bf16 v[36:39], v[170:173], v[194:197], v[36:39]
	v_mfma_f32_16x16x32_bf16 v[32:35], v[178:181], v[194:197], v[32:35]
	v_mfma_f32_16x16x32_bf16 v[20:23], v[170:173], v[202:205], v[20:23]
	v_mfma_f32_16x16x32_bf16 v[16:19], v[178:181], v[202:205], v[16:19]
	v_mfma_f32_16x16x32_bf16 v[4:7], v[170:173], v[214:217], v[4:7]
	v_mfma_f32_16x16x32_bf16 v[0:3], v[178:181], v[214:217], v[0:3]
	v_mfma_f32_16x16x32_bf16 v[52:55], v[174:177], v[190:193], v[52:55]
	v_mfma_f32_16x16x32_bf16 v[48:51], v[182:185], v[190:193], v[48:51]
	v_mfma_f32_16x16x32_bf16 v[36:39], v[174:177], v[198:201], v[36:39]
	v_mfma_f32_16x16x32_bf16 v[32:35], v[182:185], v[198:201], v[32:35]
	v_mfma_f32_16x16x32_bf16 v[20:23], v[174:177], v[206:209], v[20:23]
	v_mfma_f32_16x16x32_bf16 v[16:19], v[182:185], v[206:209], v[16:19]
	v_mfma_f32_16x16x32_bf16 v[4:7], v[174:177], v[218:221], v[4:7]
	v_mfma_f32_16x16x32_bf16 v[0:3], v[182:185], v[218:221], v[0:3]
	s_barrier
	s_setprio 0
	s_add_i32 s89, 0, 0x18000
	v_add_u32_e32 v161, s89, v151
	s_add_i32 s90, 0, 0x1c000
	ds_read_b128 v[144:147], v161
	ds_read_b128 v[156:159], v161 offset:1024
	ds_read_b128 v[162:165], v161 offset:2048
	ds_read_b128 v[166:169], v161 offset:3072
	v_add_u32_e32 v161, s90, v151
	ds_read_b128 v[170:173], v161
	ds_read_b128 v[174:177], v161 offset:1024
	ds_read_b128 v[178:181], v161 offset:2048
	ds_read_b128 v[182:185], v161 offset:3072
	s_add_u32 s72, s72, 0x80000
	s_addc_u32 s73, s73, 0
	s_mov_b32 m0, s31
	v_lshl_add_u64 v[226:227], s[72:73], 0, v[134:135]
	ds_read_b128 v[186:189], v155 offset:32768
	ds_read_b128 v[190:193], v155 offset:33792
	ds_read_b128 v[194:197], v155 offset:34816
	ds_read_b128 v[198:201], v155 offset:35840
	ds_read_b128 v[202:205], v155 offset:36864
	ds_read_b128 v[206:209], v155 offset:37888
	ds_read_b128 v[214:217], v155 offset:38912
	ds_read_b128 v[218:221], v155 offset:39936
	global_load_lds_dwordx4 v[226:227], off
	v_lshl_add_u64 v[226:227], s[72:73], 0, v[130:131]
	s_mov_b32 m0, s37
	s_nop 0
	global_load_lds_dwordx4 v[226:227], off
	s_waitcnt vmcnt(8)
	s_waitcnt lgkmcnt(0)
	s_setprio 1
	s_barrier
	v_mfma_f32_16x16x32_bf16 v[124:127], v[144:147], v[186:189], v[124:127]
	v_mfma_f32_16x16x32_bf16 v[120:123], v[162:165], v[186:189], v[120:123]
	v_mfma_f32_16x16x32_bf16 v[108:111], v[144:147], v[194:197], v[108:111]
	v_mfma_f32_16x16x32_bf16 v[104:107], v[162:165], v[194:197], v[104:107]
	v_mfma_f32_16x16x32_bf16 v[92:95], v[144:147], v[202:205], v[92:95]
	v_mfma_f32_16x16x32_bf16 v[88:91], v[162:165], v[202:205], v[88:91]
	v_mfma_f32_16x16x32_bf16 v[76:79], v[144:147], v[214:217], v[76:79]
	v_mfma_f32_16x16x32_bf16 v[72:75], v[162:165], v[214:217], v[72:75]
	v_mfma_f32_16x16x32_bf16 v[124:127], v[156:159], v[190:193], v[124:127]
	v_mfma_f32_16x16x32_bf16 v[120:123], v[166:169], v[190:193], v[120:123]
	v_mfma_f32_16x16x32_bf16 v[108:111], v[156:159], v[198:201], v[108:111]
	v_mfma_f32_16x16x32_bf16 v[104:107], v[166:169], v[198:201], v[104:107]
	v_mfma_f32_16x16x32_bf16 v[92:95], v[156:159], v[206:209], v[92:95]
	v_mfma_f32_16x16x32_bf16 v[88:91], v[166:169], v[206:209], v[88:91]
	v_mfma_f32_16x16x32_bf16 v[76:79], v[156:159], v[218:221], v[76:79]
	v_mfma_f32_16x16x32_bf16 v[72:75], v[166:169], v[218:221], v[72:75]
	s_setprio 0
	s_setprio 1
	v_mfma_f32_16x16x32_bf16 v[116:119], v[170:173], v[186:189], v[116:119]
	v_mfma_f32_16x16x32_bf16 v[112:115], v[178:181], v[186:189], v[112:115]
	v_mfma_f32_16x16x32_bf16 v[100:103], v[170:173], v[194:197], v[100:103]
	v_mfma_f32_16x16x32_bf16 v[96:99], v[178:181], v[194:197], v[96:99]
	v_mfma_f32_16x16x32_bf16 v[84:87], v[170:173], v[202:205], v[84:87]
	v_mfma_f32_16x16x32_bf16 v[80:83], v[178:181], v[202:205], v[80:83]
	v_mfma_f32_16x16x32_bf16 v[68:71], v[170:173], v[214:217], v[68:71]
	v_mfma_f32_16x16x32_bf16 v[64:67], v[178:181], v[214:217], v[64:67]
	v_mfma_f32_16x16x32_bf16 v[116:119], v[174:177], v[190:193], v[116:119]
	v_mfma_f32_16x16x32_bf16 v[112:115], v[182:185], v[190:193], v[112:115]
	v_mfma_f32_16x16x32_bf16 v[100:103], v[174:177], v[198:201], v[100:103]
	v_mfma_f32_16x16x32_bf16 v[96:99], v[182:185], v[198:201], v[96:99]
	v_mfma_f32_16x16x32_bf16 v[84:87], v[174:177], v[206:209], v[84:87]
	v_mfma_f32_16x16x32_bf16 v[80:83], v[182:185], v[206:209], v[80:83]
	v_mfma_f32_16x16x32_bf16 v[68:71], v[174:177], v[218:221], v[68:71]
	v_mfma_f32_16x16x32_bf16 v[64:67], v[182:185], v[218:221], v[64:67]
	s_barrier
	s_setprio 0
	s_add_i32 s72, s89, s28
	v_lshl_add_u64 v[148:149], v[148:149], 0, s[26:27]
	s_mov_b32 m0, s72
	ds_read_b128 v[186:189], v155 offset:49152
	ds_read_b128 v[190:193], v155 offset:50176
	ds_read_b128 v[194:197], v155 offset:51200
	ds_read_b128 v[198:201], v155 offset:52224
	ds_read_b128 v[202:205], v155 offset:53248
	ds_read_b128 v[206:209], v155 offset:54272
	ds_read_b128 v[214:217], v155 offset:55296
	ds_read_b128 v[218:221], v155 offset:56320
	global_load_lds_dwordx4 v[148:149], off
	s_add_i32 m0, s72, 0x2000
	s_add_u32 s70, s70, 0x80080
	v_lshl_add_u64 v[148:149], v[210:211], 0, s[26:27]
	s_addc_u32 s71, s71, 0
	s_add_i32 s72, s90, s28
	global_load_lds_dwordx4 v[148:149], off
	v_lshl_add_u64 v[148:149], s[70:71], 0, v[132:133]
	s_mov_b32 m0, s72
	s_nop 0
	global_load_lds_dwordx4 v[148:149], off
	v_lshl_add_u64 v[148:149], s[70:71], 0, v[128:129]
	s_add_i32 m0, s72, 0x2000
	s_nop 0
	global_load_lds_dwordx4 v[148:149], off
	v_lshl_add_u64 v[148:149], v[222:223], 0, s[26:27]
	s_mov_b32 m0, s76
	s_nop 0
	global_load_lds_dwordx4 v[148:149], off
	v_lshl_add_u64 v[148:149], v[224:225], 0, s[26:27]
	s_mov_b32 m0, s77
	s_nop 0
	global_load_lds_dwordx4 v[148:149], off
	s_waitcnt vmcnt(8)
	s_waitcnt lgkmcnt(0)
	s_setprio 1
	s_barrier
	v_mfma_f32_16x16x32_bf16 v[60:63], v[144:147], v[186:189], v[60:63]
	v_mfma_f32_16x16x32_bf16 v[56:59], v[162:165], v[186:189], v[56:59]
	v_mfma_f32_16x16x32_bf16 v[44:47], v[144:147], v[194:197], v[44:47]
	v_mfma_f32_16x16x32_bf16 v[40:43], v[162:165], v[194:197], v[40:43]
	v_mfma_f32_16x16x32_bf16 v[28:31], v[144:147], v[202:205], v[28:31]
	v_mfma_f32_16x16x32_bf16 v[24:27], v[162:165], v[202:205], v[24:27]
	v_mfma_f32_16x16x32_bf16 v[12:15], v[144:147], v[214:217], v[12:15]
	v_mfma_f32_16x16x32_bf16 v[8:11], v[162:165], v[214:217], v[8:11]
	v_mfma_f32_16x16x32_bf16 v[60:63], v[156:159], v[190:193], v[60:63]
	v_mfma_f32_16x16x32_bf16 v[56:59], v[166:169], v[190:193], v[56:59]
	v_mfma_f32_16x16x32_bf16 v[44:47], v[156:159], v[198:201], v[44:47]
	v_mfma_f32_16x16x32_bf16 v[40:43], v[166:169], v[198:201], v[40:43]
	v_mfma_f32_16x16x32_bf16 v[28:31], v[156:159], v[206:209], v[28:31]
	v_mfma_f32_16x16x32_bf16 v[24:27], v[166:169], v[206:209], v[24:27]
	v_mfma_f32_16x16x32_bf16 v[12:15], v[156:159], v[218:221], v[12:15]
	v_mfma_f32_16x16x32_bf16 v[8:11], v[166:169], v[218:221], v[8:11]
	s_setprio 0
	s_setprio 1
	v_mfma_f32_16x16x32_bf16 v[52:55], v[170:173], v[186:189], v[52:55]
	v_mfma_f32_16x16x32_bf16 v[48:51], v[178:181], v[186:189], v[48:51]
	v_mfma_f32_16x16x32_bf16 v[36:39], v[170:173], v[194:197], v[36:39]
	v_mfma_f32_16x16x32_bf16 v[32:35], v[178:181], v[194:197], v[32:35]
	v_mfma_f32_16x16x32_bf16 v[20:23], v[170:173], v[202:205], v[20:23]
	v_mfma_f32_16x16x32_bf16 v[16:19], v[178:181], v[202:205], v[16:19]
	v_mfma_f32_16x16x32_bf16 v[4:7], v[170:173], v[214:217], v[4:7]
	v_mfma_f32_16x16x32_bf16 v[0:3], v[178:181], v[214:217], v[0:3]
	v_mfma_f32_16x16x32_bf16 v[52:55], v[174:177], v[190:193], v[52:55]
	v_mfma_f32_16x16x32_bf16 v[48:51], v[182:185], v[190:193], v[48:51]
	v_mfma_f32_16x16x32_bf16 v[36:39], v[174:177], v[198:201], v[36:39]
	v_mfma_f32_16x16x32_bf16 v[32:35], v[182:185], v[198:201], v[32:35]
	v_mfma_f32_16x16x32_bf16 v[20:23], v[174:177], v[206:209], v[20:23]
	v_mfma_f32_16x16x32_bf16 v[16:19], v[182:185], v[206:209], v[16:19]
	v_mfma_f32_16x16x32_bf16 v[4:7], v[174:177], v[218:221], v[4:7]
	v_mfma_f32_16x16x32_bf16 v[0:3], v[182:185], v[218:221], v[0:3]
	s_barrier
	s_setprio 0
	s_add_i32 s88, s88, 2
	s_add_u32 s68, s68, 0x100
	s_addc_u32 s69, s69, 0
	s_add_u32 s86, s86, 0x100
	s_addc_u32 s87, s87, 0
	s_cmp_gt_u32 s88, 29
	s_cbranch_scc0 .LBB0_179
	s_and_b64 vcc, exec, s[34:35]
	s_cbranch_vccz .LBB0_182
	s_barrier

.LBB0_208:
	ds_read_b128 v[144:147], v164
	ds_read_b128 v[148:151], v164 offset:1024
	ds_read_b128 v[152:155], v164 offset:2048
	ds_read_b128 v[156:159], v164 offset:3072
	ds_read_b128 v[168:171], v165
	ds_read_b128 v[172:175], v165 offset:1024
	ds_read_b128 v[176:179], v165 offset:2048
	ds_read_b128 v[180:183], v165 offset:3072
	s_add_u32 s70, s68, 0xfff80080
	s_addc_u32 s71, s69, -1
	s_cmp_eq_u32 s67, 28
	s_cselect_b32 s73, s0, s71
	s_cselect_b32 s72, s1, s70
	s_cselect_b32 s71, s3, s65
	s_cselect_b32 s70, s57, s59
	v_lshl_add_u64 v[218:219], s[68:69], 0, v[136:137]
	s_add_i32 m0, s31, 0xc000
	ds_read_b128 v[184:187], v166
	ds_read_b128 v[188:191], v166 offset:1024
	ds_read_b128 v[192:195], v166 offset:2048
	ds_read_b128 v[196:199], v166 offset:3072
	ds_read_b128 v[200:203], v166 offset:4096
	ds_read_b128 v[204:207], v166 offset:5120
	ds_read_b128 v[208:211], v166 offset:6144
	ds_read_b128 v[214:217], v166 offset:7168
	global_load_lds_dwordx4 v[218:219], off
	v_lshl_add_u64 v[218:219], s[68:69], 0, v[138:139]
	s_add_i32 m0, s31, 0xe000
	s_nop 0
	global_load_lds_dwordx4 v[218:219], off
	s_waitcnt vmcnt(8)
	s_waitcnt lgkmcnt(0)
	s_setprio 1
	s_barrier
	v_mfma_f32_16x16x32_bf16 v[124:127], v[144:147], v[184:187], v[124:127]
	v_mfma_f32_16x16x32_bf16 v[120:123], v[152:155], v[184:187], v[120:123]
	v_mfma_f32_16x16x32_bf16 v[108:111], v[144:147], v[192:195], v[108:111]
	v_mfma_f32_16x16x32_bf16 v[104:107], v[152:155], v[192:195], v[104:107]
	v_mfma_f32_16x16x32_bf16 v[92:95], v[144:147], v[200:203], v[92:95]
	v_mfma_f32_16x16x32_bf16 v[88:91], v[152:155], v[200:203], v[88:91]
	v_mfma_f32_16x16x32_bf16 v[76:79], v[144:147], v[208:211], v[76:79]
	v_mfma_f32_16x16x32_bf16 v[72:75], v[152:155], v[208:211], v[72:75]
	v_mfma_f32_16x16x32_bf16 v[124:127], v[148:151], v[188:191], v[124:127]
	v_mfma_f32_16x16x32_bf16 v[120:123], v[156:159], v[188:191], v[120:123]
	v_mfma_f32_16x16x32_bf16 v[108:111], v[148:151], v[196:199], v[108:111]
	v_mfma_f32_16x16x32_bf16 v[104:107], v[156:159], v[196:199], v[104:107]
	v_mfma_f32_16x16x32_bf16 v[92:95], v[148:151], v[204:207], v[92:95]
	v_mfma_f32_16x16x32_bf16 v[88:91], v[156:159], v[204:207], v[88:91]
	v_mfma_f32_16x16x32_bf16 v[76:79], v[148:151], v[214:217], v[76:79]
	v_mfma_f32_16x16x32_bf16 v[72:75], v[156:159], v[214:217], v[72:75]
	s_setprio 0
	s_setprio 1
	v_mfma_f32_16x16x32_bf16 v[116:119], v[168:171], v[184:187], v[116:119]
	v_mfma_f32_16x16x32_bf16 v[112:115], v[176:179], v[184:187], v[112:115]
	v_mfma_f32_16x16x32_bf16 v[100:103], v[168:171], v[192:195], v[100:103]
	v_mfma_f32_16x16x32_bf16 v[96:99], v[176:179], v[192:195], v[96:99]
	v_mfma_f32_16x16x32_bf16 v[84:87], v[168:171], v[200:203], v[84:87]
	v_mfma_f32_16x16x32_bf16 v[80:83], v[176:179], v[200:203], v[80:83]
	v_mfma_f32_16x16x32_bf16 v[68:71], v[168:171], v[208:211], v[68:71]
	v_mfma_f32_16x16x32_bf16 v[64:67], v[176:179], v[208:211], v[64:67]
	v_mfma_f32_16x16x32_bf16 v[116:119], v[172:175], v[188:191], v[116:119]
	v_mfma_f32_16x16x32_bf16 v[112:115], v[180:183], v[188:191], v[112:115]
	v_mfma_f32_16x16x32_bf16 v[100:103], v[172:175], v[196:199], v[100:103]
	v_mfma_f32_16x16x32_bf16 v[96:99], v[180:183], v[196:199], v[96:99]
	v_mfma_f32_16x16x32_bf16 v[84:87], v[172:175], v[204:207], v[84:87]
	v_mfma_f32_16x16x32_bf16 v[80:83], v[180:183], v[204:207], v[80:83]
	v_mfma_f32_16x16x32_bf16 v[68:71], v[172:175], v[214:217], v[68:71]
	v_mfma_f32_16x16x32_bf16 v[64:67], v[180:183], v[214:217], v[64:67]
	s_barrier
	s_setprio 0
	s_add_i32 s90, s84, s30
	v_lshl_add_u64 v[218:219], s[70:71], 0, v[130:131]
	s_mov_b32 m0, s90
	ds_read_b128 v[184:187], v166 offset:16384
	ds_read_b128 v[188:191], v166 offset:17408
	ds_read_b128 v[192:195], v166 offset:18432
	ds_read_b128 v[196:199], v166 offset:19456
	ds_read_b128 v[200:203], v166 offset:20480
	ds_read_b128 v[204:207], v166 offset:21504
	ds_read_b128 v[208:211], v166 offset:22528
	ds_read_b128 v[214:217], v166 offset:23552
	global_load_lds_dwordx4 v[218:219], off
	s_add_i32 m0, s90, 0x2000
	s_add_u32 s90, s70, 0x80000
	v_lshl_add_u64 v[220:221], s[70:71], 0, v[134:135]
	s_addc_u32 s91, s71, 0
	s_add_i32 s92, s85, s30
	global_load_lds_dwordx4 v[220:221], off
	v_lshl_add_u64 v[222:223], s[90:91], 0, v[130:131]
	s_mov_b32 m0, s92
	v_lshl_add_u64 v[224:225], s[72:73], 0, v[132:133]
	global_load_lds_dwordx4 v[222:223], off
	v_lshl_add_u64 v[222:223], s[90:91], 0, v[134:135]
	s_add_i32 m0, s92, 0x2000
	s_nop 0
	global_load_lds_dwordx4 v[222:223], off
	v_lshl_add_u64 v[222:223], s[72:73], 0, v[128:129]
	s_mov_b32 m0, s31
	s_nop 0
	global_load_lds_dwordx4 v[222:223], off
	s_mov_b32 m0, s76
	s_nop 0
	global_load_lds_dwordx4 v[224:225], off
	s_waitcnt vmcnt(8)
	s_waitcnt lgkmcnt(0)
	s_setprio 1
	s_barrier
	v_mfma_f32_16x16x32_bf16 v[60:63], v[144:147], v[184:187], v[60:63]
	v_mfma_f32_16x16x32_bf16 v[56:59], v[152:155], v[184:187], v[56:59]
	v_mfma_f32_16x16x32_bf16 v[44:47], v[144:147], v[192:195], v[44:47]
	v_mfma_f32_16x16x32_bf16 v[40:43], v[152:155], v[192:195], v[40:43]
	v_mfma_f32_16x16x32_bf16 v[28:31], v[144:147], v[200:203], v[28:31]
	v_mfma_f32_16x16x32_bf16 v[24:27], v[152:155], v[200:203], v[24:27]
	v_mfma_f32_16x16x32_bf16 v[12:15], v[144:147], v[208:211], v[12:15]
	v_mfma_f32_16x16x32_bf16 v[8:11], v[152:155], v[208:211], v[8:11]
	v_mfma_f32_16x16x32_bf16 v[60:63], v[148:151], v[188:191], v[60:63]
	v_mfma_f32_16x16x32_bf16 v[56:59], v[156:159], v[188:191], v[56:59]
	v_mfma_f32_16x16x32_bf16 v[44:47], v[148:151], v[196:199], v[44:47]
	v_mfma_f32_16x16x32_bf16 v[40:43], v[156:159], v[196:199], v[40:43]
	v_mfma_f32_16x16x32_bf16 v[28:31], v[148:151], v[204:207], v[28:31]
	v_mfma_f32_16x16x32_bf16 v[24:27], v[156:159], v[204:207], v[24:27]
	v_mfma_f32_16x16x32_bf16 v[12:15], v[148:151], v[214:217], v[12:15]
	v_mfma_f32_16x16x32_bf16 v[8:11], v[156:159], v[214:217], v[8:11]
	s_setprio 0
	s_setprio 1
	v_mfma_f32_16x16x32_bf16 v[52:55], v[168:171], v[184:187], v[52:55]
	v_mfma_f32_16x16x32_bf16 v[48:51], v[176:179], v[184:187], v[48:51]
	v_mfma_f32_16x16x32_bf16 v[36:39], v[168:171], v[192:195], v[36:39]
	v_mfma_f32_16x16x32_bf16 v[32:35], v[176:179], v[192:195], v[32:35]
	v_mfma_f32_16x16x32_bf16 v[20:23], v[168:171], v[200:203], v[20:23]
	v_mfma_f32_16x16x32_bf16 v[16:19], v[176:179], v[200:203], v[16:19]
	v_mfma_f32_16x16x32_bf16 v[4:7], v[168:171], v[208:211], v[4:7]
	v_mfma_f32_16x16x32_bf16 v[0:3], v[176:179], v[208:211], v[0:3]
	v_mfma_f32_16x16x32_bf16 v[52:55], v[172:175], v[188:191], v[52:55]
	v_mfma_f32_16x16x32_bf16 v[48:51], v[180:183], v[188:191], v[48:51]
	v_mfma_f32_16x16x32_bf16 v[36:39], v[172:175], v[196:199], v[36:39]
	v_mfma_f32_16x16x32_bf16 v[32:35], v[180:183], v[196:199], v[32:35]
	v_mfma_f32_16x16x32_bf16 v[20:23], v[172:175], v[204:207], v[20:23]
	v_mfma_f32_16x16x32_bf16 v[16:19], v[180:183], v[204:207], v[16:19]
	v_mfma_f32_16x16x32_bf16 v[4:7], v[172:175], v[214:217], v[4:7]
	v_mfma_f32_16x16x32_bf16 v[0:3], v[180:183], v[214:217], v[0:3]
	s_barrier
	s_setprio 0
	s_add_i32 s90, 0, 0x18000
	s_add_i32 s91, 0, 0x1c000
	v_add_u32_e32 v156, s90, v162
	v_add_u32_e32 v167, s91, v162
	ds_read_b128 v[144:147], v156
	ds_read_b128 v[148:151], v156 offset:1024
	ds_read_b128 v[152:155], v156 offset:2048
	ds_read_b128 v[156:159], v156 offset:3072
	ds_read_b128 v[168:171], v167
	ds_read_b128 v[172:175], v167 offset:1024
	ds_read_b128 v[176:179], v167 offset:2048
	ds_read_b128 v[180:183], v167 offset:3072
	s_add_u32 s72, s72, 0x80000
	s_addc_u32 s73, s73, 0
	s_mov_b32 m0, s77
	v_lshl_add_u64 v[226:227], s[72:73], 0, v[128:129]
	ds_read_b128 v[184:187], v166 offset:32768
	ds_read_b128 v[188:191], v166 offset:33792
	ds_read_b128 v[192:195], v166 offset:34816
	ds_read_b128 v[196:199], v166 offset:35840
	ds_read_b128 v[200:203], v166 offset:36864
	ds_read_b128 v[204:207], v166 offset:37888
	ds_read_b128 v[208:211], v166 offset:38912
	ds_read_b128 v[214:217], v166 offset:39936
	global_load_lds_dwordx4 v[226:227], off
	v_lshl_add_u64 v[226:227], s[72:73], 0, v[132:133]
	s_mov_b32 m0, s78
	s_nop 0
	global_load_lds_dwordx4 v[226:227], off
	s_waitcnt vmcnt(8)
	s_waitcnt lgkmcnt(0)
	s_setprio 1
	s_barrier
	v_mfma_f32_16x16x32_bf16 v[124:127], v[144:147], v[184:187], v[124:127]
	v_mfma_f32_16x16x32_bf16 v[120:123], v[152:155], v[184:187], v[120:123]
	v_mfma_f32_16x16x32_bf16 v[108:111], v[144:147], v[192:195], v[108:111]
	v_mfma_f32_16x16x32_bf16 v[104:107], v[152:155], v[192:195], v[104:107]
	v_mfma_f32_16x16x32_bf16 v[92:95], v[144:147], v[200:203], v[92:95]
	v_mfma_f32_16x16x32_bf16 v[88:91], v[152:155], v[200:203], v[88:91]
	v_mfma_f32_16x16x32_bf16 v[76:79], v[144:147], v[208:211], v[76:79]
	v_mfma_f32_16x16x32_bf16 v[72:75], v[152:155], v[208:211], v[72:75]
	v_mfma_f32_16x16x32_bf16 v[124:127], v[148:151], v[188:191], v[124:127]
	v_mfma_f32_16x16x32_bf16 v[120:123], v[156:159], v[188:191], v[120:123]
	v_mfma_f32_16x16x32_bf16 v[108:111], v[148:151], v[196:199], v[108:111]
	v_mfma_f32_16x16x32_bf16 v[104:107], v[156:159], v[196:199], v[104:107]
	v_mfma_f32_16x16x32_bf16 v[92:95], v[148:151], v[204:207], v[92:95]
	v_mfma_f32_16x16x32_bf16 v[88:91], v[156:159], v[204:207], v[88:91]
	v_mfma_f32_16x16x32_bf16 v[76:79], v[148:151], v[214:217], v[76:79]
	v_mfma_f32_16x16x32_bf16 v[72:75], v[156:159], v[214:217], v[72:75]
	s_setprio 0
	s_setprio 1
	v_mfma_f32_16x16x32_bf16 v[116:119], v[168:171], v[184:187], v[116:119]
	v_mfma_f32_16x16x32_bf16 v[112:115], v[176:179], v[184:187], v[112:115]
	v_mfma_f32_16x16x32_bf16 v[100:103], v[168:171], v[192:195], v[100:103]
	v_mfma_f32_16x16x32_bf16 v[96:99], v[176:179], v[192:195], v[96:99]
	v_mfma_f32_16x16x32_bf16 v[84:87], v[168:171], v[200:203], v[84:87]
	v_mfma_f32_16x16x32_bf16 v[80:83], v[176:179], v[200:203], v[80:83]
	v_mfma_f32_16x16x32_bf16 v[68:71], v[168:171], v[208:211], v[68:71]
	v_mfma_f32_16x16x32_bf16 v[64:67], v[176:179], v[208:211], v[64:67]
	v_mfma_f32_16x16x32_bf16 v[116:119], v[172:175], v[188:191], v[116:119]
	v_mfma_f32_16x16x32_bf16 v[112:115], v[180:183], v[188:191], v[112:115]
	v_mfma_f32_16x16x32_bf16 v[100:103], v[172:175], v[196:199], v[100:103]
	v_mfma_f32_16x16x32_bf16 v[96:99], v[180:183], v[196:199], v[96:99]
	v_mfma_f32_16x16x32_bf16 v[84:87], v[172:175], v[204:207], v[84:87]
	v_mfma_f32_16x16x32_bf16 v[80:83], v[180:183], v[204:207], v[80:83]
	v_mfma_f32_16x16x32_bf16 v[68:71], v[172:175], v[214:217], v[68:71]
	v_mfma_f32_16x16x32_bf16 v[64:67], v[180:183], v[214:217], v[64:67]
	s_barrier
	s_setprio 0
	s_add_i32 s72, s90, s30
	v_lshl_add_u64 v[218:219], v[218:219], 0, s[34:35]
	s_mov_b32 m0, s72
	ds_read_b128 v[184:187], v166 offset:49152
	ds_read_b128 v[188:191], v166 offset:50176
	ds_read_b128 v[192:195], v166 offset:51200
	ds_read_b128 v[196:199], v166 offset:52224
	ds_read_b128 v[200:203], v166 offset:53248
	ds_read_b128 v[204:207], v166 offset:54272
	ds_read_b128 v[208:211], v166 offset:55296
	ds_read_b128 v[214:217], v166 offset:56320
	global_load_lds_dwordx4 v[218:219], off
	s_add_i32 m0, s72, 0x2000
	s_add_u32 s70, s70, 0x80080
	v_lshl_add_u64 v[218:219], v[220:221], 0, s[34:35]
	s_addc_u32 s71, s71, 0
	s_add_i32 s72, s91, s30
	global_load_lds_dwordx4 v[218:219], off
	v_lshl_add_u64 v[218:219], s[70:71], 0, v[130:131]
	s_mov_b32 m0, s72
	s_nop 0
	global_load_lds_dwordx4 v[218:219], off
	v_lshl_add_u64 v[218:219], s[70:71], 0, v[134:135]
	s_add_i32 m0, s72, 0x2000
	s_nop 0
	global_load_lds_dwordx4 v[218:219], off
	v_lshl_add_u64 v[218:219], v[222:223], 0, s[34:35]
	s_mov_b32 m0, s80
	s_nop 0
	global_load_lds_dwordx4 v[218:219], off
	v_lshl_add_u64 v[218:219], v[224:225], 0, s[34:35]
	s_mov_b32 m0, s81
	s_nop 0
	global_load_lds_dwordx4 v[218:219], off
	s_waitcnt vmcnt(8)
	s_waitcnt lgkmcnt(0)
	s_setprio 1
	s_barrier
	v_mfma_f32_16x16x32_bf16 v[60:63], v[144:147], v[184:187], v[60:63]
	v_mfma_f32_16x16x32_bf16 v[56:59], v[152:155], v[184:187], v[56:59]
	v_mfma_f32_16x16x32_bf16 v[44:47], v[144:147], v[192:195], v[44:47]
	v_mfma_f32_16x16x32_bf16 v[40:43], v[152:155], v[192:195], v[40:43]
	v_mfma_f32_16x16x32_bf16 v[28:31], v[144:147], v[200:203], v[28:31]
	v_mfma_f32_16x16x32_bf16 v[24:27], v[152:155], v[200:203], v[24:27]
	v_mfma_f32_16x16x32_bf16 v[12:15], v[144:147], v[208:211], v[12:15]
	v_mfma_f32_16x16x32_bf16 v[8:11], v[152:155], v[208:211], v[8:11]
	v_mfma_f32_16x16x32_bf16 v[60:63], v[148:151], v[188:191], v[60:63]
	v_mfma_f32_16x16x32_bf16 v[56:59], v[156:159], v[188:191], v[56:59]
	v_mfma_f32_16x16x32_bf16 v[44:47], v[148:151], v[196:199], v[44:47]
	v_mfma_f32_16x16x32_bf16 v[40:43], v[156:159], v[196:199], v[40:43]
	v_mfma_f32_16x16x32_bf16 v[28:31], v[148:151], v[204:207], v[28:31]
	v_mfma_f32_16x16x32_bf16 v[24:27], v[156:159], v[204:207], v[24:27]
	v_mfma_f32_16x16x32_bf16 v[12:15], v[148:151], v[214:217], v[12:15]
	v_mfma_f32_16x16x32_bf16 v[8:11], v[156:159], v[214:217], v[8:11]
	s_setprio 0
	s_setprio 1
	v_mfma_f32_16x16x32_bf16 v[52:55], v[168:171], v[184:187], v[52:55]
	v_mfma_f32_16x16x32_bf16 v[48:51], v[176:179], v[184:187], v[48:51]
	v_mfma_f32_16x16x32_bf16 v[36:39], v[168:171], v[192:195], v[36:39]
	v_mfma_f32_16x16x32_bf16 v[32:35], v[176:179], v[192:195], v[32:35]
	v_mfma_f32_16x16x32_bf16 v[20:23], v[168:171], v[200:203], v[20:23]
	v_mfma_f32_16x16x32_bf16 v[16:19], v[176:179], v[200:203], v[16:19]
	v_mfma_f32_16x16x32_bf16 v[4:7], v[168:171], v[208:211], v[4:7]
	v_mfma_f32_16x16x32_bf16 v[0:3], v[176:179], v[208:211], v[0:3]
	v_mfma_f32_16x16x32_bf16 v[52:55], v[172:175], v[188:191], v[52:55]
	v_mfma_f32_16x16x32_bf16 v[48:51], v[180:183], v[188:191], v[48:51]
	v_mfma_f32_16x16x32_bf16 v[36:39], v[172:175], v[196:199], v[36:39]
	v_mfma_f32_16x16x32_bf16 v[32:35], v[180:183], v[196:199], v[32:35]
	v_mfma_f32_16x16x32_bf16 v[20:23], v[172:175], v[204:207], v[20:23]
	v_mfma_f32_16x16x32_bf16 v[16:19], v[180:183], v[204:207], v[16:19]
	v_mfma_f32_16x16x32_bf16 v[4:7], v[172:175], v[214:217], v[4:7]
	v_mfma_f32_16x16x32_bf16 v[0:3], v[180:183], v[214:217], v[0:3]
	s_barrier
	s_setprio 0
	s_add_i32 s67, s67, 2
	s_add_u32 s68, s68, 0x100
	s_addc_u32 s69, s69, 0
	s_add_u32 s59, s59, 0x100
	s_addc_u32 s65, s65, 0
	s_cmp_gt_u32 s67, 29
	s_cbranch_scc0 .LBB0_208
	s_and_b64 vcc, exec, s[36:37]
	s_cbranch_vccz .LBB0_211
	s_barrier

.LBB0_271:
	s_ashr_i32 s63, s62, 31
	s_lshl_b64 s[0:1], s[62:63], 20
	s_add_u32 s66, s49, s0
	s_addc_u32 s67, s82, s1
	s_and_b64 s[0:1], s[4:5], exec
	s_cselect_b32 s0, s67, s75
	s_cselect_b32 s1, s66, s74
	s_ashr_i32 s65, s64, 31
	s_lshl_b64 s[68:69], s[64:65], 20
	s_add_u32 s68, s45, s68
	s_addc_u32 s69, s47, s69
	s_and_b64 s[78:79], s[4:5], exec
	s_cselect_b32 s3, s69, s77
	s_cselect_b32 s63, s68, s76
	s_add_u32 s74, s74, 0x80080
	s_addc_u32 s75, s75, 0
	s_add_u32 s65, s76, 0x100
	s_addc_u32 s71, s77, 0
	s_mov_b32 s90, -2
	s_waitcnt vmcnt(0)
	ds_read_b128 v[146:149], v166
	ds_read_b128 v[150:153], v166 offset:1024
	ds_read_b128 v[154:157], v166 offset:2048
	ds_read_b128 v[170:173], v166 offset:3072
	ds_read_b128 v[174:177], v167
	ds_read_b128 v[178:181], v167 offset:1024
	ds_read_b128 v[182:185], v167 offset:2048
	ds_read_b128 v[186:189], v167 offset:3072
	s_add_u32 s76, s74, 0xfff80080
	s_addc_u32 s77, s75, -1
	s_cmp_eq_u32 s90, 28
	s_cselect_b32 s79, s0, s77
	s_cselect_b32 s78, s1, s76
	s_cselect_b32 s77, s3, s71
	s_cselect_b32 s76, s63, s65
	s_add_i32 m0, s31, 0xc000
	ds_read_b128 v[190:193], v168
	ds_read_b128 v[194:197], v168 offset:1024
	ds_read_b128 v[198:201], v168 offset:2048
	ds_read_b128 v[202:205], v168 offset:3072
	ds_read_b128 v[206:209], v168 offset:4096
	ds_read_b128 v[214:217], v168 offset:5120
	ds_read_b128 v[218:221], v168 offset:6144
	ds_read_b128 v[222:225], v168 offset:7168
	global_load_lds_dwordx4 v138, s[74:75]
	s_add_i32 m0, s31, 0xe000
	s_nop 0
	global_load_lds_dwordx4 v140, s[74:75]
	s_waitcnt vmcnt(8)
	s_waitcnt lgkmcnt(0)
	s_setprio 1
	s_barrier
	v_mfma_f32_16x16x32_bf16 v[124:127], v[146:149], v[190:193], 0
	v_mfma_f32_16x16x32_bf16 v[120:123], v[154:157], v[190:193], 0
	v_mfma_f32_16x16x32_bf16 v[108:111], v[146:149], v[198:201], 0
	v_mfma_f32_16x16x32_bf16 v[104:107], v[154:157], v[198:201], 0
	v_mfma_f32_16x16x32_bf16 v[92:95], v[146:149], v[206:209], 0
	v_mfma_f32_16x16x32_bf16 v[88:91], v[154:157], v[206:209], 0
	v_mfma_f32_16x16x32_bf16 v[76:79], v[146:149], v[218:221], 0
	v_mfma_f32_16x16x32_bf16 v[72:75], v[154:157], v[218:221], 0
	v_mfma_f32_16x16x32_bf16 v[124:127], v[150:153], v[194:197], v[124:127]
	v_mfma_f32_16x16x32_bf16 v[120:123], v[170:173], v[194:197], v[120:123]
	v_mfma_f32_16x16x32_bf16 v[108:111], v[150:153], v[202:205], v[108:111]
	v_mfma_f32_16x16x32_bf16 v[104:107], v[170:173], v[202:205], v[104:107]
	v_mfma_f32_16x16x32_bf16 v[92:95], v[150:153], v[214:217], v[92:95]
	v_mfma_f32_16x16x32_bf16 v[88:91], v[170:173], v[214:217], v[88:91]
	v_mfma_f32_16x16x32_bf16 v[76:79], v[150:153], v[222:225], v[76:79]
	v_mfma_f32_16x16x32_bf16 v[72:75], v[170:173], v[222:225], v[72:75]
	s_setprio 0
	s_setprio 1
	v_mfma_f32_16x16x32_bf16 v[116:119], v[174:177], v[190:193], 0
	v_mfma_f32_16x16x32_bf16 v[112:115], v[182:185], v[190:193], 0
	v_mfma_f32_16x16x32_bf16 v[100:103], v[174:177], v[198:201], 0
	v_mfma_f32_16x16x32_bf16 v[96:99], v[182:185], v[198:201], 0
	v_mfma_f32_16x16x32_bf16 v[84:87], v[174:177], v[206:209], 0
	v_mfma_f32_16x16x32_bf16 v[80:83], v[182:185], v[206:209], 0
	v_mfma_f32_16x16x32_bf16 v[68:71], v[174:177], v[218:221], 0
	v_mfma_f32_16x16x32_bf16 v[64:67], v[182:185], v[218:221], 0
	v_mfma_f32_16x16x32_bf16 v[116:119], v[178:181], v[194:197], v[116:119]
	v_mfma_f32_16x16x32_bf16 v[112:115], v[186:189], v[194:197], v[112:115]
	v_mfma_f32_16x16x32_bf16 v[100:103], v[178:181], v[202:205], v[100:103]
	v_mfma_f32_16x16x32_bf16 v[96:99], v[186:189], v[202:205], v[96:99]
	v_mfma_f32_16x16x32_bf16 v[84:87], v[178:181], v[214:217], v[84:87]
	v_mfma_f32_16x16x32_bf16 v[80:83], v[186:189], v[214:217], v[80:83]
	v_mfma_f32_16x16x32_bf16 v[68:71], v[178:181], v[222:225], v[68:71]
	v_mfma_f32_16x16x32_bf16 v[64:67], v[186:189], v[222:225], v[64:67]
	s_barrier
	s_setprio 0
	s_add_i32 s91, s81, s30
	s_add_u32 s98, s76, s34
	s_addc_u32 s99, s77, s35
	s_mov_b32 m0, s91
	ds_read_b128 v[190:193], v168 offset:16384
	ds_read_b128 v[194:197], v168 offset:17408
	ds_read_b128 v[198:201], v168 offset:18432
	ds_read_b128 v[202:205], v168 offset:19456
	ds_read_b128 v[206:209], v168 offset:20480
	ds_read_b128 v[214:217], v168 offset:21504
	ds_read_b128 v[218:221], v168 offset:22528
	ds_read_b128 v[222:225], v168 offset:23552
	global_load_lds_dwordx4 v130, s[76:77]
	s_add_i32 m0, s91, 0x2000
	s_add_u32 s92, s76, 0x80000
	s_addc_u32 s93, s77, 0
	s_add_i32 s91, s83, s30
	global_load_lds_dwordx4 v134, s[76:77]
	s_mov_b32 m0, s91
	s_add_u32 s100, s78, s34
	s_addc_u32 s101, s79, s35
	global_load_lds_dwordx4 v130, s[92:93]
	s_add_i32 m0, s91, 0x2000
	s_nop 0
	global_load_lds_dwordx4 v134, s[92:93]
	s_mov_b32 m0, s31
	s_nop 0
	global_load_lds_dwordx4 v128, s[78:79]
	s_mov_b32 m0, s51
	s_nop 0
	global_load_lds_dwordx4 v132, s[78:79]
	s_waitcnt vmcnt(8)
	s_waitcnt lgkmcnt(0)
	s_setprio 1
	s_barrier
	v_mfma_f32_16x16x32_bf16 v[60:63], v[146:149], v[190:193], 0
	v_mfma_f32_16x16x32_bf16 v[56:59], v[154:157], v[190:193], 0
	v_mfma_f32_16x16x32_bf16 v[44:47], v[146:149], v[198:201], 0
	v_mfma_f32_16x16x32_bf16 v[40:43], v[154:157], v[198:201], 0
	v_mfma_f32_16x16x32_bf16 v[28:31], v[146:149], v[206:209], 0
	v_mfma_f32_16x16x32_bf16 v[24:27], v[154:157], v[206:209], 0
	v_mfma_f32_16x16x32_bf16 v[12:15], v[146:149], v[218:221], 0
	v_mfma_f32_16x16x32_bf16 v[8:11], v[154:157], v[218:221], 0
	v_mfma_f32_16x16x32_bf16 v[60:63], v[150:153], v[194:197], v[60:63]
	v_mfma_f32_16x16x32_bf16 v[56:59], v[170:173], v[194:197], v[56:59]
	v_mfma_f32_16x16x32_bf16 v[44:47], v[150:153], v[202:205], v[44:47]
	v_mfma_f32_16x16x32_bf16 v[40:43], v[170:173], v[202:205], v[40:43]
	v_mfma_f32_16x16x32_bf16 v[28:31], v[150:153], v[214:217], v[28:31]
	v_mfma_f32_16x16x32_bf16 v[24:27], v[170:173], v[214:217], v[24:27]
	v_mfma_f32_16x16x32_bf16 v[12:15], v[150:153], v[222:225], v[12:15]
	v_mfma_f32_16x16x32_bf16 v[8:11], v[170:173], v[222:225], v[8:11]
	s_setprio 0
	s_setprio 1
	v_mfma_f32_16x16x32_bf16 v[52:55], v[174:177], v[190:193], 0
	v_mfma_f32_16x16x32_bf16 v[48:51], v[182:185], v[190:193], 0
	v_mfma_f32_16x16x32_bf16 v[36:39], v[174:177], v[198:201], 0
	v_mfma_f32_16x16x32_bf16 v[32:35], v[182:185], v[198:201], 0
	v_mfma_f32_16x16x32_bf16 v[20:23], v[174:177], v[206:209], 0
	v_mfma_f32_16x16x32_bf16 v[16:19], v[182:185], v[206:209], 0
	v_mfma_f32_16x16x32_bf16 v[4:7], v[174:177], v[218:221], 0
	v_mfma_f32_16x16x32_bf16 v[0:3], v[182:185], v[218:221], 0
	v_mfma_f32_16x16x32_bf16 v[52:55], v[178:181], v[194:197], v[52:55]
	v_mfma_f32_16x16x32_bf16 v[48:51], v[186:189], v[194:197], v[48:51]
	v_mfma_f32_16x16x32_bf16 v[36:39], v[178:181], v[202:205], v[36:39]
	v_mfma_f32_16x16x32_bf16 v[32:35], v[186:189], v[202:205], v[32:35]
	v_mfma_f32_16x16x32_bf16 v[20:23], v[178:181], v[214:217], v[20:23]
	v_mfma_f32_16x16x32_bf16 v[16:19], v[186:189], v[214:217], v[16:19]
	v_mfma_f32_16x16x32_bf16 v[4:7], v[178:181], v[222:225], v[4:7]
	v_mfma_f32_16x16x32_bf16 v[0:3], v[186:189], v[222:225], v[0:3]
	s_barrier
	s_setprio 0
	s_add_i32 s91, 0, 0x18000
	v_add_u32_e32 v136, s91, v162
	s_add_i32 s92, 0, 0x1c000
	ds_read_b128 v[146:149], v136
	ds_read_b128 v[150:153], v136 offset:1024
	ds_read_b128 v[154:157], v136 offset:2048
	ds_read_b128 v[170:173], v136 offset:3072
	v_add_u32_e32 v136, s92, v162
	ds_read_b128 v[174:177], v136
	ds_read_b128 v[178:181], v136 offset:1024
	ds_read_b128 v[182:185], v136 offset:2048
	ds_read_b128 v[186:189], v136 offset:3072
	s_add_u32 s78, s78, 0x80000
	s_addc_u32 s79, s79, 0
	s_mov_b32 m0, s28
	ds_read_b128 v[190:193], v168 offset:32768
	ds_read_b128 v[194:197], v168 offset:33792
	ds_read_b128 v[198:201], v168 offset:34816
	ds_read_b128 v[202:205], v168 offset:35840
	ds_read_b128 v[206:209], v168 offset:36864
	ds_read_b128 v[214:217], v168 offset:37888
	ds_read_b128 v[218:221], v168 offset:38912
	ds_read_b128 v[222:225], v168 offset:39936
	global_load_lds_dwordx4 v128, s[78:79]
	s_mov_b32 m0, s29
	s_nop 0
	global_load_lds_dwordx4 v132, s[78:79]
	s_waitcnt vmcnt(8)
	s_waitcnt lgkmcnt(0)
	s_setprio 1
	s_barrier
	v_mfma_f32_16x16x32_bf16 v[124:127], v[146:149], v[190:193], v[124:127]
	v_mfma_f32_16x16x32_bf16 v[120:123], v[154:157], v[190:193], v[120:123]
	v_mfma_f32_16x16x32_bf16 v[108:111], v[146:149], v[198:201], v[108:111]
	v_mfma_f32_16x16x32_bf16 v[104:107], v[154:157], v[198:201], v[104:107]
	v_mfma_f32_16x16x32_bf16 v[92:95], v[146:149], v[206:209], v[92:95]
	v_mfma_f32_16x16x32_bf16 v[88:91], v[154:157], v[206:209], v[88:91]
	v_mfma_f32_16x16x32_bf16 v[76:79], v[146:149], v[218:221], v[76:79]
	v_mfma_f32_16x16x32_bf16 v[72:75], v[154:157], v[218:221], v[72:75]
	v_mfma_f32_16x16x32_bf16 v[124:127], v[150:153], v[194:197], v[124:127]
	v_mfma_f32_16x16x32_bf16 v[120:123], v[170:173], v[194:197], v[120:123]
	v_mfma_f32_16x16x32_bf16 v[108:111], v[150:153], v[202:205], v[108:111]
	v_mfma_f32_16x16x32_bf16 v[104:107], v[170:173], v[202:205], v[104:107]
	v_mfma_f32_16x16x32_bf16 v[92:95], v[150:153], v[214:217], v[92:95]
	v_mfma_f32_16x16x32_bf16 v[88:91], v[170:173], v[214:217], v[88:91]
	v_mfma_f32_16x16x32_bf16 v[76:79], v[150:153], v[222:225], v[76:79]
	v_mfma_f32_16x16x32_bf16 v[72:75], v[170:173], v[222:225], v[72:75]
	s_setprio 0
	s_setprio 1
	v_mfma_f32_16x16x32_bf16 v[116:119], v[174:177], v[190:193], v[116:119]
	v_mfma_f32_16x16x32_bf16 v[112:115], v[182:185], v[190:193], v[112:115]
	v_mfma_f32_16x16x32_bf16 v[100:103], v[174:177], v[198:201], v[100:103]
	v_mfma_f32_16x16x32_bf16 v[96:99], v[182:185], v[198:201], v[96:99]
	v_mfma_f32_16x16x32_bf16 v[84:87], v[174:177], v[206:209], v[84:87]
	v_mfma_f32_16x16x32_bf16 v[80:83], v[182:185], v[206:209], v[80:83]
	v_mfma_f32_16x16x32_bf16 v[68:71], v[174:177], v[218:221], v[68:71]
	v_mfma_f32_16x16x32_bf16 v[64:67], v[182:185], v[218:221], v[64:67]
	v_mfma_f32_16x16x32_bf16 v[116:119], v[178:181], v[194:197], v[116:119]
	v_mfma_f32_16x16x32_bf16 v[112:115], v[186:189], v[194:197], v[112:115]
	v_mfma_f32_16x16x32_bf16 v[100:103], v[178:181], v[202:205], v[100:103]
	v_mfma_f32_16x16x32_bf16 v[96:99], v[186:189], v[202:205], v[96:99]
	v_mfma_f32_16x16x32_bf16 v[84:87], v[178:181], v[214:217], v[84:87]
	v_mfma_f32_16x16x32_bf16 v[80:83], v[186:189], v[214:217], v[80:83]
	v_mfma_f32_16x16x32_bf16 v[68:71], v[178:181], v[222:225], v[68:71]
	v_mfma_f32_16x16x32_bf16 v[64:67], v[186:189], v[222:225], v[64:67]
	s_barrier
	s_setprio 0
	s_add_i32 s78, s91, s30
	s_mov_b32 m0, s78
	ds_read_b128 v[190:193], v168 offset:49152
	ds_read_b128 v[194:197], v168 offset:50176
	ds_read_b128 v[198:201], v168 offset:51200
	ds_read_b128 v[202:205], v168 offset:52224
	ds_read_b128 v[206:209], v168 offset:53248
	ds_read_b128 v[214:217], v168 offset:54272
	ds_read_b128 v[218:221], v168 offset:55296
	ds_read_b128 v[222:225], v168 offset:56320
	global_load_lds_dwordx4 v130, s[98:99]
	s_add_i32 m0, s78, 0x2000
	s_add_u32 s76, s76, 0x80080
	s_addc_u32 s77, s77, 0
	s_add_i32 s78, s92, s30
	global_load_lds_dwordx4 v134, s[98:99]
	s_mov_b32 m0, s78
	s_nop 0
	global_load_lds_dwordx4 v130, s[76:77]
	s_add_i32 m0, s78, 0x2000
	s_nop 0
	global_load_lds_dwordx4 v134, s[76:77]
	s_mov_b32 m0, s73
	s_nop 0
	global_load_lds_dwordx4 v128, s[100:101]
	s_mov_b32 m0, s80
	s_nop 0
	global_load_lds_dwordx4 v132, s[100:101]
	s_waitcnt vmcnt(8)
	s_waitcnt lgkmcnt(0)
	s_setprio 1
	s_barrier
	v_mfma_f32_16x16x32_bf16 v[60:63], v[146:149], v[190:193], v[60:63]
	v_mfma_f32_16x16x32_bf16 v[56:59], v[154:157], v[190:193], v[56:59]
	v_mfma_f32_16x16x32_bf16 v[44:47], v[146:149], v[198:201], v[44:47]
	v_mfma_f32_16x16x32_bf16 v[40:43], v[154:157], v[198:201], v[40:43]
	v_mfma_f32_16x16x32_bf16 v[28:31], v[146:149], v[206:209], v[28:31]
	v_mfma_f32_16x16x32_bf16 v[24:27], v[154:157], v[206:209], v[24:27]
	v_mfma_f32_16x16x32_bf16 v[12:15], v[146:149], v[218:221], v[12:15]
	v_mfma_f32_16x16x32_bf16 v[8:11], v[154:157], v[218:221], v[8:11]
	v_mfma_f32_16x16x32_bf16 v[60:63], v[150:153], v[194:197], v[60:63]
	v_mfma_f32_16x16x32_bf16 v[56:59], v[170:173], v[194:197], v[56:59]
	v_mfma_f32_16x16x32_bf16 v[44:47], v[150:153], v[202:205], v[44:47]
	v_mfma_f32_16x16x32_bf16 v[40:43], v[170:173], v[202:205], v[40:43]
	v_mfma_f32_16x16x32_bf16 v[28:31], v[150:153], v[214:217], v[28:31]
	v_mfma_f32_16x16x32_bf16 v[24:27], v[170:173], v[214:217], v[24:27]
	v_mfma_f32_16x16x32_bf16 v[12:15], v[150:153], v[222:225], v[12:15]
	v_mfma_f32_16x16x32_bf16 v[8:11], v[170:173], v[222:225], v[8:11]
	s_setprio 0
	s_setprio 1
	v_mfma_f32_16x16x32_bf16 v[52:55], v[174:177], v[190:193], v[52:55]
	v_mfma_f32_16x16x32_bf16 v[48:51], v[182:185], v[190:193], v[48:51]
	v_mfma_f32_16x16x32_bf16 v[36:39], v[174:177], v[198:201], v[36:39]
	v_mfma_f32_16x16x32_bf16 v[32:35], v[182:185], v[198:201], v[32:35]
	v_mfma_f32_16x16x32_bf16 v[20:23], v[174:177], v[206:209], v[20:23]
	v_mfma_f32_16x16x32_bf16 v[16:19], v[182:185], v[206:209], v[16:19]
	v_mfma_f32_16x16x32_bf16 v[4:7], v[174:177], v[218:221], v[4:7]
	v_mfma_f32_16x16x32_bf16 v[0:3], v[182:185], v[218:221], v[0:3]
	v_mfma_f32_16x16x32_bf16 v[52:55], v[178:181], v[194:197], v[52:55]
	v_mfma_f32_16x16x32_bf16 v[48:51], v[186:189], v[194:197], v[48:51]
	v_mfma_f32_16x16x32_bf16 v[36:39], v[178:181], v[202:205], v[36:39]
	v_mfma_f32_16x16x32_bf16 v[32:35], v[186:189], v[202:205], v[32:35]
	v_mfma_f32_16x16x32_bf16 v[20:23], v[178:181], v[214:217], v[20:23]
	v_mfma_f32_16x16x32_bf16 v[16:19], v[186:189], v[214:217], v[16:19]
	v_mfma_f32_16x16x32_bf16 v[4:7], v[178:181], v[222:225], v[4:7]
	v_mfma_f32_16x16x32_bf16 v[0:3], v[186:189], v[222:225], v[0:3]
	s_barrier
	s_setprio 0
	s_add_i32 s90, s90, 2
	s_add_u32 s74, s74, 0x100
	s_addc_u32 s75, s75, 0
	s_add_u32 s65, s65, 0x100
	s_addc_u32 s71, s71, 0
	s_cmp_gt_u32 s90, 29
.LBB0_272:
	ds_read_b128 v[146:149], v166
	ds_read_b128 v[150:153], v166 offset:1024
	ds_read_b128 v[154:157], v166 offset:2048
	ds_read_b128 v[170:173], v166 offset:3072
	ds_read_b128 v[174:177], v167
	ds_read_b128 v[178:181], v167 offset:1024
	ds_read_b128 v[182:185], v167 offset:2048
	ds_read_b128 v[186:189], v167 offset:3072
	s_add_u32 s76, s74, 0xfff80080
	s_addc_u32 s77, s75, -1
	s_cmp_eq_u32 s90, 28
	s_cselect_b32 s79, s0, s77
	s_cselect_b32 s78, s1, s76
	s_cselect_b32 s77, s3, s71
	s_cselect_b32 s76, s63, s65
	s_add_i32 m0, s31, 0xc000
	ds_read_b128 v[190:193], v168
	ds_read_b128 v[194:197], v168 offset:1024
	ds_read_b128 v[198:201], v168 offset:2048
	ds_read_b128 v[202:205], v168 offset:3072
	ds_read_b128 v[206:209], v168 offset:4096
	ds_read_b128 v[214:217], v168 offset:5120
	ds_read_b128 v[218:221], v168 offset:6144
	ds_read_b128 v[222:225], v168 offset:7168
	global_load_lds_dwordx4 v138, s[74:75]
	s_add_i32 m0, s31, 0xe000
	s_nop 0
	global_load_lds_dwordx4 v140, s[74:75]
	s_waitcnt vmcnt(8)
	s_waitcnt lgkmcnt(0)
	s_setprio 1
	s_barrier
	v_mfma_f32_16x16x32_bf16 v[124:127], v[146:149], v[190:193], v[124:127]
	v_mfma_f32_16x16x32_bf16 v[120:123], v[154:157], v[190:193], v[120:123]
	v_mfma_f32_16x16x32_bf16 v[108:111], v[146:149], v[198:201], v[108:111]
	v_mfma_f32_16x16x32_bf16 v[104:107], v[154:157], v[198:201], v[104:107]
	v_mfma_f32_16x16x32_bf16 v[92:95], v[146:149], v[206:209], v[92:95]
	v_mfma_f32_16x16x32_bf16 v[88:91], v[154:157], v[206:209], v[88:91]
	v_mfma_f32_16x16x32_bf16 v[76:79], v[146:149], v[218:221], v[76:79]
	v_mfma_f32_16x16x32_bf16 v[72:75], v[154:157], v[218:221], v[72:75]
	v_mfma_f32_16x16x32_bf16 v[124:127], v[150:153], v[194:197], v[124:127]
	v_mfma_f32_16x16x32_bf16 v[120:123], v[170:173], v[194:197], v[120:123]
	v_mfma_f32_16x16x32_bf16 v[108:111], v[150:153], v[202:205], v[108:111]
	v_mfma_f32_16x16x32_bf16 v[104:107], v[170:173], v[202:205], v[104:107]
	v_mfma_f32_16x16x32_bf16 v[92:95], v[150:153], v[214:217], v[92:95]
	v_mfma_f32_16x16x32_bf16 v[88:91], v[170:173], v[214:217], v[88:91]
	v_mfma_f32_16x16x32_bf16 v[76:79], v[150:153], v[222:225], v[76:79]
	v_mfma_f32_16x16x32_bf16 v[72:75], v[170:173], v[222:225], v[72:75]
	s_setprio 0
	s_setprio 1
	v_mfma_f32_16x16x32_bf16 v[116:119], v[174:177], v[190:193], v[116:119]
	v_mfma_f32_16x16x32_bf16 v[112:115], v[182:185], v[190:193], v[112:115]
	v_mfma_f32_16x16x32_bf16 v[100:103], v[174:177], v[198:201], v[100:103]
	v_mfma_f32_16x16x32_bf16 v[96:99], v[182:185], v[198:201], v[96:99]
	v_mfma_f32_16x16x32_bf16 v[84:87], v[174:177], v[206:209], v[84:87]
	v_mfma_f32_16x16x32_bf16 v[80:83], v[182:185], v[206:209], v[80:83]
	v_mfma_f32_16x16x32_bf16 v[68:71], v[174:177], v[218:221], v[68:71]
	v_mfma_f32_16x16x32_bf16 v[64:67], v[182:185], v[218:221], v[64:67]
	v_mfma_f32_16x16x32_bf16 v[116:119], v[178:181], v[194:197], v[116:119]
	v_mfma_f32_16x16x32_bf16 v[112:115], v[186:189], v[194:197], v[112:115]
	v_mfma_f32_16x16x32_bf16 v[100:103], v[178:181], v[202:205], v[100:103]
	v_mfma_f32_16x16x32_bf16 v[96:99], v[186:189], v[202:205], v[96:99]
	v_mfma_f32_16x16x32_bf16 v[84:87], v[178:181], v[214:217], v[84:87]
	v_mfma_f32_16x16x32_bf16 v[80:83], v[186:189], v[214:217], v[80:83]
	v_mfma_f32_16x16x32_bf16 v[68:71], v[178:181], v[222:225], v[68:71]
	v_mfma_f32_16x16x32_bf16 v[64:67], v[186:189], v[222:225], v[64:67]
	s_barrier
	s_setprio 0
	s_add_i32 s91, s81, s30
	s_add_u32 s98, s76, s34
	s_addc_u32 s99, s77, s35
	s_mov_b32 m0, s91
	ds_read_b128 v[190:193], v168 offset:16384
	ds_read_b128 v[194:197], v168 offset:17408
	ds_read_b128 v[198:201], v168 offset:18432
	ds_read_b128 v[202:205], v168 offset:19456
	ds_read_b128 v[206:209], v168 offset:20480
	ds_read_b128 v[214:217], v168 offset:21504
	ds_read_b128 v[218:221], v168 offset:22528
	ds_read_b128 v[222:225], v168 offset:23552
	global_load_lds_dwordx4 v130, s[76:77]
	s_add_i32 m0, s91, 0x2000
	s_add_u32 s92, s76, 0x80000
	s_addc_u32 s93, s77, 0
	s_add_i32 s91, s83, s30
	global_load_lds_dwordx4 v134, s[76:77]
	s_mov_b32 m0, s91
	s_add_u32 s100, s78, s34
	s_addc_u32 s101, s79, s35
	global_load_lds_dwordx4 v130, s[92:93]
	s_add_i32 m0, s91, 0x2000
	s_nop 0
	global_load_lds_dwordx4 v134, s[92:93]
	s_mov_b32 m0, s31
	s_nop 0
	global_load_lds_dwordx4 v128, s[78:79]
	s_mov_b32 m0, s51
	s_nop 0
	global_load_lds_dwordx4 v132, s[78:79]
	s_waitcnt vmcnt(8)
	s_waitcnt lgkmcnt(0)
	s_setprio 1
	s_barrier
	v_mfma_f32_16x16x32_bf16 v[60:63], v[146:149], v[190:193], v[60:63]
	v_mfma_f32_16x16x32_bf16 v[56:59], v[154:157], v[190:193], v[56:59]
	v_mfma_f32_16x16x32_bf16 v[44:47], v[146:149], v[198:201], v[44:47]
	v_mfma_f32_16x16x32_bf16 v[40:43], v[154:157], v[198:201], v[40:43]
	v_mfma_f32_16x16x32_bf16 v[28:31], v[146:149], v[206:209], v[28:31]
	v_mfma_f32_16x16x32_bf16 v[24:27], v[154:157], v[206:209], v[24:27]
	v_mfma_f32_16x16x32_bf16 v[12:15], v[146:149], v[218:221], v[12:15]
	v_mfma_f32_16x16x32_bf16 v[8:11], v[154:157], v[218:221], v[8:11]
	v_mfma_f32_16x16x32_bf16 v[60:63], v[150:153], v[194:197], v[60:63]
	v_mfma_f32_16x16x32_bf16 v[56:59], v[170:173], v[194:197], v[56:59]
	v_mfma_f32_16x16x32_bf16 v[44:47], v[150:153], v[202:205], v[44:47]
	v_mfma_f32_16x16x32_bf16 v[40:43], v[170:173], v[202:205], v[40:43]
	v_mfma_f32_16x16x32_bf16 v[28:31], v[150:153], v[214:217], v[28:31]
	v_mfma_f32_16x16x32_bf16 v[24:27], v[170:173], v[214:217], v[24:27]
	v_mfma_f32_16x16x32_bf16 v[12:15], v[150:153], v[222:225], v[12:15]
	v_mfma_f32_16x16x32_bf16 v[8:11], v[170:173], v[222:225], v[8:11]
	s_setprio 0
	s_setprio 1
	v_mfma_f32_16x16x32_bf16 v[52:55], v[174:177], v[190:193], v[52:55]
	v_mfma_f32_16x16x32_bf16 v[48:51], v[182:185], v[190:193], v[48:51]
	v_mfma_f32_16x16x32_bf16 v[36:39], v[174:177], v[198:201], v[36:39]
	v_mfma_f32_16x16x32_bf16 v[32:35], v[182:185], v[198:201], v[32:35]
	v_mfma_f32_16x16x32_bf16 v[20:23], v[174:177], v[206:209], v[20:23]
	v_mfma_f32_16x16x32_bf16 v[16:19], v[182:185], v[206:209], v[16:19]
	v_mfma_f32_16x16x32_bf16 v[4:7], v[174:177], v[218:221], v[4:7]
	v_mfma_f32_16x16x32_bf16 v[0:3], v[182:185], v[218:221], v[0:3]
	v_mfma_f32_16x16x32_bf16 v[52:55], v[178:181], v[194:197], v[52:55]
	v_mfma_f32_16x16x32_bf16 v[48:51], v[186:189], v[194:197], v[48:51]
	v_mfma_f32_16x16x32_bf16 v[36:39], v[178:181], v[202:205], v[36:39]
	v_mfma_f32_16x16x32_bf16 v[32:35], v[186:189], v[202:205], v[32:35]
	v_mfma_f32_16x16x32_bf16 v[20:23], v[178:181], v[214:217], v[20:23]
	v_mfma_f32_16x16x32_bf16 v[16:19], v[186:189], v[214:217], v[16:19]
	v_mfma_f32_16x16x32_bf16 v[4:7], v[178:181], v[222:225], v[4:7]
	v_mfma_f32_16x16x32_bf16 v[0:3], v[186:189], v[222:225], v[0:3]
	s_barrier
	s_setprio 0
	s_add_i32 s91, 0, 0x18000
	v_add_u32_e32 v136, s91, v162
	s_add_i32 s92, 0, 0x1c000
	ds_read_b128 v[146:149], v136
	ds_read_b128 v[150:153], v136 offset:1024
	ds_read_b128 v[154:157], v136 offset:2048
	ds_read_b128 v[170:173], v136 offset:3072
	v_add_u32_e32 v136, s92, v162
	ds_read_b128 v[174:177], v136
	ds_read_b128 v[178:181], v136 offset:1024
	ds_read_b128 v[182:185], v136 offset:2048
	ds_read_b128 v[186:189], v136 offset:3072
	s_add_u32 s78, s78, 0x80000
	s_addc_u32 s79, s79, 0
	s_mov_b32 m0, s28
	ds_read_b128 v[190:193], v168 offset:32768
	ds_read_b128 v[194:197], v168 offset:33792
	ds_read_b128 v[198:201], v168 offset:34816
	ds_read_b128 v[202:205], v168 offset:35840
	ds_read_b128 v[206:209], v168 offset:36864
	ds_read_b128 v[214:217], v168 offset:37888
	ds_read_b128 v[218:221], v168 offset:38912
	ds_read_b128 v[222:225], v168 offset:39936
	global_load_lds_dwordx4 v128, s[78:79]
	s_mov_b32 m0, s29
	s_nop 0
	global_load_lds_dwordx4 v132, s[78:79]
	s_waitcnt vmcnt(8)
	s_waitcnt lgkmcnt(0)
	s_setprio 1
	s_barrier
	v_mfma_f32_16x16x32_bf16 v[124:127], v[146:149], v[190:193], v[124:127]
	v_mfma_f32_16x16x32_bf16 v[120:123], v[154:157], v[190:193], v[120:123]
	v_mfma_f32_16x16x32_bf16 v[108:111], v[146:149], v[198:201], v[108:111]
	v_mfma_f32_16x16x32_bf16 v[104:107], v[154:157], v[198:201], v[104:107]
	v_mfma_f32_16x16x32_bf16 v[92:95], v[146:149], v[206:209], v[92:95]
	v_mfma_f32_16x16x32_bf16 v[88:91], v[154:157], v[206:209], v[88:91]
	v_mfma_f32_16x16x32_bf16 v[76:79], v[146:149], v[218:221], v[76:79]
	v_mfma_f32_16x16x32_bf16 v[72:75], v[154:157], v[218:221], v[72:75]
	v_mfma_f32_16x16x32_bf16 v[124:127], v[150:153], v[194:197], v[124:127]
	v_mfma_f32_16x16x32_bf16 v[120:123], v[170:173], v[194:197], v[120:123]
	v_mfma_f32_16x16x32_bf16 v[108:111], v[150:153], v[202:205], v[108:111]
	v_mfma_f32_16x16x32_bf16 v[104:107], v[170:173], v[202:205], v[104:107]
	v_mfma_f32_16x16x32_bf16 v[92:95], v[150:153], v[214:217], v[92:95]
	v_mfma_f32_16x16x32_bf16 v[88:91], v[170:173], v[214:217], v[88:91]
	v_mfma_f32_16x16x32_bf16 v[76:79], v[150:153], v[222:225], v[76:79]
	v_mfma_f32_16x16x32_bf16 v[72:75], v[170:173], v[222:225], v[72:75]
	s_setprio 0
	s_setprio 1
	v_mfma_f32_16x16x32_bf16 v[116:119], v[174:177], v[190:193], v[116:119]
	v_mfma_f32_16x16x32_bf16 v[112:115], v[182:185], v[190:193], v[112:115]
	v_mfma_f32_16x16x32_bf16 v[100:103], v[174:177], v[198:201], v[100:103]
	v_mfma_f32_16x16x32_bf16 v[96:99], v[182:185], v[198:201], v[96:99]
	v_mfma_f32_16x16x32_bf16 v[84:87], v[174:177], v[206:209], v[84:87]
	v_mfma_f32_16x16x32_bf16 v[80:83], v[182:185], v[206:209], v[80:83]
	v_mfma_f32_16x16x32_bf16 v[68:71], v[174:177], v[218:221], v[68:71]
	v_mfma_f32_16x16x32_bf16 v[64:67], v[182:185], v[218:221], v[64:67]
	v_mfma_f32_16x16x32_bf16 v[116:119], v[178:181], v[194:197], v[116:119]
	v_mfma_f32_16x16x32_bf16 v[112:115], v[186:189], v[194:197], v[112:115]
	v_mfma_f32_16x16x32_bf16 v[100:103], v[178:181], v[202:205], v[100:103]
	v_mfma_f32_16x16x32_bf16 v[96:99], v[186:189], v[202:205], v[96:99]
	v_mfma_f32_16x16x32_bf16 v[84:87], v[178:181], v[214:217], v[84:87]
	v_mfma_f32_16x16x32_bf16 v[80:83], v[186:189], v[214:217], v[80:83]
	v_mfma_f32_16x16x32_bf16 v[68:71], v[178:181], v[222:225], v[68:71]
	v_mfma_f32_16x16x32_bf16 v[64:67], v[186:189], v[222:225], v[64:67]
	s_barrier
	s_setprio 0
	s_add_i32 s78, s91, s30
	s_mov_b32 m0, s78
	ds_read_b128 v[190:193], v168 offset:49152
	ds_read_b128 v[194:197], v168 offset:50176
	ds_read_b128 v[198:201], v168 offset:51200
	ds_read_b128 v[202:205], v168 offset:52224
	ds_read_b128 v[206:209], v168 offset:53248
	ds_read_b128 v[214:217], v168 offset:54272
	ds_read_b128 v[218:221], v168 offset:55296
	ds_read_b128 v[222:225], v168 offset:56320
	global_load_lds_dwordx4 v130, s[98:99]
	s_add_i32 m0, s78, 0x2000
	s_add_u32 s76, s76, 0x80080
	s_addc_u32 s77, s77, 0
	s_add_i32 s78, s92, s30
	global_load_lds_dwordx4 v134, s[98:99]
	s_mov_b32 m0, s78
	s_nop 0
	global_load_lds_dwordx4 v130, s[76:77]
	s_add_i32 m0, s78, 0x2000
	s_nop 0
	global_load_lds_dwordx4 v134, s[76:77]
	s_mov_b32 m0, s73
	s_nop 0
	global_load_lds_dwordx4 v128, s[100:101]
	s_mov_b32 m0, s80
	s_nop 0
	global_load_lds_dwordx4 v132, s[100:101]
	s_waitcnt vmcnt(8)
	s_waitcnt lgkmcnt(0)
	s_setprio 1
	s_barrier
	v_mfma_f32_16x16x32_bf16 v[60:63], v[146:149], v[190:193], v[60:63]
	v_mfma_f32_16x16x32_bf16 v[56:59], v[154:157], v[190:193], v[56:59]
	v_mfma_f32_16x16x32_bf16 v[44:47], v[146:149], v[198:201], v[44:47]
	v_mfma_f32_16x16x32_bf16 v[40:43], v[154:157], v[198:201], v[40:43]
	v_mfma_f32_16x16x32_bf16 v[28:31], v[146:149], v[206:209], v[28:31]
	v_mfma_f32_16x16x32_bf16 v[24:27], v[154:157], v[206:209], v[24:27]
	v_mfma_f32_16x16x32_bf16 v[12:15], v[146:149], v[218:221], v[12:15]
	v_mfma_f32_16x16x32_bf16 v[8:11], v[154:157], v[218:221], v[8:11]
	v_mfma_f32_16x16x32_bf16 v[60:63], v[150:153], v[194:197], v[60:63]
	v_mfma_f32_16x16x32_bf16 v[56:59], v[170:173], v[194:197], v[56:59]
	v_mfma_f32_16x16x32_bf16 v[44:47], v[150:153], v[202:205], v[44:47]
	v_mfma_f32_16x16x32_bf16 v[40:43], v[170:173], v[202:205], v[40:43]
	v_mfma_f32_16x16x32_bf16 v[28:31], v[150:153], v[214:217], v[28:31]
	v_mfma_f32_16x16x32_bf16 v[24:27], v[170:173], v[214:217], v[24:27]
	v_mfma_f32_16x16x32_bf16 v[12:15], v[150:153], v[222:225], v[12:15]
	v_mfma_f32_16x16x32_bf16 v[8:11], v[170:173], v[222:225], v[8:11]
	s_setprio 0
	s_setprio 1
	v_mfma_f32_16x16x32_bf16 v[52:55], v[174:177], v[190:193], v[52:55]
	v_mfma_f32_16x16x32_bf16 v[48:51], v[182:185], v[190:193], v[48:51]
	v_mfma_f32_16x16x32_bf16 v[36:39], v[174:177], v[198:201], v[36:39]
	v_mfma_f32_16x16x32_bf16 v[32:35], v[182:185], v[198:201], v[32:35]
	v_mfma_f32_16x16x32_bf16 v[20:23], v[174:177], v[206:209], v[20:23]
	v_mfma_f32_16x16x32_bf16 v[16:19], v[182:185], v[206:209], v[16:19]
	v_mfma_f32_16x16x32_bf16 v[4:7], v[174:177], v[218:221], v[4:7]
	v_mfma_f32_16x16x32_bf16 v[0:3], v[182:185], v[218:221], v[0:3]
	v_mfma_f32_16x16x32_bf16 v[52:55], v[178:181], v[194:197], v[52:55]
	v_mfma_f32_16x16x32_bf16 v[48:51], v[186:189], v[194:197], v[48:51]
	v_mfma_f32_16x16x32_bf16 v[36:39], v[178:181], v[202:205], v[36:39]
	v_mfma_f32_16x16x32_bf16 v[32:35], v[186:189], v[202:205], v[32:35]
	v_mfma_f32_16x16x32_bf16 v[20:23], v[178:181], v[214:217], v[20:23]
	v_mfma_f32_16x16x32_bf16 v[16:19], v[186:189], v[214:217], v[16:19]
	v_mfma_f32_16x16x32_bf16 v[4:7], v[178:181], v[222:225], v[4:7]
	v_mfma_f32_16x16x32_bf16 v[0:3], v[186:189], v[222:225], v[0:3]
	s_barrier
	s_setprio 0
	s_add_i32 s90, s90, 2
	s_add_u32 s74, s74, 0x100
	s_addc_u32 s75, s75, 0
	s_add_u32 s65, s65, 0x100
	s_addc_u32 s71, s71, 0
	s_cmp_gt_u32 s90, 29
	s_cbranch_scc0 .LBB0_272
	s_and_b64 vcc, exec, s[36:37]
	s_cbranch_vccz .LBB0_275
	s_barrier

.LBB0_542:
	s_ashr_i32 s35, s34, 31
	s_lshl_b64 s[0:1], s[34:35], 20
	s_add_u32 s36, s29, s0
	s_addc_u32 s37, s30, s1
	s_and_b64 s[0:1], s[6:7], exec
	s_cselect_b32 s0, s37, s43
	s_cselect_b32 s1, s36, s42
	s_ashr_i32 s25, s24, 31
	s_lshl_b64 s[38:39], s[24:25], 20
	s_add_u32 s38, s27, s38
	s_addc_u32 s39, s28, s39
	s_and_b64 s[46:47], s[6:7], exec
	s_cselect_b32 s3, s39, s45
	s_cselect_b32 s9, s38, s44
	s_add_u32 s42, s42, 0x80080
	s_addc_u32 s43, s43, 0
	s_add_u32 s25, s44, 0x100
	s_addc_u32 s35, s45, 0
	s_mov_b32 s58, -2
	s_waitcnt lgkmcnt(0)
	s_waitcnt vmcnt(0)
	ds_read_b128 v[128:131], v216
	ds_read_b128 v[132:135], v216 offset:1024
	ds_read_b128 v[136:139], v216 offset:2048
	ds_read_b128 v[140:143], v216 offset:3072
	ds_read_b128 v[144:147], v217
	ds_read_b128 v[148:151], v217 offset:1024
	ds_read_b128 v[152:155], v217 offset:2048
	ds_read_b128 v[156:159], v217 offset:3072
	s_add_u32 s44, s42, 0xfff80080
	s_addc_u32 s45, s43, -1
	s_cmp_eq_u32 s58, 28
	s_cselect_b32 s47, s0, s45
	s_cselect_b32 s46, s1, s44
	s_cselect_b32 s45, s3, s35
	s_cselect_b32 s44, s9, s25
	s_add_i32 m0, s41, 0xc000
	ds_read_b128 v[160:163], v218
	ds_read_b128 v[164:167], v218 offset:1024
	ds_read_b128 v[168:171], v218 offset:2048
	ds_read_b128 v[172:175], v218 offset:3072
	ds_read_b128 v[192:195], v218 offset:4096
	ds_read_b128 v[196:199], v218 offset:5120
	ds_read_b128 v[200:203], v218 offset:6144
	ds_read_b128 v[204:207], v218 offset:7168
	global_load_lds_dwordx4 v184, s[42:43]
	s_add_i32 m0, s41, 0xe000
	s_nop 0
	global_load_lds_dwordx4 v186, s[42:43]
	s_waitcnt vmcnt(8)
	s_waitcnt lgkmcnt(0)
	s_setprio 1
	s_barrier
	v_mfma_f32_16x16x32_bf16 v[124:127], v[128:131], v[160:163], 0
	v_mfma_f32_16x16x32_bf16 v[120:123], v[136:139], v[160:163], 0
	v_mfma_f32_16x16x32_bf16 v[108:111], v[128:131], v[168:171], 0
	v_mfma_f32_16x16x32_bf16 v[104:107], v[136:139], v[168:171], 0
	v_mfma_f32_16x16x32_bf16 v[92:95], v[128:131], v[192:195], 0
	v_mfma_f32_16x16x32_bf16 v[88:91], v[136:139], v[192:195], 0
	v_mfma_f32_16x16x32_bf16 v[76:79], v[128:131], v[200:203], 0
	v_mfma_f32_16x16x32_bf16 v[72:75], v[136:139], v[200:203], 0
	v_mfma_f32_16x16x32_bf16 v[124:127], v[132:135], v[164:167], v[124:127]
	v_mfma_f32_16x16x32_bf16 v[120:123], v[140:143], v[164:167], v[120:123]
	v_mfma_f32_16x16x32_bf16 v[108:111], v[132:135], v[172:175], v[108:111]
	v_mfma_f32_16x16x32_bf16 v[104:107], v[140:143], v[172:175], v[104:107]
	v_mfma_f32_16x16x32_bf16 v[92:95], v[132:135], v[196:199], v[92:95]
	v_mfma_f32_16x16x32_bf16 v[88:91], v[140:143], v[196:199], v[88:91]
	v_mfma_f32_16x16x32_bf16 v[76:79], v[132:135], v[204:207], v[76:79]
	v_mfma_f32_16x16x32_bf16 v[72:75], v[140:143], v[204:207], v[72:75]
	s_setprio 0
	s_setprio 1
	v_mfma_f32_16x16x32_bf16 v[116:119], v[144:147], v[160:163], 0
	v_mfma_f32_16x16x32_bf16 v[112:115], v[152:155], v[160:163], 0
	v_mfma_f32_16x16x32_bf16 v[100:103], v[144:147], v[168:171], 0
	v_mfma_f32_16x16x32_bf16 v[96:99], v[152:155], v[168:171], 0
	v_mfma_f32_16x16x32_bf16 v[84:87], v[144:147], v[192:195], 0
	v_mfma_f32_16x16x32_bf16 v[80:83], v[152:155], v[192:195], 0
	v_mfma_f32_16x16x32_bf16 v[68:71], v[144:147], v[200:203], 0
	v_mfma_f32_16x16x32_bf16 v[64:67], v[152:155], v[200:203], 0
	v_mfma_f32_16x16x32_bf16 v[116:119], v[148:151], v[164:167], v[116:119]
	v_mfma_f32_16x16x32_bf16 v[112:115], v[156:159], v[164:167], v[112:115]
	v_mfma_f32_16x16x32_bf16 v[100:103], v[148:151], v[172:175], v[100:103]
	v_mfma_f32_16x16x32_bf16 v[96:99], v[156:159], v[172:175], v[96:99]
	v_mfma_f32_16x16x32_bf16 v[84:87], v[148:151], v[196:199], v[84:87]
	v_mfma_f32_16x16x32_bf16 v[80:83], v[156:159], v[196:199], v[80:83]
	v_mfma_f32_16x16x32_bf16 v[68:71], v[148:151], v[204:207], v[68:71]
	v_mfma_f32_16x16x32_bf16 v[64:67], v[156:159], v[204:207], v[64:67]
	s_barrier
	s_setprio 0
	s_add_i32 s59, s55, s31
	s_add_u32 s98, s44, s20
	s_addc_u32 s99, s45, s21
	s_mov_b32 m0, s59
	ds_read_b128 v[160:163], v218 offset:16384
	ds_read_b128 v[164:167], v218 offset:17408
	ds_read_b128 v[168:171], v218 offset:18432
	ds_read_b128 v[172:175], v218 offset:19456
	ds_read_b128 v[192:195], v218 offset:20480
	ds_read_b128 v[196:199], v218 offset:21504
	ds_read_b128 v[200:203], v218 offset:22528
	ds_read_b128 v[204:207], v218 offset:23552
	global_load_lds_dwordx4 v178, s[44:45]
	s_add_i32 m0, s59, 0x2000
	s_add_u32 s60, s44, 0x80000
	s_addc_u32 s61, s45, 0
	s_add_i32 s59, s56, s31
	global_load_lds_dwordx4 v182, s[44:45]
	s_mov_b32 m0, s59
	s_add_u32 s100, s46, s20
	s_addc_u32 s101, s47, s21
	global_load_lds_dwordx4 v178, s[60:61]
	s_add_i32 m0, s59, 0x2000
	s_nop 0
	global_load_lds_dwordx4 v182, s[60:61]
	s_mov_b32 m0, s41
	s_nop 0
	global_load_lds_dwordx4 v176, s[46:47]
	s_mov_b32 m0, s48
	s_nop 0
	global_load_lds_dwordx4 v180, s[46:47]
	s_waitcnt vmcnt(8)
	s_waitcnt lgkmcnt(0)
	s_setprio 1
	s_barrier
	v_mfma_f32_16x16x32_bf16 v[60:63], v[128:131], v[160:163], 0
	v_mfma_f32_16x16x32_bf16 v[56:59], v[136:139], v[160:163], 0
	v_mfma_f32_16x16x32_bf16 v[44:47], v[128:131], v[168:171], 0
	v_mfma_f32_16x16x32_bf16 v[40:43], v[136:139], v[168:171], 0
	v_mfma_f32_16x16x32_bf16 v[28:31], v[128:131], v[192:195], 0
	v_mfma_f32_16x16x32_bf16 v[24:27], v[136:139], v[192:195], 0
	v_mfma_f32_16x16x32_bf16 v[12:15], v[128:131], v[200:203], 0
	v_mfma_f32_16x16x32_bf16 v[8:11], v[136:139], v[200:203], 0
	v_mfma_f32_16x16x32_bf16 v[60:63], v[132:135], v[164:167], v[60:63]
	v_mfma_f32_16x16x32_bf16 v[56:59], v[140:143], v[164:167], v[56:59]
	v_mfma_f32_16x16x32_bf16 v[44:47], v[132:135], v[172:175], v[44:47]
	v_mfma_f32_16x16x32_bf16 v[40:43], v[140:143], v[172:175], v[40:43]
	v_mfma_f32_16x16x32_bf16 v[28:31], v[132:135], v[196:199], v[28:31]
	v_mfma_f32_16x16x32_bf16 v[24:27], v[140:143], v[196:199], v[24:27]
	v_mfma_f32_16x16x32_bf16 v[12:15], v[132:135], v[204:207], v[12:15]
	v_mfma_f32_16x16x32_bf16 v[8:11], v[140:143], v[204:207], v[8:11]
	s_setprio 0
	s_setprio 1
	v_mfma_f32_16x16x32_bf16 v[52:55], v[144:147], v[160:163], 0
	v_mfma_f32_16x16x32_bf16 v[48:51], v[152:155], v[160:163], 0
	v_mfma_f32_16x16x32_bf16 v[36:39], v[144:147], v[168:171], 0
	v_mfma_f32_16x16x32_bf16 v[32:35], v[152:155], v[168:171], 0
	v_mfma_f32_16x16x32_bf16 v[20:23], v[144:147], v[192:195], 0
	v_mfma_f32_16x16x32_bf16 v[16:19], v[152:155], v[192:195], 0
	v_mfma_f32_16x16x32_bf16 v[4:7], v[144:147], v[200:203], 0
	v_mfma_f32_16x16x32_bf16 v[0:3], v[152:155], v[200:203], 0
	v_mfma_f32_16x16x32_bf16 v[52:55], v[148:151], v[164:167], v[52:55]
	v_mfma_f32_16x16x32_bf16 v[48:51], v[156:159], v[164:167], v[48:51]
	v_mfma_f32_16x16x32_bf16 v[36:39], v[148:151], v[172:175], v[36:39]
	v_mfma_f32_16x16x32_bf16 v[32:35], v[156:159], v[172:175], v[32:35]
	v_mfma_f32_16x16x32_bf16 v[20:23], v[148:151], v[196:199], v[20:23]
	v_mfma_f32_16x16x32_bf16 v[16:19], v[156:159], v[196:199], v[16:19]
	v_mfma_f32_16x16x32_bf16 v[4:7], v[148:151], v[204:207], v[4:7]
	v_mfma_f32_16x16x32_bf16 v[0:3], v[156:159], v[204:207], v[0:3]
	s_barrier
	s_setprio 0
	s_add_i32 s59, 0, 0x18000
	s_add_i32 s60, 0, 0x1c000
	v_add_u32_e32 v140, s59, v214
	v_add_u32_e32 v156, s60, v214
	ds_read_b128 v[128:131], v140
	ds_read_b128 v[132:135], v140 offset:1024
	ds_read_b128 v[136:139], v140 offset:2048
	ds_read_b128 v[140:143], v140 offset:3072
	ds_read_b128 v[144:147], v156
	ds_read_b128 v[148:151], v156 offset:1024
	ds_read_b128 v[152:155], v156 offset:2048
	ds_read_b128 v[156:159], v156 offset:3072
	s_add_u32 s46, s46, 0x80000
	s_addc_u32 s47, s47, 0
	s_mov_b32 m0, s49
	ds_read_b128 v[160:163], v218 offset:32768
	ds_read_b128 v[164:167], v218 offset:33792
	ds_read_b128 v[168:171], v218 offset:34816
	ds_read_b128 v[172:175], v218 offset:35840
	ds_read_b128 v[192:195], v218 offset:36864
	ds_read_b128 v[196:199], v218 offset:37888
	ds_read_b128 v[200:203], v218 offset:38912
	ds_read_b128 v[204:207], v218 offset:39936
	global_load_lds_dwordx4 v176, s[46:47]
	s_mov_b32 m0, s50
	s_nop 0
	global_load_lds_dwordx4 v180, s[46:47]
	s_waitcnt vmcnt(8)
	s_waitcnt lgkmcnt(0)
	s_setprio 1
	s_barrier
	v_mfma_f32_16x16x32_bf16 v[124:127], v[128:131], v[160:163], v[124:127]
	v_mfma_f32_16x16x32_bf16 v[120:123], v[136:139], v[160:163], v[120:123]
	v_mfma_f32_16x16x32_bf16 v[108:111], v[128:131], v[168:171], v[108:111]
	v_mfma_f32_16x16x32_bf16 v[104:107], v[136:139], v[168:171], v[104:107]
	v_mfma_f32_16x16x32_bf16 v[92:95], v[128:131], v[192:195], v[92:95]
	v_mfma_f32_16x16x32_bf16 v[88:91], v[136:139], v[192:195], v[88:91]
	v_mfma_f32_16x16x32_bf16 v[76:79], v[128:131], v[200:203], v[76:79]
	v_mfma_f32_16x16x32_bf16 v[72:75], v[136:139], v[200:203], v[72:75]
	v_mfma_f32_16x16x32_bf16 v[124:127], v[132:135], v[164:167], v[124:127]
	v_mfma_f32_16x16x32_bf16 v[120:123], v[140:143], v[164:167], v[120:123]
	v_mfma_f32_16x16x32_bf16 v[108:111], v[132:135], v[172:175], v[108:111]
	v_mfma_f32_16x16x32_bf16 v[104:107], v[140:143], v[172:175], v[104:107]
	v_mfma_f32_16x16x32_bf16 v[92:95], v[132:135], v[196:199], v[92:95]
	v_mfma_f32_16x16x32_bf16 v[88:91], v[140:143], v[196:199], v[88:91]
	v_mfma_f32_16x16x32_bf16 v[76:79], v[132:135], v[204:207], v[76:79]
	v_mfma_f32_16x16x32_bf16 v[72:75], v[140:143], v[204:207], v[72:75]
	s_setprio 0
	s_setprio 1
	v_mfma_f32_16x16x32_bf16 v[116:119], v[144:147], v[160:163], v[116:119]
	v_mfma_f32_16x16x32_bf16 v[112:115], v[152:155], v[160:163], v[112:115]
	v_mfma_f32_16x16x32_bf16 v[100:103], v[144:147], v[168:171], v[100:103]
	v_mfma_f32_16x16x32_bf16 v[96:99], v[152:155], v[168:171], v[96:99]
	v_mfma_f32_16x16x32_bf16 v[84:87], v[144:147], v[192:195], v[84:87]
	v_mfma_f32_16x16x32_bf16 v[80:83], v[152:155], v[192:195], v[80:83]
	v_mfma_f32_16x16x32_bf16 v[68:71], v[144:147], v[200:203], v[68:71]
	v_mfma_f32_16x16x32_bf16 v[64:67], v[152:155], v[200:203], v[64:67]
	v_mfma_f32_16x16x32_bf16 v[116:119], v[148:151], v[164:167], v[116:119]
	v_mfma_f32_16x16x32_bf16 v[112:115], v[156:159], v[164:167], v[112:115]
	v_mfma_f32_16x16x32_bf16 v[100:103], v[148:151], v[172:175], v[100:103]
	v_mfma_f32_16x16x32_bf16 v[96:99], v[156:159], v[172:175], v[96:99]
	v_mfma_f32_16x16x32_bf16 v[84:87], v[148:151], v[196:199], v[84:87]
	v_mfma_f32_16x16x32_bf16 v[80:83], v[156:159], v[196:199], v[80:83]
	v_mfma_f32_16x16x32_bf16 v[68:71], v[148:151], v[204:207], v[68:71]
	v_mfma_f32_16x16x32_bf16 v[64:67], v[156:159], v[204:207], v[64:67]
	s_barrier
	s_setprio 0
	s_add_i32 s46, s59, s31
	s_mov_b32 m0, s46
	ds_read_b128 v[160:163], v218 offset:49152
	ds_read_b128 v[164:167], v218 offset:50176
	ds_read_b128 v[168:171], v218 offset:51200
	ds_read_b128 v[172:175], v218 offset:52224
	ds_read_b128 v[192:195], v218 offset:53248
	ds_read_b128 v[196:199], v218 offset:54272
	ds_read_b128 v[200:203], v218 offset:55296
	ds_read_b128 v[204:207], v218 offset:56320
	global_load_lds_dwordx4 v178, s[98:99]
	s_add_i32 m0, s46, 0x2000
	s_add_u32 s44, s44, 0x80080
	s_addc_u32 s45, s45, 0
	s_add_i32 s46, s60, s31
	global_load_lds_dwordx4 v182, s[98:99]
	s_mov_b32 m0, s46
	s_nop 0
	global_load_lds_dwordx4 v178, s[44:45]
	s_add_i32 m0, s46, 0x2000
	s_nop 0
	global_load_lds_dwordx4 v182, s[44:45]
	s_mov_b32 m0, s52
	s_nop 0
	global_load_lds_dwordx4 v176, s[100:101]
	s_mov_b32 m0, s53
	s_nop 0
	global_load_lds_dwordx4 v180, s[100:101]
	s_waitcnt vmcnt(8)
	s_waitcnt lgkmcnt(0)
	s_setprio 1
	s_barrier
	v_mfma_f32_16x16x32_bf16 v[60:63], v[128:131], v[160:163], v[60:63]
	v_mfma_f32_16x16x32_bf16 v[56:59], v[136:139], v[160:163], v[56:59]
	v_mfma_f32_16x16x32_bf16 v[44:47], v[128:131], v[168:171], v[44:47]
	v_mfma_f32_16x16x32_bf16 v[40:43], v[136:139], v[168:171], v[40:43]
	v_mfma_f32_16x16x32_bf16 v[28:31], v[128:131], v[192:195], v[28:31]
	v_mfma_f32_16x16x32_bf16 v[24:27], v[136:139], v[192:195], v[24:27]
	v_mfma_f32_16x16x32_bf16 v[12:15], v[128:131], v[200:203], v[12:15]
	v_mfma_f32_16x16x32_bf16 v[8:11], v[136:139], v[200:203], v[8:11]
	v_mfma_f32_16x16x32_bf16 v[60:63], v[132:135], v[164:167], v[60:63]
	v_mfma_f32_16x16x32_bf16 v[56:59], v[140:143], v[164:167], v[56:59]
	v_mfma_f32_16x16x32_bf16 v[44:47], v[132:135], v[172:175], v[44:47]
	v_mfma_f32_16x16x32_bf16 v[40:43], v[140:143], v[172:175], v[40:43]
	v_mfma_f32_16x16x32_bf16 v[28:31], v[132:135], v[196:199], v[28:31]
	v_mfma_f32_16x16x32_bf16 v[24:27], v[140:143], v[196:199], v[24:27]
	v_mfma_f32_16x16x32_bf16 v[12:15], v[132:135], v[204:207], v[12:15]
	v_mfma_f32_16x16x32_bf16 v[8:11], v[140:143], v[204:207], v[8:11]
	s_setprio 0
	s_setprio 1
	v_mfma_f32_16x16x32_bf16 v[52:55], v[144:147], v[160:163], v[52:55]
	v_mfma_f32_16x16x32_bf16 v[48:51], v[152:155], v[160:163], v[48:51]
	v_mfma_f32_16x16x32_bf16 v[36:39], v[144:147], v[168:171], v[36:39]
	v_mfma_f32_16x16x32_bf16 v[32:35], v[152:155], v[168:171], v[32:35]
	v_mfma_f32_16x16x32_bf16 v[20:23], v[144:147], v[192:195], v[20:23]
	v_mfma_f32_16x16x32_bf16 v[16:19], v[152:155], v[192:195], v[16:19]
	v_mfma_f32_16x16x32_bf16 v[4:7], v[144:147], v[200:203], v[4:7]
	v_mfma_f32_16x16x32_bf16 v[0:3], v[152:155], v[200:203], v[0:3]
	v_mfma_f32_16x16x32_bf16 v[52:55], v[148:151], v[164:167], v[52:55]
	v_mfma_f32_16x16x32_bf16 v[48:51], v[156:159], v[164:167], v[48:51]
	v_mfma_f32_16x16x32_bf16 v[36:39], v[148:151], v[172:175], v[36:39]
	v_mfma_f32_16x16x32_bf16 v[32:35], v[156:159], v[172:175], v[32:35]
	v_mfma_f32_16x16x32_bf16 v[20:23], v[148:151], v[196:199], v[20:23]
	v_mfma_f32_16x16x32_bf16 v[16:19], v[156:159], v[196:199], v[16:19]
	v_mfma_f32_16x16x32_bf16 v[4:7], v[148:151], v[204:207], v[4:7]
	v_mfma_f32_16x16x32_bf16 v[0:3], v[156:159], v[204:207], v[0:3]
	s_barrier
	s_setprio 0
	s_add_i32 s58, s58, 2
	s_add_u32 s42, s42, 0x100
	s_addc_u32 s43, s43, 0
	s_add_u32 s25, s25, 0x100
	s_addc_u32 s35, s35, 0
	s_cmp_gt_u32 s58, 29
.LBB0_543:
	ds_read_b128 v[128:131], v216
	ds_read_b128 v[132:135], v216 offset:1024
	ds_read_b128 v[136:139], v216 offset:2048
	ds_read_b128 v[140:143], v216 offset:3072
	ds_read_b128 v[144:147], v217
	ds_read_b128 v[148:151], v217 offset:1024
	ds_read_b128 v[152:155], v217 offset:2048
	ds_read_b128 v[156:159], v217 offset:3072
	s_add_u32 s44, s42, 0xfff80080
	s_addc_u32 s45, s43, -1
	s_cmp_eq_u32 s58, 28
	s_cselect_b32 s47, s0, s45
	s_cselect_b32 s46, s1, s44
	s_cselect_b32 s45, s3, s35
	s_cselect_b32 s44, s9, s25
	s_add_i32 m0, s41, 0xc000
	ds_read_b128 v[160:163], v218
	ds_read_b128 v[164:167], v218 offset:1024
	ds_read_b128 v[168:171], v218 offset:2048
	ds_read_b128 v[172:175], v218 offset:3072
	ds_read_b128 v[192:195], v218 offset:4096
	ds_read_b128 v[196:199], v218 offset:5120
	ds_read_b128 v[200:203], v218 offset:6144
	ds_read_b128 v[204:207], v218 offset:7168
	global_load_lds_dwordx4 v184, s[42:43]
	s_add_i32 m0, s41, 0xe000
	s_nop 0
	global_load_lds_dwordx4 v186, s[42:43]
	s_waitcnt vmcnt(8)
	s_waitcnt lgkmcnt(0)
	s_setprio 1
	s_barrier
	v_mfma_f32_16x16x32_bf16 v[124:127], v[128:131], v[160:163], v[124:127]
	v_mfma_f32_16x16x32_bf16 v[120:123], v[136:139], v[160:163], v[120:123]
	v_mfma_f32_16x16x32_bf16 v[108:111], v[128:131], v[168:171], v[108:111]
	v_mfma_f32_16x16x32_bf16 v[104:107], v[136:139], v[168:171], v[104:107]
	v_mfma_f32_16x16x32_bf16 v[92:95], v[128:131], v[192:195], v[92:95]
	v_mfma_f32_16x16x32_bf16 v[88:91], v[136:139], v[192:195], v[88:91]
	v_mfma_f32_16x16x32_bf16 v[76:79], v[128:131], v[200:203], v[76:79]
	v_mfma_f32_16x16x32_bf16 v[72:75], v[136:139], v[200:203], v[72:75]
	v_mfma_f32_16x16x32_bf16 v[124:127], v[132:135], v[164:167], v[124:127]
	v_mfma_f32_16x16x32_bf16 v[120:123], v[140:143], v[164:167], v[120:123]
	v_mfma_f32_16x16x32_bf16 v[108:111], v[132:135], v[172:175], v[108:111]
	v_mfma_f32_16x16x32_bf16 v[104:107], v[140:143], v[172:175], v[104:107]
	v_mfma_f32_16x16x32_bf16 v[92:95], v[132:135], v[196:199], v[92:95]
	v_mfma_f32_16x16x32_bf16 v[88:91], v[140:143], v[196:199], v[88:91]
	v_mfma_f32_16x16x32_bf16 v[76:79], v[132:135], v[204:207], v[76:79]
	v_mfma_f32_16x16x32_bf16 v[72:75], v[140:143], v[204:207], v[72:75]
	s_setprio 0
	s_setprio 1
	v_mfma_f32_16x16x32_bf16 v[116:119], v[144:147], v[160:163], v[116:119]
	v_mfma_f32_16x16x32_bf16 v[112:115], v[152:155], v[160:163], v[112:115]
	v_mfma_f32_16x16x32_bf16 v[100:103], v[144:147], v[168:171], v[100:103]
	v_mfma_f32_16x16x32_bf16 v[96:99], v[152:155], v[168:171], v[96:99]
	v_mfma_f32_16x16x32_bf16 v[84:87], v[144:147], v[192:195], v[84:87]
	v_mfma_f32_16x16x32_bf16 v[80:83], v[152:155], v[192:195], v[80:83]
	v_mfma_f32_16x16x32_bf16 v[68:71], v[144:147], v[200:203], v[68:71]
	v_mfma_f32_16x16x32_bf16 v[64:67], v[152:155], v[200:203], v[64:67]
	v_mfma_f32_16x16x32_bf16 v[116:119], v[148:151], v[164:167], v[116:119]
	v_mfma_f32_16x16x32_bf16 v[112:115], v[156:159], v[164:167], v[112:115]
	v_mfma_f32_16x16x32_bf16 v[100:103], v[148:151], v[172:175], v[100:103]
	v_mfma_f32_16x16x32_bf16 v[96:99], v[156:159], v[172:175], v[96:99]
	v_mfma_f32_16x16x32_bf16 v[84:87], v[148:151], v[196:199], v[84:87]
	v_mfma_f32_16x16x32_bf16 v[80:83], v[156:159], v[196:199], v[80:83]
	v_mfma_f32_16x16x32_bf16 v[68:71], v[148:151], v[204:207], v[68:71]
	v_mfma_f32_16x16x32_bf16 v[64:67], v[156:159], v[204:207], v[64:67]
	s_barrier
	s_setprio 0
	s_add_i32 s59, s55, s31
	s_add_u32 s98, s44, s20
	s_addc_u32 s99, s45, s21
	s_mov_b32 m0, s59
	ds_read_b128 v[160:163], v218 offset:16384
	ds_read_b128 v[164:167], v218 offset:17408
	ds_read_b128 v[168:171], v218 offset:18432
	ds_read_b128 v[172:175], v218 offset:19456
	ds_read_b128 v[192:195], v218 offset:20480
	ds_read_b128 v[196:199], v218 offset:21504
	ds_read_b128 v[200:203], v218 offset:22528
	ds_read_b128 v[204:207], v218 offset:23552
	global_load_lds_dwordx4 v178, s[44:45]
	s_add_i32 m0, s59, 0x2000
	s_add_u32 s60, s44, 0x80000
	s_addc_u32 s61, s45, 0
	s_add_i32 s59, s56, s31
	global_load_lds_dwordx4 v182, s[44:45]
	s_mov_b32 m0, s59
	s_add_u32 s100, s46, s20
	s_addc_u32 s101, s47, s21
	global_load_lds_dwordx4 v178, s[60:61]
	s_add_i32 m0, s59, 0x2000
	s_nop 0
	global_load_lds_dwordx4 v182, s[60:61]
	s_mov_b32 m0, s41
	s_nop 0
	global_load_lds_dwordx4 v176, s[46:47]
	s_mov_b32 m0, s48
	s_nop 0
	global_load_lds_dwordx4 v180, s[46:47]
	s_waitcnt vmcnt(8)
	s_waitcnt lgkmcnt(0)
	s_setprio 1
	s_barrier
	v_mfma_f32_16x16x32_bf16 v[60:63], v[128:131], v[160:163], v[60:63]
	v_mfma_f32_16x16x32_bf16 v[56:59], v[136:139], v[160:163], v[56:59]
	v_mfma_f32_16x16x32_bf16 v[44:47], v[128:131], v[168:171], v[44:47]
	v_mfma_f32_16x16x32_bf16 v[40:43], v[136:139], v[168:171], v[40:43]
	v_mfma_f32_16x16x32_bf16 v[28:31], v[128:131], v[192:195], v[28:31]
	v_mfma_f32_16x16x32_bf16 v[24:27], v[136:139], v[192:195], v[24:27]
	v_mfma_f32_16x16x32_bf16 v[12:15], v[128:131], v[200:203], v[12:15]
	v_mfma_f32_16x16x32_bf16 v[8:11], v[136:139], v[200:203], v[8:11]
	v_mfma_f32_16x16x32_bf16 v[60:63], v[132:135], v[164:167], v[60:63]
	v_mfma_f32_16x16x32_bf16 v[56:59], v[140:143], v[164:167], v[56:59]
	v_mfma_f32_16x16x32_bf16 v[44:47], v[132:135], v[172:175], v[44:47]
	v_mfma_f32_16x16x32_bf16 v[40:43], v[140:143], v[172:175], v[40:43]
	v_mfma_f32_16x16x32_bf16 v[28:31], v[132:135], v[196:199], v[28:31]
	v_mfma_f32_16x16x32_bf16 v[24:27], v[140:143], v[196:199], v[24:27]
	v_mfma_f32_16x16x32_bf16 v[12:15], v[132:135], v[204:207], v[12:15]
	v_mfma_f32_16x16x32_bf16 v[8:11], v[140:143], v[204:207], v[8:11]
	s_setprio 0
	s_setprio 1
	v_mfma_f32_16x16x32_bf16 v[52:55], v[144:147], v[160:163], v[52:55]
	v_mfma_f32_16x16x32_bf16 v[48:51], v[152:155], v[160:163], v[48:51]
	v_mfma_f32_16x16x32_bf16 v[36:39], v[144:147], v[168:171], v[36:39]
	v_mfma_f32_16x16x32_bf16 v[32:35], v[152:155], v[168:171], v[32:35]
	v_mfma_f32_16x16x32_bf16 v[20:23], v[144:147], v[192:195], v[20:23]
	v_mfma_f32_16x16x32_bf16 v[16:19], v[152:155], v[192:195], v[16:19]
	v_mfma_f32_16x16x32_bf16 v[4:7], v[144:147], v[200:203], v[4:7]
	v_mfma_f32_16x16x32_bf16 v[0:3], v[152:155], v[200:203], v[0:3]
	v_mfma_f32_16x16x32_bf16 v[52:55], v[148:151], v[164:167], v[52:55]
	v_mfma_f32_16x16x32_bf16 v[48:51], v[156:159], v[164:167], v[48:51]
	v_mfma_f32_16x16x32_bf16 v[36:39], v[148:151], v[172:175], v[36:39]
	v_mfma_f32_16x16x32_bf16 v[32:35], v[156:159], v[172:175], v[32:35]
	v_mfma_f32_16x16x32_bf16 v[20:23], v[148:151], v[196:199], v[20:23]
	v_mfma_f32_16x16x32_bf16 v[16:19], v[156:159], v[196:199], v[16:19]
	v_mfma_f32_16x16x32_bf16 v[4:7], v[148:151], v[204:207], v[4:7]
	v_mfma_f32_16x16x32_bf16 v[0:3], v[156:159], v[204:207], v[0:3]
	s_barrier
	s_setprio 0
	s_add_i32 s59, 0, 0x18000
	s_add_i32 s60, 0, 0x1c000
	v_add_u32_e32 v140, s59, v214
	v_add_u32_e32 v156, s60, v214
	ds_read_b128 v[128:131], v140
	ds_read_b128 v[132:135], v140 offset:1024
	ds_read_b128 v[136:139], v140 offset:2048
	ds_read_b128 v[140:143], v140 offset:3072
	ds_read_b128 v[144:147], v156
	ds_read_b128 v[148:151], v156 offset:1024
	ds_read_b128 v[152:155], v156 offset:2048
	ds_read_b128 v[156:159], v156 offset:3072
	s_add_u32 s46, s46, 0x80000
	s_addc_u32 s47, s47, 0
	s_mov_b32 m0, s49
	ds_read_b128 v[160:163], v218 offset:32768
	ds_read_b128 v[164:167], v218 offset:33792
	ds_read_b128 v[168:171], v218 offset:34816
	ds_read_b128 v[172:175], v218 offset:35840
	ds_read_b128 v[192:195], v218 offset:36864
	ds_read_b128 v[196:199], v218 offset:37888
	ds_read_b128 v[200:203], v218 offset:38912
	ds_read_b128 v[204:207], v218 offset:39936
	global_load_lds_dwordx4 v176, s[46:47]
	s_mov_b32 m0, s50
	s_nop 0
	global_load_lds_dwordx4 v180, s[46:47]
	s_waitcnt vmcnt(8)
	s_waitcnt lgkmcnt(0)
	s_setprio 1
	s_barrier
	v_mfma_f32_16x16x32_bf16 v[124:127], v[128:131], v[160:163], v[124:127]
	v_mfma_f32_16x16x32_bf16 v[120:123], v[136:139], v[160:163], v[120:123]
	v_mfma_f32_16x16x32_bf16 v[108:111], v[128:131], v[168:171], v[108:111]
	v_mfma_f32_16x16x32_bf16 v[104:107], v[136:139], v[168:171], v[104:107]
	v_mfma_f32_16x16x32_bf16 v[92:95], v[128:131], v[192:195], v[92:95]
	v_mfma_f32_16x16x32_bf16 v[88:91], v[136:139], v[192:195], v[88:91]
	v_mfma_f32_16x16x32_bf16 v[76:79], v[128:131], v[200:203], v[76:79]
	v_mfma_f32_16x16x32_bf16 v[72:75], v[136:139], v[200:203], v[72:75]
	v_mfma_f32_16x16x32_bf16 v[124:127], v[132:135], v[164:167], v[124:127]
	v_mfma_f32_16x16x32_bf16 v[120:123], v[140:143], v[164:167], v[120:123]
	v_mfma_f32_16x16x32_bf16 v[108:111], v[132:135], v[172:175], v[108:111]
	v_mfma_f32_16x16x32_bf16 v[104:107], v[140:143], v[172:175], v[104:107]
	v_mfma_f32_16x16x32_bf16 v[92:95], v[132:135], v[196:199], v[92:95]
	v_mfma_f32_16x16x32_bf16 v[88:91], v[140:143], v[196:199], v[88:91]
	v_mfma_f32_16x16x32_bf16 v[76:79], v[132:135], v[204:207], v[76:79]
	v_mfma_f32_16x16x32_bf16 v[72:75], v[140:143], v[204:207], v[72:75]
	s_setprio 0
	s_setprio 1
	v_mfma_f32_16x16x32_bf16 v[116:119], v[144:147], v[160:163], v[116:119]
	v_mfma_f32_16x16x32_bf16 v[112:115], v[152:155], v[160:163], v[112:115]
	v_mfma_f32_16x16x32_bf16 v[100:103], v[144:147], v[168:171], v[100:103]
	v_mfma_f32_16x16x32_bf16 v[96:99], v[152:155], v[168:171], v[96:99]
	v_mfma_f32_16x16x32_bf16 v[84:87], v[144:147], v[192:195], v[84:87]
	v_mfma_f32_16x16x32_bf16 v[80:83], v[152:155], v[192:195], v[80:83]
	v_mfma_f32_16x16x32_bf16 v[68:71], v[144:147], v[200:203], v[68:71]
	v_mfma_f32_16x16x32_bf16 v[64:67], v[152:155], v[200:203], v[64:67]
	v_mfma_f32_16x16x32_bf16 v[116:119], v[148:151], v[164:167], v[116:119]
	v_mfma_f32_16x16x32_bf16 v[112:115], v[156:159], v[164:167], v[112:115]
	v_mfma_f32_16x16x32_bf16 v[100:103], v[148:151], v[172:175], v[100:103]
	v_mfma_f32_16x16x32_bf16 v[96:99], v[156:159], v[172:175], v[96:99]
	v_mfma_f32_16x16x32_bf16 v[84:87], v[148:151], v[196:199], v[84:87]
	v_mfma_f32_16x16x32_bf16 v[80:83], v[156:159], v[196:199], v[80:83]
	v_mfma_f32_16x16x32_bf16 v[68:71], v[148:151], v[204:207], v[68:71]
	v_mfma_f32_16x16x32_bf16 v[64:67], v[156:159], v[204:207], v[64:67]
	s_barrier
	s_setprio 0
	s_add_i32 s46, s59, s31
	s_mov_b32 m0, s46
	ds_read_b128 v[160:163], v218 offset:49152
	ds_read_b128 v[164:167], v218 offset:50176
	ds_read_b128 v[168:171], v218 offset:51200
	ds_read_b128 v[172:175], v218 offset:52224
	ds_read_b128 v[192:195], v218 offset:53248
	ds_read_b128 v[196:199], v218 offset:54272
	ds_read_b128 v[200:203], v218 offset:55296
	ds_read_b128 v[204:207], v218 offset:56320
	global_load_lds_dwordx4 v178, s[98:99]
	s_add_i32 m0, s46, 0x2000
	s_add_u32 s44, s44, 0x80080
	s_addc_u32 s45, s45, 0
	s_add_i32 s46, s60, s31
	global_load_lds_dwordx4 v182, s[98:99]
	s_mov_b32 m0, s46
	s_nop 0
	global_load_lds_dwordx4 v178, s[44:45]
	s_add_i32 m0, s46, 0x2000
	s_nop 0
	global_load_lds_dwordx4 v182, s[44:45]
	s_mov_b32 m0, s52
	s_nop 0
	global_load_lds_dwordx4 v176, s[100:101]
	s_mov_b32 m0, s53
	s_nop 0
	global_load_lds_dwordx4 v180, s[100:101]
	s_waitcnt vmcnt(8)
	s_waitcnt lgkmcnt(0)
	s_setprio 1
	s_barrier
	v_mfma_f32_16x16x32_bf16 v[60:63], v[128:131], v[160:163], v[60:63]
	v_mfma_f32_16x16x32_bf16 v[56:59], v[136:139], v[160:163], v[56:59]
	v_mfma_f32_16x16x32_bf16 v[44:47], v[128:131], v[168:171], v[44:47]
	v_mfma_f32_16x16x32_bf16 v[40:43], v[136:139], v[168:171], v[40:43]
	v_mfma_f32_16x16x32_bf16 v[28:31], v[128:131], v[192:195], v[28:31]
	v_mfma_f32_16x16x32_bf16 v[24:27], v[136:139], v[192:195], v[24:27]
	v_mfma_f32_16x16x32_bf16 v[12:15], v[128:131], v[200:203], v[12:15]
	v_mfma_f32_16x16x32_bf16 v[8:11], v[136:139], v[200:203], v[8:11]
	v_mfma_f32_16x16x32_bf16 v[60:63], v[132:135], v[164:167], v[60:63]
	v_mfma_f32_16x16x32_bf16 v[56:59], v[140:143], v[164:167], v[56:59]
	v_mfma_f32_16x16x32_bf16 v[44:47], v[132:135], v[172:175], v[44:47]
	v_mfma_f32_16x16x32_bf16 v[40:43], v[140:143], v[172:175], v[40:43]
	v_mfma_f32_16x16x32_bf16 v[28:31], v[132:135], v[196:199], v[28:31]
	v_mfma_f32_16x16x32_bf16 v[24:27], v[140:143], v[196:199], v[24:27]
	v_mfma_f32_16x16x32_bf16 v[12:15], v[132:135], v[204:207], v[12:15]
	v_mfma_f32_16x16x32_bf16 v[8:11], v[140:143], v[204:207], v[8:11]
	s_setprio 0
	s_setprio 1
	v_mfma_f32_16x16x32_bf16 v[52:55], v[144:147], v[160:163], v[52:55]
	v_mfma_f32_16x16x32_bf16 v[48:51], v[152:155], v[160:163], v[48:51]
	v_mfma_f32_16x16x32_bf16 v[36:39], v[144:147], v[168:171], v[36:39]
	v_mfma_f32_16x16x32_bf16 v[32:35], v[152:155], v[168:171], v[32:35]
	v_mfma_f32_16x16x32_bf16 v[20:23], v[144:147], v[192:195], v[20:23]
	v_mfma_f32_16x16x32_bf16 v[16:19], v[152:155], v[192:195], v[16:19]
	v_mfma_f32_16x16x32_bf16 v[4:7], v[144:147], v[200:203], v[4:7]
	v_mfma_f32_16x16x32_bf16 v[0:3], v[152:155], v[200:203], v[0:3]
	v_mfma_f32_16x16x32_bf16 v[52:55], v[148:151], v[164:167], v[52:55]
	v_mfma_f32_16x16x32_bf16 v[48:51], v[156:159], v[164:167], v[48:51]
	v_mfma_f32_16x16x32_bf16 v[36:39], v[148:151], v[172:175], v[36:39]
	v_mfma_f32_16x16x32_bf16 v[32:35], v[156:159], v[172:175], v[32:35]
	v_mfma_f32_16x16x32_bf16 v[20:23], v[148:151], v[196:199], v[20:23]
	v_mfma_f32_16x16x32_bf16 v[16:19], v[156:159], v[196:199], v[16:19]
	v_mfma_f32_16x16x32_bf16 v[4:7], v[148:151], v[204:207], v[4:7]
	v_mfma_f32_16x16x32_bf16 v[0:3], v[156:159], v[204:207], v[0:3]
	s_barrier
	s_setprio 0
	s_add_i32 s58, s58, 2
	s_add_u32 s42, s42, 0x100
	s_addc_u32 s43, s43, 0
	s_add_u32 s25, s25, 0x100
	s_addc_u32 s35, s35, 0
	s_cmp_gt_u32 s58, 29
	s_cbranch_scc0 .LBB0_543
	s_and_b64 vcc, exec, s[22:23]
	s_cbranch_vccz .LBB0_546
	s_barrier

.LBB0_635:
	s_ashr_i32 s67, s66, 31
	s_lshl_b64 s[12:13], s[66:67], 20
	s_add_u32 s70, s55, s12
	s_addc_u32 s71, s57, s13
	s_and_b64 s[6:7], s[6:7], exec
	s_cselect_b32 s1, s71, s11
	s_cselect_b32 s3, s70, s10
	s_add_u32 s6, s8, 0x80080
	s_addc_u32 s7, s9, 0
	s_add_u32 s12, s10, 0x100
	s_addc_u32 s13, s11, 0
	s_mov_b32 s15, -2
	s_waitcnt vmcnt(0)
	ds_read_b128 v[148:151], v197
	ds_read_b128 v[170:173], v197 offset:1024
	ds_read_b128 v[174:177], v197 offset:2048
	ds_read_b128 v[178:181], v197 offset:3072
	ds_read_b128 v[182:185], v198
	ds_read_b128 v[186:189], v198 offset:1024
	ds_read_b128 v[202:205], v198 offset:2048
	ds_read_b128 v[206:209], v198 offset:3072
	s_add_u32 s8, s6, 0xfff80080
	s_addc_u32 s9, s7, -1
	s_cmp_eq_u32 s15, 28
	s_cselect_b32 s11, s69, s9
	s_cselect_b32 s10, s68, s8
	s_cselect_b32 s9, s1, s13
	s_cselect_b32 s8, s3, s12
	s_add_i32 m0, s72, 0xc000
	ds_read_b128 v[214:217], v199
	ds_read_b128 v[218:221], v199 offset:1024
	ds_read_b128 v[222:225], v199 offset:2048
	ds_read_b128 v[226:229], v199 offset:3072
	ds_read_b128 v[230:233], v199 offset:4096
	ds_read_b128 v[234:237], v199 offset:5120
	ds_read_b128 v[238:241], v199 offset:6144
	ds_read_b128 v[242:245], v199 offset:7168
	global_load_lds_dwordx4 v162, s[6:7]
	s_add_i32 m0, s72, 0xe000
	s_nop 0
	global_load_lds_dwordx4 v164, s[6:7]
	s_waitcnt vmcnt(8)
	s_waitcnt lgkmcnt(0)
	s_setprio 1
	s_barrier
	v_mfma_f32_16x16x32_bf16 v[112:115], v[148:151], v[214:217], 0
	v_mfma_f32_16x16x32_bf16 v[80:83], v[174:177], v[214:217], 0
	v_mfma_f32_16x16x32_bf16 v[116:119], v[148:151], v[222:225], 0
	v_mfma_f32_16x16x32_bf16 v[88:91], v[174:177], v[222:225], 0
	v_mfma_f32_16x16x32_bf16 v[124:127], v[148:151], v[230:233], 0
	v_mfma_f32_16x16x32_bf16 v[92:95], v[174:177], v[230:233], 0
	v_mfma_f32_16x16x32_bf16 v[120:123], v[148:151], v[238:241], 0
	v_mfma_f32_16x16x32_bf16 v[84:87], v[174:177], v[238:241], 0
	v_mfma_f32_16x16x32_bf16 v[112:115], v[170:173], v[218:221], v[112:115]
	v_mfma_f32_16x16x32_bf16 v[80:83], v[178:181], v[218:221], v[80:83]
	v_mfma_f32_16x16x32_bf16 v[116:119], v[170:173], v[226:229], v[116:119]
	v_mfma_f32_16x16x32_bf16 v[88:91], v[178:181], v[226:229], v[88:91]
	v_mfma_f32_16x16x32_bf16 v[124:127], v[170:173], v[234:237], v[124:127]
	v_mfma_f32_16x16x32_bf16 v[92:95], v[178:181], v[234:237], v[92:95]
	v_mfma_f32_16x16x32_bf16 v[120:123], v[170:173], v[242:245], v[120:123]
	v_mfma_f32_16x16x32_bf16 v[84:87], v[178:181], v[242:245], v[84:87]
	s_setprio 0
	s_setprio 1
	v_mfma_f32_16x16x32_bf16 v[108:111], v[182:185], v[214:217], 0
	v_mfma_f32_16x16x32_bf16 v[76:79], v[202:205], v[214:217], 0
	v_mfma_f32_16x16x32_bf16 v[104:107], v[182:185], v[222:225], 0
	v_mfma_f32_16x16x32_bf16 v[72:75], v[202:205], v[222:225], 0
	v_mfma_f32_16x16x32_bf16 v[100:103], v[182:185], v[230:233], 0
	v_mfma_f32_16x16x32_bf16 v[68:71], v[202:205], v[230:233], 0
	v_mfma_f32_16x16x32_bf16 v[96:99], v[182:185], v[238:241], 0
	v_mfma_f32_16x16x32_bf16 v[64:67], v[202:205], v[238:241], 0
	v_mfma_f32_16x16x32_bf16 v[108:111], v[186:189], v[218:221], v[108:111]
	v_mfma_f32_16x16x32_bf16 v[76:79], v[206:209], v[218:221], v[76:79]
	v_mfma_f32_16x16x32_bf16 v[104:107], v[186:189], v[226:229], v[104:107]
	v_mfma_f32_16x16x32_bf16 v[72:75], v[206:209], v[226:229], v[72:75]
	v_mfma_f32_16x16x32_bf16 v[100:103], v[186:189], v[234:237], v[100:103]
	v_mfma_f32_16x16x32_bf16 v[68:71], v[206:209], v[234:237], v[68:71]
	v_mfma_f32_16x16x32_bf16 v[96:99], v[186:189], v[242:245], v[96:99]
	v_mfma_f32_16x16x32_bf16 v[64:67], v[206:209], v[242:245], v[64:67]
	s_barrier
	s_setprio 0
	s_add_i32 s16, s94, s63
	s_add_u32 s98, s8, s40
	s_addc_u32 s99, s9, s41
	s_mov_b32 m0, s16
	ds_read_b128 v[214:217], v199 offset:16384
	ds_read_b128 v[218:221], v199 offset:17408
	ds_read_b128 v[222:225], v199 offset:18432
	ds_read_b128 v[226:229], v199 offset:19456
	ds_read_b128 v[230:233], v199 offset:20480
	ds_read_b128 v[234:237], v199 offset:21504
	ds_read_b128 v[238:241], v199 offset:22528
	ds_read_b128 v[242:245], v199 offset:23552
	global_load_lds_dwordx4 v154, s[8:9]
	s_add_i32 m0, s16, 0x2000
	s_add_u32 s16, s8, 0x80000
	s_addc_u32 s17, s9, 0
	s_add_i32 s18, s95, s63
	global_load_lds_dwordx4 v158, s[8:9]
	s_mov_b32 m0, s18
	s_add_u32 s100, s10, s40
	s_addc_u32 s101, s11, s41
	global_load_lds_dwordx4 v154, s[16:17]
	s_add_i32 m0, s18, 0x2000
	s_nop 0
	global_load_lds_dwordx4 v158, s[16:17]
	s_mov_b32 m0, s72
	s_nop 0
	global_load_lds_dwordx4 v152, s[10:11]
	s_mov_b32 m0, s73
	s_nop 0
	global_load_lds_dwordx4 v156, s[10:11]
	s_waitcnt vmcnt(8)
	s_waitcnt lgkmcnt(0)
	s_setprio 1
	s_barrier
	v_mfma_f32_16x16x32_bf16 v[48:51], v[148:151], v[214:217], 0
	v_mfma_f32_16x16x32_bf16 v[16:19], v[174:177], v[214:217], 0
	v_mfma_f32_16x16x32_bf16 v[52:55], v[148:151], v[222:225], 0
	v_mfma_f32_16x16x32_bf16 v[24:27], v[174:177], v[222:225], 0
	v_mfma_f32_16x16x32_bf16 v[60:63], v[148:151], v[230:233], 0
	v_mfma_f32_16x16x32_bf16 v[28:31], v[174:177], v[230:233], 0
	v_mfma_f32_16x16x32_bf16 v[56:59], v[148:151], v[238:241], 0
	v_mfma_f32_16x16x32_bf16 v[20:23], v[174:177], v[238:241], 0
	v_mfma_f32_16x16x32_bf16 v[48:51], v[170:173], v[218:221], v[48:51]
	v_mfma_f32_16x16x32_bf16 v[16:19], v[178:181], v[218:221], v[16:19]
	v_mfma_f32_16x16x32_bf16 v[52:55], v[170:173], v[226:229], v[52:55]
	v_mfma_f32_16x16x32_bf16 v[24:27], v[178:181], v[226:229], v[24:27]
	v_mfma_f32_16x16x32_bf16 v[60:63], v[170:173], v[234:237], v[60:63]
	v_mfma_f32_16x16x32_bf16 v[28:31], v[178:181], v[234:237], v[28:31]
	v_mfma_f32_16x16x32_bf16 v[56:59], v[170:173], v[242:245], v[56:59]
	v_mfma_f32_16x16x32_bf16 v[20:23], v[178:181], v[242:245], v[20:23]
	s_setprio 0
	s_setprio 1
	v_mfma_f32_16x16x32_bf16 v[44:47], v[182:185], v[214:217], 0
	v_mfma_f32_16x16x32_bf16 v[12:15], v[202:205], v[214:217], 0
	v_mfma_f32_16x16x32_bf16 v[40:43], v[182:185], v[222:225], 0
	v_mfma_f32_16x16x32_bf16 v[8:11], v[202:205], v[222:225], 0
	v_mfma_f32_16x16x32_bf16 v[36:39], v[182:185], v[230:233], 0
	v_mfma_f32_16x16x32_bf16 v[4:7], v[202:205], v[230:233], 0
	v_mfma_f32_16x16x32_bf16 v[32:35], v[182:185], v[238:241], 0
	v_mfma_f32_16x16x32_bf16 v[0:3], v[202:205], v[238:241], 0
	v_mfma_f32_16x16x32_bf16 v[44:47], v[186:189], v[218:221], v[44:47]
	v_mfma_f32_16x16x32_bf16 v[12:15], v[206:209], v[218:221], v[12:15]
	v_mfma_f32_16x16x32_bf16 v[40:43], v[186:189], v[226:229], v[40:43]
	v_mfma_f32_16x16x32_bf16 v[8:11], v[206:209], v[226:229], v[8:11]
	v_mfma_f32_16x16x32_bf16 v[36:39], v[186:189], v[234:237], v[36:39]
	v_mfma_f32_16x16x32_bf16 v[4:7], v[206:209], v[234:237], v[4:7]
	v_mfma_f32_16x16x32_bf16 v[32:35], v[186:189], v[242:245], v[32:35]
	v_mfma_f32_16x16x32_bf16 v[0:3], v[206:209], v[242:245], v[0:3]
	s_barrier
	s_setprio 0
	s_add_i32 s16, 0, 0x18000
	s_add_i32 s17, 0, 0x1c000
	v_add_u32_e32 v178, s16, v196
	v_add_u32_e32 v201, s17, v196
	ds_read_b128 v[148:151], v178
	ds_read_b128 v[170:173], v178 offset:1024
	ds_read_b128 v[174:177], v178 offset:2048
	ds_read_b128 v[178:181], v178 offset:3072
	ds_read_b128 v[182:185], v201
	ds_read_b128 v[186:189], v201 offset:1024
	ds_read_b128 v[202:205], v201 offset:2048
	ds_read_b128 v[206:209], v201 offset:3072
	s_add_u32 s10, s10, 0x80000
	s_addc_u32 s11, s11, 0
	s_mov_b32 m0, s74
	ds_read_b128 v[214:217], v199 offset:32768
	ds_read_b128 v[218:221], v199 offset:33792
	ds_read_b128 v[222:225], v199 offset:34816
	ds_read_b128 v[226:229], v199 offset:35840
	ds_read_b128 v[230:233], v199 offset:36864
	ds_read_b128 v[234:237], v199 offset:37888
	ds_read_b128 v[238:241], v199 offset:38912
	ds_read_b128 v[242:245], v199 offset:39936
	global_load_lds_dwordx4 v152, s[10:11]
	s_mov_b32 m0, s75
	s_nop 0
	global_load_lds_dwordx4 v156, s[10:11]
	s_waitcnt vmcnt(8)
	s_waitcnt lgkmcnt(0)
	s_setprio 1
	s_barrier
	v_mfma_f32_16x16x32_bf16 v[112:115], v[148:151], v[214:217], v[112:115]
	v_mfma_f32_16x16x32_bf16 v[80:83], v[174:177], v[214:217], v[80:83]
	v_mfma_f32_16x16x32_bf16 v[116:119], v[148:151], v[222:225], v[116:119]
	v_mfma_f32_16x16x32_bf16 v[88:91], v[174:177], v[222:225], v[88:91]
	v_mfma_f32_16x16x32_bf16 v[124:127], v[148:151], v[230:233], v[124:127]
	v_mfma_f32_16x16x32_bf16 v[92:95], v[174:177], v[230:233], v[92:95]
	v_mfma_f32_16x16x32_bf16 v[120:123], v[148:151], v[238:241], v[120:123]
	v_mfma_f32_16x16x32_bf16 v[84:87], v[174:177], v[238:241], v[84:87]
	v_mfma_f32_16x16x32_bf16 v[112:115], v[170:173], v[218:221], v[112:115]
	v_mfma_f32_16x16x32_bf16 v[80:83], v[178:181], v[218:221], v[80:83]
	v_mfma_f32_16x16x32_bf16 v[116:119], v[170:173], v[226:229], v[116:119]
	v_mfma_f32_16x16x32_bf16 v[88:91], v[178:181], v[226:229], v[88:91]
	v_mfma_f32_16x16x32_bf16 v[124:127], v[170:173], v[234:237], v[124:127]
	v_mfma_f32_16x16x32_bf16 v[92:95], v[178:181], v[234:237], v[92:95]
	v_mfma_f32_16x16x32_bf16 v[120:123], v[170:173], v[242:245], v[120:123]
	v_mfma_f32_16x16x32_bf16 v[84:87], v[178:181], v[242:245], v[84:87]
	s_setprio 0
	s_setprio 1
	v_mfma_f32_16x16x32_bf16 v[108:111], v[182:185], v[214:217], v[108:111]
	v_mfma_f32_16x16x32_bf16 v[76:79], v[202:205], v[214:217], v[76:79]
	v_mfma_f32_16x16x32_bf16 v[104:107], v[182:185], v[222:225], v[104:107]
	v_mfma_f32_16x16x32_bf16 v[72:75], v[202:205], v[222:225], v[72:75]
	v_mfma_f32_16x16x32_bf16 v[100:103], v[182:185], v[230:233], v[100:103]
	v_mfma_f32_16x16x32_bf16 v[68:71], v[202:205], v[230:233], v[68:71]
	v_mfma_f32_16x16x32_bf16 v[96:99], v[182:185], v[238:241], v[96:99]
	v_mfma_f32_16x16x32_bf16 v[64:67], v[202:205], v[238:241], v[64:67]
	v_mfma_f32_16x16x32_bf16 v[108:111], v[186:189], v[218:221], v[108:111]
	v_mfma_f32_16x16x32_bf16 v[76:79], v[206:209], v[218:221], v[76:79]
	v_mfma_f32_16x16x32_bf16 v[104:107], v[186:189], v[226:229], v[104:107]
	v_mfma_f32_16x16x32_bf16 v[72:75], v[206:209], v[226:229], v[72:75]
	v_mfma_f32_16x16x32_bf16 v[100:103], v[186:189], v[234:237], v[100:103]
	v_mfma_f32_16x16x32_bf16 v[68:71], v[206:209], v[234:237], v[68:71]
	v_mfma_f32_16x16x32_bf16 v[96:99], v[186:189], v[242:245], v[96:99]
	v_mfma_f32_16x16x32_bf16 v[64:67], v[206:209], v[242:245], v[64:67]
	s_barrier
	s_setprio 0
	s_add_i32 s10, s16, s63
	s_mov_b32 m0, s10
	ds_read_b128 v[214:217], v199 offset:49152
	ds_read_b128 v[218:221], v199 offset:50176
	ds_read_b128 v[222:225], v199 offset:51200
	ds_read_b128 v[226:229], v199 offset:52224
	ds_read_b128 v[230:233], v199 offset:53248
	ds_read_b128 v[234:237], v199 offset:54272
	ds_read_b128 v[238:241], v199 offset:55296
	ds_read_b128 v[242:245], v199 offset:56320
	global_load_lds_dwordx4 v154, s[98:99]
	s_add_i32 m0, s10, 0x2000
	s_add_u32 s8, s8, 0x80080
	s_addc_u32 s9, s9, 0
	s_add_i32 s10, s17, s63
	global_load_lds_dwordx4 v158, s[98:99]
	s_mov_b32 m0, s10
	s_nop 0
	global_load_lds_dwordx4 v154, s[8:9]
	s_add_i32 m0, s10, 0x2000
	s_nop 0
	global_load_lds_dwordx4 v158, s[8:9]
	s_mov_b32 m0, s82
	s_nop 0
	global_load_lds_dwordx4 v152, s[100:101]
	s_mov_b32 m0, s83
	s_nop 0
	global_load_lds_dwordx4 v156, s[100:101]
	s_waitcnt vmcnt(8)
	s_waitcnt lgkmcnt(0)
	s_setprio 1
	s_barrier
	v_mfma_f32_16x16x32_bf16 v[48:51], v[148:151], v[214:217], v[48:51]
	v_mfma_f32_16x16x32_bf16 v[16:19], v[174:177], v[214:217], v[16:19]
	v_mfma_f32_16x16x32_bf16 v[52:55], v[148:151], v[222:225], v[52:55]
	v_mfma_f32_16x16x32_bf16 v[24:27], v[174:177], v[222:225], v[24:27]
	v_mfma_f32_16x16x32_bf16 v[60:63], v[148:151], v[230:233], v[60:63]
	v_mfma_f32_16x16x32_bf16 v[28:31], v[174:177], v[230:233], v[28:31]
	v_mfma_f32_16x16x32_bf16 v[56:59], v[148:151], v[238:241], v[56:59]
	v_mfma_f32_16x16x32_bf16 v[20:23], v[174:177], v[238:241], v[20:23]
	v_mfma_f32_16x16x32_bf16 v[48:51], v[170:173], v[218:221], v[48:51]
	v_mfma_f32_16x16x32_bf16 v[16:19], v[178:181], v[218:221], v[16:19]
	v_mfma_f32_16x16x32_bf16 v[52:55], v[170:173], v[226:229], v[52:55]
	v_mfma_f32_16x16x32_bf16 v[24:27], v[178:181], v[226:229], v[24:27]
	v_mfma_f32_16x16x32_bf16 v[60:63], v[170:173], v[234:237], v[60:63]
	v_mfma_f32_16x16x32_bf16 v[28:31], v[178:181], v[234:237], v[28:31]
	v_mfma_f32_16x16x32_bf16 v[56:59], v[170:173], v[242:245], v[56:59]
	v_mfma_f32_16x16x32_bf16 v[20:23], v[178:181], v[242:245], v[20:23]
	s_setprio 0
	s_setprio 1
	v_mfma_f32_16x16x32_bf16 v[44:47], v[182:185], v[214:217], v[44:47]
	v_mfma_f32_16x16x32_bf16 v[12:15], v[202:205], v[214:217], v[12:15]
	v_mfma_f32_16x16x32_bf16 v[40:43], v[182:185], v[222:225], v[40:43]
	v_mfma_f32_16x16x32_bf16 v[8:11], v[202:205], v[222:225], v[8:11]
	v_mfma_f32_16x16x32_bf16 v[36:39], v[182:185], v[230:233], v[36:39]
	v_mfma_f32_16x16x32_bf16 v[4:7], v[202:205], v[230:233], v[4:7]
	v_mfma_f32_16x16x32_bf16 v[32:35], v[182:185], v[238:241], v[32:35]
	v_mfma_f32_16x16x32_bf16 v[0:3], v[202:205], v[238:241], v[0:3]
	v_mfma_f32_16x16x32_bf16 v[44:47], v[186:189], v[218:221], v[44:47]
	v_mfma_f32_16x16x32_bf16 v[12:15], v[206:209], v[218:221], v[12:15]
	v_mfma_f32_16x16x32_bf16 v[40:43], v[186:189], v[226:229], v[40:43]
	v_mfma_f32_16x16x32_bf16 v[8:11], v[206:209], v[226:229], v[8:11]
	v_mfma_f32_16x16x32_bf16 v[36:39], v[186:189], v[234:237], v[36:39]
	v_mfma_f32_16x16x32_bf16 v[4:7], v[206:209], v[234:237], v[4:7]
	v_mfma_f32_16x16x32_bf16 v[32:35], v[186:189], v[242:245], v[32:35]
	v_mfma_f32_16x16x32_bf16 v[0:3], v[206:209], v[242:245], v[0:3]
	s_barrier
	s_setprio 0
	s_add_i32 s15, s15, 2
	s_add_u32 s6, s6, 0x100
	s_addc_u32 s7, s7, 0
	s_add_u32 s12, s12, 0x100
	s_addc_u32 s13, s13, 0
	s_cmp_gt_u32 s15, 29
.LBB0_636:
	ds_read_b128 v[148:151], v197
	ds_read_b128 v[170:173], v197 offset:1024
	ds_read_b128 v[174:177], v197 offset:2048
	ds_read_b128 v[178:181], v197 offset:3072
	ds_read_b128 v[182:185], v198
	ds_read_b128 v[186:189], v198 offset:1024
	ds_read_b128 v[202:205], v198 offset:2048
	ds_read_b128 v[206:209], v198 offset:3072
	s_add_u32 s8, s6, 0xfff80080
	s_addc_u32 s9, s7, -1
	s_cmp_eq_u32 s15, 28
	s_cselect_b32 s11, s69, s9
	s_cselect_b32 s10, s68, s8
	s_cselect_b32 s9, s1, s13
	s_cselect_b32 s8, s3, s12
	s_add_i32 m0, s72, 0xc000
	ds_read_b128 v[214:217], v199
	ds_read_b128 v[218:221], v199 offset:1024
	ds_read_b128 v[222:225], v199 offset:2048
	ds_read_b128 v[226:229], v199 offset:3072
	ds_read_b128 v[230:233], v199 offset:4096
	ds_read_b128 v[234:237], v199 offset:5120
	ds_read_b128 v[238:241], v199 offset:6144
	ds_read_b128 v[242:245], v199 offset:7168
	global_load_lds_dwordx4 v162, s[6:7]
	s_add_i32 m0, s72, 0xe000
	s_nop 0
	global_load_lds_dwordx4 v164, s[6:7]
	s_waitcnt vmcnt(8)
	s_waitcnt lgkmcnt(0)
	s_setprio 1
	s_barrier
	v_mfma_f32_16x16x32_bf16 v[112:115], v[148:151], v[214:217], v[112:115]
	v_mfma_f32_16x16x32_bf16 v[80:83], v[174:177], v[214:217], v[80:83]
	v_mfma_f32_16x16x32_bf16 v[116:119], v[148:151], v[222:225], v[116:119]
	v_mfma_f32_16x16x32_bf16 v[88:91], v[174:177], v[222:225], v[88:91]
	v_mfma_f32_16x16x32_bf16 v[124:127], v[148:151], v[230:233], v[124:127]
	v_mfma_f32_16x16x32_bf16 v[92:95], v[174:177], v[230:233], v[92:95]
	v_mfma_f32_16x16x32_bf16 v[120:123], v[148:151], v[238:241], v[120:123]
	v_mfma_f32_16x16x32_bf16 v[84:87], v[174:177], v[238:241], v[84:87]
	v_mfma_f32_16x16x32_bf16 v[112:115], v[170:173], v[218:221], v[112:115]
	v_mfma_f32_16x16x32_bf16 v[80:83], v[178:181], v[218:221], v[80:83]
	v_mfma_f32_16x16x32_bf16 v[116:119], v[170:173], v[226:229], v[116:119]
	v_mfma_f32_16x16x32_bf16 v[88:91], v[178:181], v[226:229], v[88:91]
	v_mfma_f32_16x16x32_bf16 v[124:127], v[170:173], v[234:237], v[124:127]
	v_mfma_f32_16x16x32_bf16 v[92:95], v[178:181], v[234:237], v[92:95]
	v_mfma_f32_16x16x32_bf16 v[120:123], v[170:173], v[242:245], v[120:123]
	v_mfma_f32_16x16x32_bf16 v[84:87], v[178:181], v[242:245], v[84:87]
	s_setprio 0
	s_setprio 1
	v_mfma_f32_16x16x32_bf16 v[108:111], v[182:185], v[214:217], v[108:111]
	v_mfma_f32_16x16x32_bf16 v[76:79], v[202:205], v[214:217], v[76:79]
	v_mfma_f32_16x16x32_bf16 v[104:107], v[182:185], v[222:225], v[104:107]
	v_mfma_f32_16x16x32_bf16 v[72:75], v[202:205], v[222:225], v[72:75]
	v_mfma_f32_16x16x32_bf16 v[100:103], v[182:185], v[230:233], v[100:103]
	v_mfma_f32_16x16x32_bf16 v[68:71], v[202:205], v[230:233], v[68:71]
	v_mfma_f32_16x16x32_bf16 v[96:99], v[182:185], v[238:241], v[96:99]
	v_mfma_f32_16x16x32_bf16 v[64:67], v[202:205], v[238:241], v[64:67]
	v_mfma_f32_16x16x32_bf16 v[108:111], v[186:189], v[218:221], v[108:111]
	v_mfma_f32_16x16x32_bf16 v[76:79], v[206:209], v[218:221], v[76:79]
	v_mfma_f32_16x16x32_bf16 v[104:107], v[186:189], v[226:229], v[104:107]
	v_mfma_f32_16x16x32_bf16 v[72:75], v[206:209], v[226:229], v[72:75]
	v_mfma_f32_16x16x32_bf16 v[100:103], v[186:189], v[234:237], v[100:103]
	v_mfma_f32_16x16x32_bf16 v[68:71], v[206:209], v[234:237], v[68:71]
	v_mfma_f32_16x16x32_bf16 v[96:99], v[186:189], v[242:245], v[96:99]
	v_mfma_f32_16x16x32_bf16 v[64:67], v[206:209], v[242:245], v[64:67]
	s_barrier
	s_setprio 0
	s_add_i32 s16, s94, s63
	s_add_u32 s98, s8, s40
	s_addc_u32 s99, s9, s41
	s_mov_b32 m0, s16
	ds_read_b128 v[214:217], v199 offset:16384
	ds_read_b128 v[218:221], v199 offset:17408
	ds_read_b128 v[222:225], v199 offset:18432
	ds_read_b128 v[226:229], v199 offset:19456
	ds_read_b128 v[230:233], v199 offset:20480
	ds_read_b128 v[234:237], v199 offset:21504
	ds_read_b128 v[238:241], v199 offset:22528
	ds_read_b128 v[242:245], v199 offset:23552
	global_load_lds_dwordx4 v154, s[8:9]
	s_add_i32 m0, s16, 0x2000
	s_add_u32 s16, s8, 0x80000
	s_addc_u32 s17, s9, 0
	s_add_i32 s18, s95, s63
	global_load_lds_dwordx4 v158, s[8:9]
	s_mov_b32 m0, s18
	s_add_u32 s100, s10, s40
	s_addc_u32 s101, s11, s41
	global_load_lds_dwordx4 v154, s[16:17]
	s_add_i32 m0, s18, 0x2000
	s_nop 0
	global_load_lds_dwordx4 v158, s[16:17]
	s_mov_b32 m0, s72
	s_nop 0
	global_load_lds_dwordx4 v152, s[10:11]
	s_mov_b32 m0, s73
	s_nop 0
	global_load_lds_dwordx4 v156, s[10:11]
	s_waitcnt vmcnt(8)
	s_waitcnt lgkmcnt(0)
	s_setprio 1
	s_barrier
	v_mfma_f32_16x16x32_bf16 v[48:51], v[148:151], v[214:217], v[48:51]
	v_mfma_f32_16x16x32_bf16 v[16:19], v[174:177], v[214:217], v[16:19]
	v_mfma_f32_16x16x32_bf16 v[52:55], v[148:151], v[222:225], v[52:55]
	v_mfma_f32_16x16x32_bf16 v[24:27], v[174:177], v[222:225], v[24:27]
	v_mfma_f32_16x16x32_bf16 v[60:63], v[148:151], v[230:233], v[60:63]
	v_mfma_f32_16x16x32_bf16 v[28:31], v[174:177], v[230:233], v[28:31]
	v_mfma_f32_16x16x32_bf16 v[56:59], v[148:151], v[238:241], v[56:59]
	v_mfma_f32_16x16x32_bf16 v[20:23], v[174:177], v[238:241], v[20:23]
	v_mfma_f32_16x16x32_bf16 v[48:51], v[170:173], v[218:221], v[48:51]
	v_mfma_f32_16x16x32_bf16 v[16:19], v[178:181], v[218:221], v[16:19]
	v_mfma_f32_16x16x32_bf16 v[52:55], v[170:173], v[226:229], v[52:55]
	v_mfma_f32_16x16x32_bf16 v[24:27], v[178:181], v[226:229], v[24:27]
	v_mfma_f32_16x16x32_bf16 v[60:63], v[170:173], v[234:237], v[60:63]
	v_mfma_f32_16x16x32_bf16 v[28:31], v[178:181], v[234:237], v[28:31]
	v_mfma_f32_16x16x32_bf16 v[56:59], v[170:173], v[242:245], v[56:59]
	v_mfma_f32_16x16x32_bf16 v[20:23], v[178:181], v[242:245], v[20:23]
	s_setprio 0
	s_setprio 1
	v_mfma_f32_16x16x32_bf16 v[44:47], v[182:185], v[214:217], v[44:47]
	v_mfma_f32_16x16x32_bf16 v[12:15], v[202:205], v[214:217], v[12:15]
	v_mfma_f32_16x16x32_bf16 v[40:43], v[182:185], v[222:225], v[40:43]
	v_mfma_f32_16x16x32_bf16 v[8:11], v[202:205], v[222:225], v[8:11]
	v_mfma_f32_16x16x32_bf16 v[36:39], v[182:185], v[230:233], v[36:39]
	v_mfma_f32_16x16x32_bf16 v[4:7], v[202:205], v[230:233], v[4:7]
	v_mfma_f32_16x16x32_bf16 v[32:35], v[182:185], v[238:241], v[32:35]
	v_mfma_f32_16x16x32_bf16 v[0:3], v[202:205], v[238:241], v[0:3]
	v_mfma_f32_16x16x32_bf16 v[44:47], v[186:189], v[218:221], v[44:47]
	v_mfma_f32_16x16x32_bf16 v[12:15], v[206:209], v[218:221], v[12:15]
	v_mfma_f32_16x16x32_bf16 v[40:43], v[186:189], v[226:229], v[40:43]
	v_mfma_f32_16x16x32_bf16 v[8:11], v[206:209], v[226:229], v[8:11]
	v_mfma_f32_16x16x32_bf16 v[36:39], v[186:189], v[234:237], v[36:39]
	v_mfma_f32_16x16x32_bf16 v[4:7], v[206:209], v[234:237], v[4:7]
	v_mfma_f32_16x16x32_bf16 v[32:35], v[186:189], v[242:245], v[32:35]
	v_mfma_f32_16x16x32_bf16 v[0:3], v[206:209], v[242:245], v[0:3]
	s_barrier
	s_setprio 0
	s_add_i32 s16, 0, 0x18000
	s_add_i32 s17, 0, 0x1c000
	v_add_u32_e32 v178, s16, v196
	v_add_u32_e32 v201, s17, v196
	ds_read_b128 v[148:151], v178
	ds_read_b128 v[170:173], v178 offset:1024
	ds_read_b128 v[174:177], v178 offset:2048
	ds_read_b128 v[178:181], v178 offset:3072
	ds_read_b128 v[182:185], v201
	ds_read_b128 v[186:189], v201 offset:1024
	ds_read_b128 v[202:205], v201 offset:2048
	ds_read_b128 v[206:209], v201 offset:3072
	s_add_u32 s10, s10, 0x80000
	s_addc_u32 s11, s11, 0
	s_mov_b32 m0, s74
	ds_read_b128 v[214:217], v199 offset:32768
	ds_read_b128 v[218:221], v199 offset:33792
	ds_read_b128 v[222:225], v199 offset:34816
	ds_read_b128 v[226:229], v199 offset:35840
	ds_read_b128 v[230:233], v199 offset:36864
	ds_read_b128 v[234:237], v199 offset:37888
	ds_read_b128 v[238:241], v199 offset:38912
	ds_read_b128 v[242:245], v199 offset:39936
	global_load_lds_dwordx4 v152, s[10:11]
	s_mov_b32 m0, s75
	s_nop 0
	global_load_lds_dwordx4 v156, s[10:11]
	s_waitcnt vmcnt(8)
	s_waitcnt lgkmcnt(0)
	s_setprio 1
	s_barrier
	v_mfma_f32_16x16x32_bf16 v[112:115], v[148:151], v[214:217], v[112:115]
	v_mfma_f32_16x16x32_bf16 v[80:83], v[174:177], v[214:217], v[80:83]
	v_mfma_f32_16x16x32_bf16 v[116:119], v[148:151], v[222:225], v[116:119]
	v_mfma_f32_16x16x32_bf16 v[88:91], v[174:177], v[222:225], v[88:91]
	v_mfma_f32_16x16x32_bf16 v[124:127], v[148:151], v[230:233], v[124:127]
	v_mfma_f32_16x16x32_bf16 v[92:95], v[174:177], v[230:233], v[92:95]
	v_mfma_f32_16x16x32_bf16 v[120:123], v[148:151], v[238:241], v[120:123]
	v_mfma_f32_16x16x32_bf16 v[84:87], v[174:177], v[238:241], v[84:87]
	v_mfma_f32_16x16x32_bf16 v[112:115], v[170:173], v[218:221], v[112:115]
	v_mfma_f32_16x16x32_bf16 v[80:83], v[178:181], v[218:221], v[80:83]
	v_mfma_f32_16x16x32_bf16 v[116:119], v[170:173], v[226:229], v[116:119]
	v_mfma_f32_16x16x32_bf16 v[88:91], v[178:181], v[226:229], v[88:91]
	v_mfma_f32_16x16x32_bf16 v[124:127], v[170:173], v[234:237], v[124:127]
	v_mfma_f32_16x16x32_bf16 v[92:95], v[178:181], v[234:237], v[92:95]
	v_mfma_f32_16x16x32_bf16 v[120:123], v[170:173], v[242:245], v[120:123]
	v_mfma_f32_16x16x32_bf16 v[84:87], v[178:181], v[242:245], v[84:87]
	s_setprio 0
	s_setprio 1
	v_mfma_f32_16x16x32_bf16 v[108:111], v[182:185], v[214:217], v[108:111]
	v_mfma_f32_16x16x32_bf16 v[76:79], v[202:205], v[214:217], v[76:79]
	v_mfma_f32_16x16x32_bf16 v[104:107], v[182:185], v[222:225], v[104:107]
	v_mfma_f32_16x16x32_bf16 v[72:75], v[202:205], v[222:225], v[72:75]
	v_mfma_f32_16x16x32_bf16 v[100:103], v[182:185], v[230:233], v[100:103]
	v_mfma_f32_16x16x32_bf16 v[68:71], v[202:205], v[230:233], v[68:71]
	v_mfma_f32_16x16x32_bf16 v[96:99], v[182:185], v[238:241], v[96:99]
	v_mfma_f32_16x16x32_bf16 v[64:67], v[202:205], v[238:241], v[64:67]
	v_mfma_f32_16x16x32_bf16 v[108:111], v[186:189], v[218:221], v[108:111]
	v_mfma_f32_16x16x32_bf16 v[76:79], v[206:209], v[218:221], v[76:79]
	v_mfma_f32_16x16x32_bf16 v[104:107], v[186:189], v[226:229], v[104:107]
	v_mfma_f32_16x16x32_bf16 v[72:75], v[206:209], v[226:229], v[72:75]
	v_mfma_f32_16x16x32_bf16 v[100:103], v[186:189], v[234:237], v[100:103]
	v_mfma_f32_16x16x32_bf16 v[68:71], v[206:209], v[234:237], v[68:71]
	v_mfma_f32_16x16x32_bf16 v[96:99], v[186:189], v[242:245], v[96:99]
	v_mfma_f32_16x16x32_bf16 v[64:67], v[206:209], v[242:245], v[64:67]
	s_barrier
	s_setprio 0
	s_add_i32 s10, s16, s63
	s_mov_b32 m0, s10
	ds_read_b128 v[214:217], v199 offset:49152
	ds_read_b128 v[218:221], v199 offset:50176
	ds_read_b128 v[222:225], v199 offset:51200
	ds_read_b128 v[226:229], v199 offset:52224
	ds_read_b128 v[230:233], v199 offset:53248
	ds_read_b128 v[234:237], v199 offset:54272
	ds_read_b128 v[238:241], v199 offset:55296
	ds_read_b128 v[242:245], v199 offset:56320
	global_load_lds_dwordx4 v154, s[98:99]
	s_add_i32 m0, s10, 0x2000
	s_add_u32 s8, s8, 0x80080
	s_addc_u32 s9, s9, 0
	s_add_i32 s10, s17, s63
	global_load_lds_dwordx4 v158, s[98:99]
	s_mov_b32 m0, s10
	s_nop 0
	global_load_lds_dwordx4 v154, s[8:9]
	s_add_i32 m0, s10, 0x2000
	s_nop 0
	global_load_lds_dwordx4 v158, s[8:9]
	s_mov_b32 m0, s82
	s_nop 0
	global_load_lds_dwordx4 v152, s[100:101]
	s_mov_b32 m0, s83
	s_nop 0
	global_load_lds_dwordx4 v156, s[100:101]
	s_waitcnt vmcnt(8)
	s_waitcnt lgkmcnt(0)
	s_setprio 1
	s_barrier
	v_mfma_f32_16x16x32_bf16 v[48:51], v[148:151], v[214:217], v[48:51]
	v_mfma_f32_16x16x32_bf16 v[16:19], v[174:177], v[214:217], v[16:19]
	v_mfma_f32_16x16x32_bf16 v[52:55], v[148:151], v[222:225], v[52:55]
	v_mfma_f32_16x16x32_bf16 v[24:27], v[174:177], v[222:225], v[24:27]
	v_mfma_f32_16x16x32_bf16 v[60:63], v[148:151], v[230:233], v[60:63]
	v_mfma_f32_16x16x32_bf16 v[28:31], v[174:177], v[230:233], v[28:31]
	v_mfma_f32_16x16x32_bf16 v[56:59], v[148:151], v[238:241], v[56:59]
	v_mfma_f32_16x16x32_bf16 v[20:23], v[174:177], v[238:241], v[20:23]
	v_mfma_f32_16x16x32_bf16 v[48:51], v[170:173], v[218:221], v[48:51]
	v_mfma_f32_16x16x32_bf16 v[16:19], v[178:181], v[218:221], v[16:19]
	v_mfma_f32_16x16x32_bf16 v[52:55], v[170:173], v[226:229], v[52:55]
	v_mfma_f32_16x16x32_bf16 v[24:27], v[178:181], v[226:229], v[24:27]
	v_mfma_f32_16x16x32_bf16 v[60:63], v[170:173], v[234:237], v[60:63]
	v_mfma_f32_16x16x32_bf16 v[28:31], v[178:181], v[234:237], v[28:31]
	v_mfma_f32_16x16x32_bf16 v[56:59], v[170:173], v[242:245], v[56:59]
	v_mfma_f32_16x16x32_bf16 v[20:23], v[178:181], v[242:245], v[20:23]
	s_setprio 0
	s_setprio 1
	v_mfma_f32_16x16x32_bf16 v[44:47], v[182:185], v[214:217], v[44:47]
	v_mfma_f32_16x16x32_bf16 v[12:15], v[202:205], v[214:217], v[12:15]
	v_mfma_f32_16x16x32_bf16 v[40:43], v[182:185], v[222:225], v[40:43]
	v_mfma_f32_16x16x32_bf16 v[8:11], v[202:205], v[222:225], v[8:11]
	v_mfma_f32_16x16x32_bf16 v[36:39], v[182:185], v[230:233], v[36:39]
	v_mfma_f32_16x16x32_bf16 v[4:7], v[202:205], v[230:233], v[4:7]
	v_mfma_f32_16x16x32_bf16 v[32:35], v[182:185], v[238:241], v[32:35]
	v_mfma_f32_16x16x32_bf16 v[0:3], v[202:205], v[238:241], v[0:3]
	v_mfma_f32_16x16x32_bf16 v[44:47], v[186:189], v[218:221], v[44:47]
	v_mfma_f32_16x16x32_bf16 v[12:15], v[206:209], v[218:221], v[12:15]
	v_mfma_f32_16x16x32_bf16 v[40:43], v[186:189], v[226:229], v[40:43]
	v_mfma_f32_16x16x32_bf16 v[8:11], v[206:209], v[226:229], v[8:11]
	v_mfma_f32_16x16x32_bf16 v[36:39], v[186:189], v[234:237], v[36:39]
	v_mfma_f32_16x16x32_bf16 v[4:7], v[206:209], v[234:237], v[4:7]
	v_mfma_f32_16x16x32_bf16 v[32:35], v[186:189], v[242:245], v[32:35]
	v_mfma_f32_16x16x32_bf16 v[0:3], v[206:209], v[242:245], v[0:3]
	s_barrier
	s_setprio 0
	s_add_i32 s15, s15, 2
	s_add_u32 s6, s6, 0x100
	s_addc_u32 s7, s7, 0
	s_add_u32 s12, s12, 0x100
	s_addc_u32 s13, s13, 0
	s_cmp_gt_u32 s15, 29
	s_cbranch_scc0 .LBB0_636
	s_and_b64 vcc, exec, s[42:43]
	s_cbranch_vccz .LBB0_639
	s_barrier

.LBB0_843:
	ds_read_b128 v[128:131], v184
	ds_read_b128 v[132:135], v184 offset:1024
	ds_read_b128 v[136:139], v184 offset:2048
	ds_read_b128 v[140:143], v184 offset:3072
	ds_read_b128 v[144:147], v185
	ds_read_b128 v[148:151], v185 offset:1024
	ds_read_b128 v[168:171], v185 offset:2048
	ds_read_b128 v[172:175], v185 offset:3072
	s_add_u32 s34, s30, 0x100
	s_addc_u32 s35, s31, 0
	s_cmpk_eq_i32 s59, 0x52
	s_cselect_b32 s39, s7, s35
	s_cselect_b32 s38, s6, s34
	s_cselect_b32 s37, s27, s58
	s_cselect_b32 s36, s26, s3
	v_lshl_add_u64 v[218:219], s[30:31], 0, v[160:161]
	s_add_i32 m0, s45, 0xc000
	ds_read_b128 v[176:179], v186
	ds_read_b128 v[188:191], v186 offset:1024
	ds_read_b128 v[192:195], v186 offset:2048
	ds_read_b128 v[196:199], v186 offset:3072
	ds_read_b128 v[200:203], v186 offset:4096
	ds_read_b128 v[204:207], v186 offset:5120
	ds_read_b128 v[208:211], v186 offset:6144
	ds_read_b128 v[214:217], v186 offset:7168
	global_load_lds_dwordx4 v[218:219], off
	v_lshl_add_u64 v[218:219], s[30:31], 0, v[162:163]
	s_add_i32 m0, s45, 0xe000
	s_nop 0
	global_load_lds_dwordx4 v[218:219], off
	s_waitcnt vmcnt(8)
	s_waitcnt lgkmcnt(0)
	s_setprio 1
	s_barrier
	v_mfma_f32_16x16x32_bf16 v[124:127], v[128:131], v[176:179], v[124:127]
	v_mfma_f32_16x16x32_bf16 v[120:123], v[136:139], v[176:179], v[120:123]
	v_mfma_f32_16x16x32_bf16 v[108:111], v[128:131], v[192:195], v[108:111]
	v_mfma_f32_16x16x32_bf16 v[104:107], v[136:139], v[192:195], v[104:107]
	v_mfma_f32_16x16x32_bf16 v[92:95], v[128:131], v[200:203], v[92:95]
	v_mfma_f32_16x16x32_bf16 v[88:91], v[136:139], v[200:203], v[88:91]
	v_mfma_f32_16x16x32_bf16 v[76:79], v[128:131], v[208:211], v[76:79]
	v_mfma_f32_16x16x32_bf16 v[72:75], v[136:139], v[208:211], v[72:75]
	v_mfma_f32_16x16x32_bf16 v[124:127], v[132:135], v[188:191], v[124:127]
	v_mfma_f32_16x16x32_bf16 v[120:123], v[140:143], v[188:191], v[120:123]
	v_mfma_f32_16x16x32_bf16 v[108:111], v[132:135], v[196:199], v[108:111]
	v_mfma_f32_16x16x32_bf16 v[104:107], v[140:143], v[196:199], v[104:107]
	v_mfma_f32_16x16x32_bf16 v[92:95], v[132:135], v[204:207], v[92:95]
	v_mfma_f32_16x16x32_bf16 v[88:91], v[140:143], v[204:207], v[88:91]
	v_mfma_f32_16x16x32_bf16 v[76:79], v[132:135], v[214:217], v[76:79]
	v_mfma_f32_16x16x32_bf16 v[72:75], v[140:143], v[214:217], v[72:75]
	s_setprio 0
	s_setprio 1
	v_mfma_f32_16x16x32_bf16 v[116:119], v[144:147], v[176:179], v[116:119]
	v_mfma_f32_16x16x32_bf16 v[112:115], v[168:171], v[176:179], v[112:115]
	v_mfma_f32_16x16x32_bf16 v[100:103], v[144:147], v[192:195], v[100:103]
	v_mfma_f32_16x16x32_bf16 v[96:99], v[168:171], v[192:195], v[96:99]
	v_mfma_f32_16x16x32_bf16 v[84:87], v[144:147], v[200:203], v[84:87]
	v_mfma_f32_16x16x32_bf16 v[80:83], v[168:171], v[200:203], v[80:83]
	v_mfma_f32_16x16x32_bf16 v[68:71], v[144:147], v[208:211], v[68:71]
	v_mfma_f32_16x16x32_bf16 v[64:67], v[168:171], v[208:211], v[64:67]
	v_mfma_f32_16x16x32_bf16 v[116:119], v[148:151], v[188:191], v[116:119]
	v_mfma_f32_16x16x32_bf16 v[112:115], v[172:175], v[188:191], v[112:115]
	v_mfma_f32_16x16x32_bf16 v[100:103], v[148:151], v[196:199], v[100:103]
	v_mfma_f32_16x16x32_bf16 v[96:99], v[172:175], v[196:199], v[96:99]
	v_mfma_f32_16x16x32_bf16 v[84:87], v[148:151], v[204:207], v[84:87]
	v_mfma_f32_16x16x32_bf16 v[80:83], v[172:175], v[204:207], v[80:83]
	v_mfma_f32_16x16x32_bf16 v[68:71], v[148:151], v[214:217], v[68:71]
	v_mfma_f32_16x16x32_bf16 v[64:67], v[172:175], v[214:217], v[64:67]
	s_barrier
	s_setprio 0
	s_add_i32 s30, s54, s44
	v_lshl_add_u64 v[218:219], s[36:37], 0, v[154:155]
	s_mov_b32 m0, s30
	ds_read_b128 v[176:179], v186 offset:16384
	ds_read_b128 v[188:191], v186 offset:17408
	ds_read_b128 v[192:195], v186 offset:18432
	ds_read_b128 v[196:199], v186 offset:19456
	ds_read_b128 v[200:203], v186 offset:20480
	ds_read_b128 v[204:207], v186 offset:21504
	ds_read_b128 v[208:211], v186 offset:22528
	ds_read_b128 v[214:217], v186 offset:23552
	global_load_lds_dwordx4 v[218:219], off
	s_add_i32 m0, s30, 0x2000
	s_add_u32 s30, s36, 0x158000
	v_lshl_add_u64 v[220:221], s[36:37], 0, v[158:159]
	s_addc_u32 s31, s37, 0
	s_add_i32 s60, s55, s44
	global_load_lds_dwordx4 v[220:221], off
	v_lshl_add_u64 v[222:223], s[30:31], 0, v[154:155]
	s_mov_b32 m0, s60
	v_lshl_add_u64 v[224:225], s[38:39], 0, v[156:157]
	global_load_lds_dwordx4 v[222:223], off
	v_lshl_add_u64 v[222:223], s[30:31], 0, v[158:159]
	s_add_i32 m0, s60, 0x2000
	s_nop 0
	global_load_lds_dwordx4 v[222:223], off
	v_lshl_add_u64 v[222:223], s[38:39], 0, v[152:153]
	s_mov_b32 m0, s45
	s_nop 0
	global_load_lds_dwordx4 v[222:223], off
	s_mov_b32 m0, s46
	s_nop 0
	global_load_lds_dwordx4 v[224:225], off
	s_waitcnt vmcnt(8)
	s_waitcnt lgkmcnt(0)
	s_setprio 1
	s_barrier
	v_mfma_f32_16x16x32_bf16 v[60:63], v[128:131], v[176:179], v[60:63]
	v_mfma_f32_16x16x32_bf16 v[56:59], v[136:139], v[176:179], v[56:59]
	v_mfma_f32_16x16x32_bf16 v[44:47], v[128:131], v[192:195], v[44:47]
	v_mfma_f32_16x16x32_bf16 v[40:43], v[136:139], v[192:195], v[40:43]
	v_mfma_f32_16x16x32_bf16 v[28:31], v[128:131], v[200:203], v[28:31]
	v_mfma_f32_16x16x32_bf16 v[24:27], v[136:139], v[200:203], v[24:27]
	v_mfma_f32_16x16x32_bf16 v[12:15], v[128:131], v[208:211], v[12:15]
	v_mfma_f32_16x16x32_bf16 v[8:11], v[136:139], v[208:211], v[8:11]
	v_mfma_f32_16x16x32_bf16 v[60:63], v[132:135], v[188:191], v[60:63]
	v_mfma_f32_16x16x32_bf16 v[56:59], v[140:143], v[188:191], v[56:59]
	v_mfma_f32_16x16x32_bf16 v[44:47], v[132:135], v[196:199], v[44:47]
	v_mfma_f32_16x16x32_bf16 v[40:43], v[140:143], v[196:199], v[40:43]
	v_mfma_f32_16x16x32_bf16 v[28:31], v[132:135], v[204:207], v[28:31]
	v_mfma_f32_16x16x32_bf16 v[24:27], v[140:143], v[204:207], v[24:27]
	v_mfma_f32_16x16x32_bf16 v[12:15], v[132:135], v[214:217], v[12:15]
	v_mfma_f32_16x16x32_bf16 v[8:11], v[140:143], v[214:217], v[8:11]
	s_setprio 0
	s_setprio 1
	v_mfma_f32_16x16x32_bf16 v[52:55], v[144:147], v[176:179], v[52:55]
	v_mfma_f32_16x16x32_bf16 v[48:51], v[168:171], v[176:179], v[48:51]
	v_mfma_f32_16x16x32_bf16 v[36:39], v[144:147], v[192:195], v[36:39]
	v_mfma_f32_16x16x32_bf16 v[32:35], v[168:171], v[192:195], v[32:35]
	v_mfma_f32_16x16x32_bf16 v[20:23], v[144:147], v[200:203], v[20:23]
	v_mfma_f32_16x16x32_bf16 v[16:19], v[168:171], v[200:203], v[16:19]
	v_mfma_f32_16x16x32_bf16 v[4:7], v[144:147], v[208:211], v[4:7]
	v_mfma_f32_16x16x32_bf16 v[0:3], v[168:171], v[208:211], v[0:3]
	v_mfma_f32_16x16x32_bf16 v[52:55], v[148:151], v[188:191], v[52:55]
	v_mfma_f32_16x16x32_bf16 v[48:51], v[172:175], v[188:191], v[48:51]
	v_mfma_f32_16x16x32_bf16 v[36:39], v[148:151], v[196:199], v[36:39]
	v_mfma_f32_16x16x32_bf16 v[32:35], v[172:175], v[196:199], v[32:35]
	v_mfma_f32_16x16x32_bf16 v[20:23], v[148:151], v[204:207], v[20:23]
	v_mfma_f32_16x16x32_bf16 v[16:19], v[172:175], v[204:207], v[16:19]
	v_mfma_f32_16x16x32_bf16 v[4:7], v[148:151], v[214:217], v[4:7]
	v_mfma_f32_16x16x32_bf16 v[0:3], v[172:175], v[214:217], v[0:3]
	s_barrier
	s_setprio 0
	s_add_i32 s60, 0, 0x18000
	s_add_i32 s61, 0, 0x1c000
	v_add_u32_e32 v140, s60, v182
	v_add_u32_e32 v172, s61, v182
	ds_read_b128 v[128:131], v140
	ds_read_b128 v[132:135], v140 offset:1024
	ds_read_b128 v[136:139], v140 offset:2048
	ds_read_b128 v[140:143], v140 offset:3072
	ds_read_b128 v[144:147], v172
	ds_read_b128 v[148:151], v172 offset:1024
	ds_read_b128 v[168:171], v172 offset:2048
	ds_read_b128 v[172:175], v172 offset:3072
	s_add_u32 s30, s38, 0x158000
	s_addc_u32 s31, s39, 0
	s_mov_b32 m0, s47
	v_lshl_add_u64 v[226:227], s[30:31], 0, v[152:153]
	ds_read_b128 v[176:179], v186 offset:32768
	ds_read_b128 v[188:191], v186 offset:33792
	ds_read_b128 v[192:195], v186 offset:34816
	ds_read_b128 v[196:199], v186 offset:35840
	ds_read_b128 v[200:203], v186 offset:36864
	ds_read_b128 v[204:207], v186 offset:37888
	ds_read_b128 v[208:211], v186 offset:38912
	ds_read_b128 v[214:217], v186 offset:39936
	global_load_lds_dwordx4 v[226:227], off
	v_lshl_add_u64 v[226:227], s[30:31], 0, v[156:157]
	s_mov_b32 m0, s48
	s_nop 0
	global_load_lds_dwordx4 v[226:227], off
	s_waitcnt vmcnt(8)
	s_waitcnt lgkmcnt(0)
	s_setprio 1
	s_barrier
	v_mfma_f32_16x16x32_bf16 v[124:127], v[128:131], v[176:179], v[124:127]
	v_mfma_f32_16x16x32_bf16 v[120:123], v[136:139], v[176:179], v[120:123]
	v_mfma_f32_16x16x32_bf16 v[108:111], v[128:131], v[192:195], v[108:111]
	v_mfma_f32_16x16x32_bf16 v[104:107], v[136:139], v[192:195], v[104:107]
	v_mfma_f32_16x16x32_bf16 v[92:95], v[128:131], v[200:203], v[92:95]
	v_mfma_f32_16x16x32_bf16 v[88:91], v[136:139], v[200:203], v[88:91]
	v_mfma_f32_16x16x32_bf16 v[76:79], v[128:131], v[208:211], v[76:79]
	v_mfma_f32_16x16x32_bf16 v[72:75], v[136:139], v[208:211], v[72:75]
	v_mfma_f32_16x16x32_bf16 v[124:127], v[132:135], v[188:191], v[124:127]
	v_mfma_f32_16x16x32_bf16 v[120:123], v[140:143], v[188:191], v[120:123]
	v_mfma_f32_16x16x32_bf16 v[108:111], v[132:135], v[196:199], v[108:111]
	v_mfma_f32_16x16x32_bf16 v[104:107], v[140:143], v[196:199], v[104:107]
	v_mfma_f32_16x16x32_bf16 v[92:95], v[132:135], v[204:207], v[92:95]
	v_mfma_f32_16x16x32_bf16 v[88:91], v[140:143], v[204:207], v[88:91]
	v_mfma_f32_16x16x32_bf16 v[76:79], v[132:135], v[214:217], v[76:79]
	v_mfma_f32_16x16x32_bf16 v[72:75], v[140:143], v[214:217], v[72:75]
	s_setprio 0
	s_setprio 1
	v_mfma_f32_16x16x32_bf16 v[116:119], v[144:147], v[176:179], v[116:119]
	v_mfma_f32_16x16x32_bf16 v[112:115], v[168:171], v[176:179], v[112:115]
	v_mfma_f32_16x16x32_bf16 v[100:103], v[144:147], v[192:195], v[100:103]
	v_mfma_f32_16x16x32_bf16 v[96:99], v[168:171], v[192:195], v[96:99]
	v_mfma_f32_16x16x32_bf16 v[84:87], v[144:147], v[200:203], v[84:87]
	v_mfma_f32_16x16x32_bf16 v[80:83], v[168:171], v[200:203], v[80:83]
	v_mfma_f32_16x16x32_bf16 v[68:71], v[144:147], v[208:211], v[68:71]
	v_mfma_f32_16x16x32_bf16 v[64:67], v[168:171], v[208:211], v[64:67]
	v_mfma_f32_16x16x32_bf16 v[116:119], v[148:151], v[188:191], v[116:119]
	v_mfma_f32_16x16x32_bf16 v[112:115], v[172:175], v[188:191], v[112:115]
	v_mfma_f32_16x16x32_bf16 v[100:103], v[148:151], v[196:199], v[100:103]
	v_mfma_f32_16x16x32_bf16 v[96:99], v[172:175], v[196:199], v[96:99]
	v_mfma_f32_16x16x32_bf16 v[84:87], v[148:151], v[204:207], v[84:87]
	v_mfma_f32_16x16x32_bf16 v[80:83], v[172:175], v[204:207], v[80:83]
	v_mfma_f32_16x16x32_bf16 v[68:71], v[148:151], v[214:217], v[68:71]
	v_mfma_f32_16x16x32_bf16 v[64:67], v[172:175], v[214:217], v[64:67]
	s_barrier
	s_setprio 0
	s_add_i32 s30, s60, s44
	v_lshl_add_u64 v[218:219], v[218:219], 0, s[20:21]
	s_mov_b32 m0, s30
	ds_read_b128 v[176:179], v186 offset:49152
	ds_read_b128 v[188:191], v186 offset:50176
	ds_read_b128 v[192:195], v186 offset:51200
	ds_read_b128 v[196:199], v186 offset:52224
	ds_read_b128 v[200:203], v186 offset:53248
	ds_read_b128 v[204:207], v186 offset:54272
	ds_read_b128 v[208:211], v186 offset:55296
	ds_read_b128 v[214:217], v186 offset:56320
	global_load_lds_dwordx4 v[218:219], off
	s_add_i32 m0, s30, 0x2000
	s_add_u32 s30, s36, 0x158080
	v_lshl_add_u64 v[218:219], v[220:221], 0, s[20:21]
	s_addc_u32 s31, s37, 0
	s_add_i32 s36, s61, s44
	global_load_lds_dwordx4 v[218:219], off
	v_lshl_add_u64 v[218:219], s[30:31], 0, v[154:155]
	s_mov_b32 m0, s36
	s_nop 0
	global_load_lds_dwordx4 v[218:219], off
	v_lshl_add_u64 v[218:219], s[30:31], 0, v[158:159]
	s_add_i32 m0, s36, 0x2000
	s_nop 0
	global_load_lds_dwordx4 v[218:219], off
	v_lshl_add_u64 v[218:219], v[222:223], 0, s[20:21]
	s_mov_b32 m0, s51
	s_nop 0
	global_load_lds_dwordx4 v[218:219], off
	v_lshl_add_u64 v[218:219], v[224:225], 0, s[20:21]
	s_mov_b32 m0, s52
	s_nop 0
	global_load_lds_dwordx4 v[218:219], off
	s_waitcnt vmcnt(8)
	s_waitcnt lgkmcnt(0)
	s_setprio 1
	s_barrier
	v_mfma_f32_16x16x32_bf16 v[60:63], v[128:131], v[176:179], v[60:63]
	v_mfma_f32_16x16x32_bf16 v[56:59], v[136:139], v[176:179], v[56:59]
	v_mfma_f32_16x16x32_bf16 v[44:47], v[128:131], v[192:195], v[44:47]
	v_mfma_f32_16x16x32_bf16 v[40:43], v[136:139], v[192:195], v[40:43]
	v_mfma_f32_16x16x32_bf16 v[28:31], v[128:131], v[200:203], v[28:31]
	v_mfma_f32_16x16x32_bf16 v[24:27], v[136:139], v[200:203], v[24:27]
	v_mfma_f32_16x16x32_bf16 v[12:15], v[128:131], v[208:211], v[12:15]
	v_mfma_f32_16x16x32_bf16 v[8:11], v[136:139], v[208:211], v[8:11]
	v_mfma_f32_16x16x32_bf16 v[60:63], v[132:135], v[188:191], v[60:63]
	v_mfma_f32_16x16x32_bf16 v[56:59], v[140:143], v[188:191], v[56:59]
	v_mfma_f32_16x16x32_bf16 v[44:47], v[132:135], v[196:199], v[44:47]
	v_mfma_f32_16x16x32_bf16 v[40:43], v[140:143], v[196:199], v[40:43]
	v_mfma_f32_16x16x32_bf16 v[28:31], v[132:135], v[204:207], v[28:31]
	v_mfma_f32_16x16x32_bf16 v[24:27], v[140:143], v[204:207], v[24:27]
	v_mfma_f32_16x16x32_bf16 v[12:15], v[132:135], v[214:217], v[12:15]
	v_mfma_f32_16x16x32_bf16 v[8:11], v[140:143], v[214:217], v[8:11]
	s_setprio 0
	s_setprio 1
	v_mfma_f32_16x16x32_bf16 v[52:55], v[144:147], v[176:179], v[52:55]
	v_mfma_f32_16x16x32_bf16 v[48:51], v[168:171], v[176:179], v[48:51]
	v_mfma_f32_16x16x32_bf16 v[36:39], v[144:147], v[192:195], v[36:39]
	v_mfma_f32_16x16x32_bf16 v[32:35], v[168:171], v[192:195], v[32:35]
	v_mfma_f32_16x16x32_bf16 v[20:23], v[144:147], v[200:203], v[20:23]
	v_mfma_f32_16x16x32_bf16 v[16:19], v[168:171], v[200:203], v[16:19]
	v_mfma_f32_16x16x32_bf16 v[4:7], v[144:147], v[208:211], v[4:7]
	v_mfma_f32_16x16x32_bf16 v[0:3], v[168:171], v[208:211], v[0:3]
	v_mfma_f32_16x16x32_bf16 v[52:55], v[148:151], v[188:191], v[52:55]
	v_mfma_f32_16x16x32_bf16 v[48:51], v[172:175], v[188:191], v[48:51]
	v_mfma_f32_16x16x32_bf16 v[36:39], v[148:151], v[196:199], v[36:39]
	v_mfma_f32_16x16x32_bf16 v[32:35], v[172:175], v[196:199], v[32:35]
	v_mfma_f32_16x16x32_bf16 v[20:23], v[148:151], v[204:207], v[20:23]
	v_mfma_f32_16x16x32_bf16 v[16:19], v[172:175], v[204:207], v[16:19]
	v_mfma_f32_16x16x32_bf16 v[4:7], v[148:151], v[214:217], v[4:7]
	v_mfma_f32_16x16x32_bf16 v[0:3], v[172:175], v[214:217], v[0:3]
	s_barrier
	s_setprio 0
	s_add_i32 s59, s59, 2
	s_add_u32 s3, s3, 0x100
	s_addc_u32 s58, s58, 0
	s_cmpk_gt_u32 s59, 0x53
	s_mov_b64 s[30:31], s[34:35]
	s_cbranch_scc0 .LBB0_843
	s_and_b64 vcc, exec, s[24:25]
	s_cbranch_vccz .LBB0_846
	s_barrier

.LBB0_875:
	s_mov_b32 s1, -2
	s_mov_b64 s[4:5], s[22:23]
	ds_read_b128 v[128:131], v188
	ds_read_b128 v[132:135], v188 offset:1024
	ds_read_b128 v[136:139], v188 offset:2048
	ds_read_b128 v[140:143], v188 offset:3072
	ds_read_b128 v[144:147], v189
	ds_read_b128 v[148:151], v189 offset:1024
	ds_read_b128 v[166:169], v189 offset:2048
	ds_read_b128 v[170:173], v189 offset:3072
	s_add_u32 s40, s38, 0x100
	s_addc_u32 s41, s39, 0
	s_cmpk_eq_i32 s1, 0x52
	s_cselect_b32 s45, s37, s41
	s_cselect_b32 s44, s36, s40
	s_cselect_b32 s43, s17, s5
	s_cselect_b32 s42, s16, s4
	s_add_i32 m0, s48, 0xc000
	ds_read_b128 v[174:177], v190
	ds_read_b128 v[178:181], v190 offset:1024
	ds_read_b128 v[194:197], v190 offset:2048
	ds_read_b128 v[198:201], v190 offset:3072
	ds_read_b128 v[202:205], v190 offset:4096
	ds_read_b128 v[206:209], v190 offset:5120
	ds_read_b128 v[210:213], v190 offset:6144
	ds_read_b128 v[214:217], v190 offset:7168
	global_load_lds_dwordx4 v160, s[38:39]
	s_add_i32 m0, s48, 0xe000
	s_nop 0
	global_load_lds_dwordx4 v162, s[38:39]
	s_waitcnt vmcnt(8)
	s_waitcnt lgkmcnt(0)
	s_setprio 1
	s_barrier
	v_mfma_f32_16x16x32_bf16 v[124:127], v[128:131], v[174:177], 0
	v_mfma_f32_16x16x32_bf16 v[120:123], v[136:139], v[174:177], 0
	v_mfma_f32_16x16x32_bf16 v[108:111], v[128:131], v[194:197], 0
	v_mfma_f32_16x16x32_bf16 v[104:107], v[136:139], v[194:197], 0
	v_mfma_f32_16x16x32_bf16 v[92:95], v[128:131], v[202:205], 0
	v_mfma_f32_16x16x32_bf16 v[88:91], v[136:139], v[202:205], 0
	v_mfma_f32_16x16x32_bf16 v[76:79], v[128:131], v[210:213], 0
	v_mfma_f32_16x16x32_bf16 v[72:75], v[136:139], v[210:213], 0
	v_mfma_f32_16x16x32_bf16 v[124:127], v[132:135], v[178:181], v[124:127]
	v_mfma_f32_16x16x32_bf16 v[120:123], v[140:143], v[178:181], v[120:123]
	v_mfma_f32_16x16x32_bf16 v[108:111], v[132:135], v[198:201], v[108:111]
	v_mfma_f32_16x16x32_bf16 v[104:107], v[140:143], v[198:201], v[104:107]
	v_mfma_f32_16x16x32_bf16 v[92:95], v[132:135], v[206:209], v[92:95]
	v_mfma_f32_16x16x32_bf16 v[88:91], v[140:143], v[206:209], v[88:91]
	v_mfma_f32_16x16x32_bf16 v[76:79], v[132:135], v[214:217], v[76:79]
	v_mfma_f32_16x16x32_bf16 v[72:75], v[140:143], v[214:217], v[72:75]
	s_setprio 0
	s_setprio 1
	v_mfma_f32_16x16x32_bf16 v[116:119], v[144:147], v[174:177], 0
	v_mfma_f32_16x16x32_bf16 v[112:115], v[166:169], v[174:177], 0
	v_mfma_f32_16x16x32_bf16 v[100:103], v[144:147], v[194:197], 0
	v_mfma_f32_16x16x32_bf16 v[96:99], v[166:169], v[194:197], 0
	v_mfma_f32_16x16x32_bf16 v[84:87], v[144:147], v[202:205], 0
	v_mfma_f32_16x16x32_bf16 v[80:83], v[166:169], v[202:205], 0
	v_mfma_f32_16x16x32_bf16 v[68:71], v[144:147], v[210:213], 0
	v_mfma_f32_16x16x32_bf16 v[64:67], v[166:169], v[210:213], 0
	v_mfma_f32_16x16x32_bf16 v[116:119], v[148:151], v[178:181], v[116:119]
	v_mfma_f32_16x16x32_bf16 v[112:115], v[170:173], v[178:181], v[112:115]
	v_mfma_f32_16x16x32_bf16 v[100:103], v[148:151], v[198:201], v[100:103]
	v_mfma_f32_16x16x32_bf16 v[96:99], v[170:173], v[198:201], v[96:99]
	v_mfma_f32_16x16x32_bf16 v[84:87], v[148:151], v[206:209], v[84:87]
	v_mfma_f32_16x16x32_bf16 v[80:83], v[170:173], v[206:209], v[80:83]
	v_mfma_f32_16x16x32_bf16 v[68:71], v[148:151], v[214:217], v[68:71]
	v_mfma_f32_16x16x32_bf16 v[64:67], v[170:173], v[214:217], v[64:67]
	s_barrier
	s_setprio 0
	s_add_i32 s3, s70, s33
	s_add_u32 s98, s42, s24
	s_addc_u32 s99, s43, s25
	s_mov_b32 m0, s3
	ds_read_b128 v[174:177], v190 offset:16384
	ds_read_b128 v[178:181], v190 offset:17408
	ds_read_b128 v[194:197], v190 offset:18432
	ds_read_b128 v[198:201], v190 offset:19456
	ds_read_b128 v[202:205], v190 offset:20480
	ds_read_b128 v[206:209], v190 offset:21504
	ds_read_b128 v[210:213], v190 offset:22528
	ds_read_b128 v[214:217], v190 offset:23552
	global_load_lds_dwordx4 v154, s[42:43]
	s_add_i32 m0, s3, 0x2000
	s_add_u32 s38, s42, 0x158000
	s_addc_u32 s39, s43, 0
	s_add_i32 s3, s71, s33
	global_load_lds_dwordx4 v158, s[42:43]
	s_mov_b32 m0, s3
	s_add_u32 s100, s44, s24
	s_addc_u32 s101, s45, s25
	global_load_lds_dwordx4 v154, s[38:39]
	s_add_i32 m0, s3, 0x2000
	s_nop 0
	global_load_lds_dwordx4 v158, s[38:39]
	s_mov_b32 m0, s48
	s_nop 0
	global_load_lds_dwordx4 v152, s[44:45]
	s_mov_b32 m0, s49
	s_nop 0
	global_load_lds_dwordx4 v156, s[44:45]
	s_waitcnt vmcnt(8)
	s_waitcnt lgkmcnt(0)
	s_setprio 1
	s_barrier
	v_mfma_f32_16x16x32_bf16 v[60:63], v[128:131], v[174:177], 0
	v_mfma_f32_16x16x32_bf16 v[56:59], v[136:139], v[174:177], 0
	v_mfma_f32_16x16x32_bf16 v[44:47], v[128:131], v[194:197], 0
	v_mfma_f32_16x16x32_bf16 v[40:43], v[136:139], v[194:197], 0
	v_mfma_f32_16x16x32_bf16 v[28:31], v[128:131], v[202:205], 0
	v_mfma_f32_16x16x32_bf16 v[24:27], v[136:139], v[202:205], 0
	v_mfma_f32_16x16x32_bf16 v[12:15], v[128:131], v[210:213], 0
	v_mfma_f32_16x16x32_bf16 v[8:11], v[136:139], v[210:213], 0
	v_mfma_f32_16x16x32_bf16 v[60:63], v[132:135], v[178:181], v[60:63]
	v_mfma_f32_16x16x32_bf16 v[56:59], v[140:143], v[178:181], v[56:59]
	v_mfma_f32_16x16x32_bf16 v[44:47], v[132:135], v[198:201], v[44:47]
	v_mfma_f32_16x16x32_bf16 v[40:43], v[140:143], v[198:201], v[40:43]
	v_mfma_f32_16x16x32_bf16 v[28:31], v[132:135], v[206:209], v[28:31]
	v_mfma_f32_16x16x32_bf16 v[24:27], v[140:143], v[206:209], v[24:27]
	v_mfma_f32_16x16x32_bf16 v[12:15], v[132:135], v[214:217], v[12:15]
	v_mfma_f32_16x16x32_bf16 v[8:11], v[140:143], v[214:217], v[8:11]
	s_setprio 0
	s_setprio 1
	v_mfma_f32_16x16x32_bf16 v[52:55], v[144:147], v[174:177], 0
	v_mfma_f32_16x16x32_bf16 v[48:51], v[166:169], v[174:177], 0
	v_mfma_f32_16x16x32_bf16 v[36:39], v[144:147], v[194:197], 0
	v_mfma_f32_16x16x32_bf16 v[32:35], v[166:169], v[194:197], 0
	v_mfma_f32_16x16x32_bf16 v[20:23], v[144:147], v[202:205], 0
	v_mfma_f32_16x16x32_bf16 v[16:19], v[166:169], v[202:205], 0
	v_mfma_f32_16x16x32_bf16 v[4:7], v[144:147], v[210:213], 0
	v_mfma_f32_16x16x32_bf16 v[0:3], v[166:169], v[210:213], 0
	v_mfma_f32_16x16x32_bf16 v[52:55], v[148:151], v[178:181], v[52:55]
	v_mfma_f32_16x16x32_bf16 v[48:51], v[170:173], v[178:181], v[48:51]
	v_mfma_f32_16x16x32_bf16 v[36:39], v[148:151], v[198:201], v[36:39]
	v_mfma_f32_16x16x32_bf16 v[32:35], v[170:173], v[198:201], v[32:35]
	v_mfma_f32_16x16x32_bf16 v[20:23], v[148:151], v[206:209], v[20:23]
	v_mfma_f32_16x16x32_bf16 v[16:19], v[170:173], v[206:209], v[16:19]
	v_mfma_f32_16x16x32_bf16 v[4:7], v[148:151], v[214:217], v[4:7]
	v_mfma_f32_16x16x32_bf16 v[0:3], v[170:173], v[214:217], v[0:3]
	s_barrier
	s_setprio 0
	s_add_i32 s3, 0, 0x18000
	s_add_i32 s73, 0, 0x1c000
	v_add_u32_e32 v140, s3, v187
	v_add_u32_e32 v170, s73, v187
	ds_read_b128 v[128:131], v140
	ds_read_b128 v[132:135], v140 offset:1024
	ds_read_b128 v[136:139], v140 offset:2048
	ds_read_b128 v[140:143], v140 offset:3072
	ds_read_b128 v[144:147], v170
	ds_read_b128 v[148:151], v170 offset:1024
	ds_read_b128 v[166:169], v170 offset:2048
	ds_read_b128 v[170:173], v170 offset:3072
	s_add_u32 s38, s44, 0x158000
	s_addc_u32 s39, s45, 0
	s_mov_b32 m0, s51
	ds_read_b128 v[174:177], v190 offset:32768
	ds_read_b128 v[178:181], v190 offset:33792
	ds_read_b128 v[194:197], v190 offset:34816
	ds_read_b128 v[198:201], v190 offset:35840
	ds_read_b128 v[202:205], v190 offset:36864
	ds_read_b128 v[206:209], v190 offset:37888
	ds_read_b128 v[210:213], v190 offset:38912
	ds_read_b128 v[214:217], v190 offset:39936
	global_load_lds_dwordx4 v152, s[38:39]
	s_mov_b32 m0, s52
	s_nop 0
	global_load_lds_dwordx4 v156, s[38:39]
	s_waitcnt vmcnt(8)
	s_waitcnt lgkmcnt(0)
	s_setprio 1
	s_barrier
	v_mfma_f32_16x16x32_bf16 v[124:127], v[128:131], v[174:177], v[124:127]
	v_mfma_f32_16x16x32_bf16 v[120:123], v[136:139], v[174:177], v[120:123]
	v_mfma_f32_16x16x32_bf16 v[108:111], v[128:131], v[194:197], v[108:111]
	v_mfma_f32_16x16x32_bf16 v[104:107], v[136:139], v[194:197], v[104:107]
	v_mfma_f32_16x16x32_bf16 v[92:95], v[128:131], v[202:205], v[92:95]
	v_mfma_f32_16x16x32_bf16 v[88:91], v[136:139], v[202:205], v[88:91]
	v_mfma_f32_16x16x32_bf16 v[76:79], v[128:131], v[210:213], v[76:79]
	v_mfma_f32_16x16x32_bf16 v[72:75], v[136:139], v[210:213], v[72:75]
	v_mfma_f32_16x16x32_bf16 v[124:127], v[132:135], v[178:181], v[124:127]
	v_mfma_f32_16x16x32_bf16 v[120:123], v[140:143], v[178:181], v[120:123]
	v_mfma_f32_16x16x32_bf16 v[108:111], v[132:135], v[198:201], v[108:111]
	v_mfma_f32_16x16x32_bf16 v[104:107], v[140:143], v[198:201], v[104:107]
	v_mfma_f32_16x16x32_bf16 v[92:95], v[132:135], v[206:209], v[92:95]
	v_mfma_f32_16x16x32_bf16 v[88:91], v[140:143], v[206:209], v[88:91]
	v_mfma_f32_16x16x32_bf16 v[76:79], v[132:135], v[214:217], v[76:79]
	v_mfma_f32_16x16x32_bf16 v[72:75], v[140:143], v[214:217], v[72:75]
	s_setprio 0
	s_setprio 1
	v_mfma_f32_16x16x32_bf16 v[116:119], v[144:147], v[174:177], v[116:119]
	v_mfma_f32_16x16x32_bf16 v[112:115], v[166:169], v[174:177], v[112:115]
	v_mfma_f32_16x16x32_bf16 v[100:103], v[144:147], v[194:197], v[100:103]
	v_mfma_f32_16x16x32_bf16 v[96:99], v[166:169], v[194:197], v[96:99]
	v_mfma_f32_16x16x32_bf16 v[84:87], v[144:147], v[202:205], v[84:87]
	v_mfma_f32_16x16x32_bf16 v[80:83], v[166:169], v[202:205], v[80:83]
	v_mfma_f32_16x16x32_bf16 v[68:71], v[144:147], v[210:213], v[68:71]
	v_mfma_f32_16x16x32_bf16 v[64:67], v[166:169], v[210:213], v[64:67]
	v_mfma_f32_16x16x32_bf16 v[116:119], v[148:151], v[178:181], v[116:119]
	v_mfma_f32_16x16x32_bf16 v[112:115], v[170:173], v[178:181], v[112:115]
	v_mfma_f32_16x16x32_bf16 v[100:103], v[148:151], v[198:201], v[100:103]
	v_mfma_f32_16x16x32_bf16 v[96:99], v[170:173], v[198:201], v[96:99]
	v_mfma_f32_16x16x32_bf16 v[84:87], v[148:151], v[206:209], v[84:87]
	v_mfma_f32_16x16x32_bf16 v[80:83], v[170:173], v[206:209], v[80:83]
	v_mfma_f32_16x16x32_bf16 v[68:71], v[148:151], v[214:217], v[68:71]
	v_mfma_f32_16x16x32_bf16 v[64:67], v[170:173], v[214:217], v[64:67]
	s_barrier
	s_setprio 0
	s_add_i32 s3, s3, s33
	s_mov_b32 m0, s3
	ds_read_b128 v[174:177], v190 offset:49152
	ds_read_b128 v[178:181], v190 offset:50176
	ds_read_b128 v[194:197], v190 offset:51200
	ds_read_b128 v[198:201], v190 offset:52224
	ds_read_b128 v[202:205], v190 offset:53248
	ds_read_b128 v[206:209], v190 offset:54272
	ds_read_b128 v[210:213], v190 offset:55296
	ds_read_b128 v[214:217], v190 offset:56320
	global_load_lds_dwordx4 v154, s[98:99]
	s_add_i32 m0, s3, 0x2000
	s_add_u32 s38, s42, 0x158080
	s_addc_u32 s39, s43, 0
	s_add_i32 s3, s73, s33
	global_load_lds_dwordx4 v158, s[98:99]
	s_mov_b32 m0, s3
	s_nop 0
	global_load_lds_dwordx4 v154, s[38:39]
	s_add_i32 m0, s3, 0x2000
	s_nop 0
	global_load_lds_dwordx4 v158, s[38:39]
	s_mov_b32 m0, s56
	s_nop 0
	global_load_lds_dwordx4 v152, s[100:101]
	s_mov_b32 m0, s57
	s_nop 0
	global_load_lds_dwordx4 v156, s[100:101]
	s_waitcnt vmcnt(8)
	s_waitcnt lgkmcnt(0)
	s_setprio 1
	s_barrier
	v_mfma_f32_16x16x32_bf16 v[60:63], v[128:131], v[174:177], v[60:63]
	v_mfma_f32_16x16x32_bf16 v[56:59], v[136:139], v[174:177], v[56:59]
	v_mfma_f32_16x16x32_bf16 v[44:47], v[128:131], v[194:197], v[44:47]
	v_mfma_f32_16x16x32_bf16 v[40:43], v[136:139], v[194:197], v[40:43]
	v_mfma_f32_16x16x32_bf16 v[28:31], v[128:131], v[202:205], v[28:31]
	v_mfma_f32_16x16x32_bf16 v[24:27], v[136:139], v[202:205], v[24:27]
	v_mfma_f32_16x16x32_bf16 v[12:15], v[128:131], v[210:213], v[12:15]
	v_mfma_f32_16x16x32_bf16 v[8:11], v[136:139], v[210:213], v[8:11]
	v_mfma_f32_16x16x32_bf16 v[60:63], v[132:135], v[178:181], v[60:63]
	v_mfma_f32_16x16x32_bf16 v[56:59], v[140:143], v[178:181], v[56:59]
	v_mfma_f32_16x16x32_bf16 v[44:47], v[132:135], v[198:201], v[44:47]
	v_mfma_f32_16x16x32_bf16 v[40:43], v[140:143], v[198:201], v[40:43]
	v_mfma_f32_16x16x32_bf16 v[28:31], v[132:135], v[206:209], v[28:31]
	v_mfma_f32_16x16x32_bf16 v[24:27], v[140:143], v[206:209], v[24:27]
	v_mfma_f32_16x16x32_bf16 v[12:15], v[132:135], v[214:217], v[12:15]
	v_mfma_f32_16x16x32_bf16 v[8:11], v[140:143], v[214:217], v[8:11]
	s_setprio 0
	s_setprio 1
	v_mfma_f32_16x16x32_bf16 v[52:55], v[144:147], v[174:177], v[52:55]
	v_mfma_f32_16x16x32_bf16 v[48:51], v[166:169], v[174:177], v[48:51]
	v_mfma_f32_16x16x32_bf16 v[36:39], v[144:147], v[194:197], v[36:39]
	v_mfma_f32_16x16x32_bf16 v[32:35], v[166:169], v[194:197], v[32:35]
	v_mfma_f32_16x16x32_bf16 v[20:23], v[144:147], v[202:205], v[20:23]
	v_mfma_f32_16x16x32_bf16 v[16:19], v[166:169], v[202:205], v[16:19]
	v_mfma_f32_16x16x32_bf16 v[4:7], v[144:147], v[210:213], v[4:7]
	v_mfma_f32_16x16x32_bf16 v[0:3], v[166:169], v[210:213], v[0:3]
	v_mfma_f32_16x16x32_bf16 v[52:55], v[148:151], v[178:181], v[52:55]
	v_mfma_f32_16x16x32_bf16 v[48:51], v[170:173], v[178:181], v[48:51]
	v_mfma_f32_16x16x32_bf16 v[36:39], v[148:151], v[198:201], v[36:39]
	v_mfma_f32_16x16x32_bf16 v[32:35], v[170:173], v[198:201], v[32:35]
	v_mfma_f32_16x16x32_bf16 v[20:23], v[148:151], v[206:209], v[20:23]
	v_mfma_f32_16x16x32_bf16 v[16:19], v[170:173], v[206:209], v[16:19]
	v_mfma_f32_16x16x32_bf16 v[4:7], v[148:151], v[214:217], v[4:7]
	v_mfma_f32_16x16x32_bf16 v[0:3], v[170:173], v[214:217], v[0:3]
	s_barrier
	s_setprio 0
	s_add_i32 s1, s1, 2
	s_add_u32 s4, s4, 0x100
	s_addc_u32 s5, s5, 0
	s_cmpk_gt_u32 s1, 0x53
	s_mov_b64 s[38:39], s[40:41]
.LBB0_876:
	ds_read_b128 v[128:131], v188
	ds_read_b128 v[132:135], v188 offset:1024
	ds_read_b128 v[136:139], v188 offset:2048
	ds_read_b128 v[140:143], v188 offset:3072
	ds_read_b128 v[144:147], v189
	ds_read_b128 v[148:151], v189 offset:1024
	ds_read_b128 v[166:169], v189 offset:2048
	ds_read_b128 v[170:173], v189 offset:3072
	s_add_u32 s40, s38, 0x100
	s_addc_u32 s41, s39, 0
	s_cmpk_eq_i32 s1, 0x52
	s_cselect_b32 s45, s37, s41
	s_cselect_b32 s44, s36, s40
	s_cselect_b32 s43, s17, s5
	s_cselect_b32 s42, s16, s4
	s_add_i32 m0, s48, 0xc000
	ds_read_b128 v[174:177], v190
	ds_read_b128 v[178:181], v190 offset:1024
	ds_read_b128 v[194:197], v190 offset:2048
	ds_read_b128 v[198:201], v190 offset:3072
	ds_read_b128 v[202:205], v190 offset:4096
	ds_read_b128 v[206:209], v190 offset:5120
	ds_read_b128 v[210:213], v190 offset:6144
	ds_read_b128 v[214:217], v190 offset:7168
	global_load_lds_dwordx4 v160, s[38:39]
	s_add_i32 m0, s48, 0xe000
	s_nop 0
	global_load_lds_dwordx4 v162, s[38:39]
	s_waitcnt vmcnt(8)
	s_waitcnt lgkmcnt(0)
	s_setprio 1
	s_barrier
	v_mfma_f32_16x16x32_bf16 v[124:127], v[128:131], v[174:177], v[124:127]
	v_mfma_f32_16x16x32_bf16 v[120:123], v[136:139], v[174:177], v[120:123]
	v_mfma_f32_16x16x32_bf16 v[108:111], v[128:131], v[194:197], v[108:111]
	v_mfma_f32_16x16x32_bf16 v[104:107], v[136:139], v[194:197], v[104:107]
	v_mfma_f32_16x16x32_bf16 v[92:95], v[128:131], v[202:205], v[92:95]
	v_mfma_f32_16x16x32_bf16 v[88:91], v[136:139], v[202:205], v[88:91]
	v_mfma_f32_16x16x32_bf16 v[76:79], v[128:131], v[210:213], v[76:79]
	v_mfma_f32_16x16x32_bf16 v[72:75], v[136:139], v[210:213], v[72:75]
	v_mfma_f32_16x16x32_bf16 v[124:127], v[132:135], v[178:181], v[124:127]
	v_mfma_f32_16x16x32_bf16 v[120:123], v[140:143], v[178:181], v[120:123]
	v_mfma_f32_16x16x32_bf16 v[108:111], v[132:135], v[198:201], v[108:111]
	v_mfma_f32_16x16x32_bf16 v[104:107], v[140:143], v[198:201], v[104:107]
	v_mfma_f32_16x16x32_bf16 v[92:95], v[132:135], v[206:209], v[92:95]
	v_mfma_f32_16x16x32_bf16 v[88:91], v[140:143], v[206:209], v[88:91]
	v_mfma_f32_16x16x32_bf16 v[76:79], v[132:135], v[214:217], v[76:79]
	v_mfma_f32_16x16x32_bf16 v[72:75], v[140:143], v[214:217], v[72:75]
	s_setprio 0
	s_setprio 1
	v_mfma_f32_16x16x32_bf16 v[116:119], v[144:147], v[174:177], v[116:119]
	v_mfma_f32_16x16x32_bf16 v[112:115], v[166:169], v[174:177], v[112:115]
	v_mfma_f32_16x16x32_bf16 v[100:103], v[144:147], v[194:197], v[100:103]
	v_mfma_f32_16x16x32_bf16 v[96:99], v[166:169], v[194:197], v[96:99]
	v_mfma_f32_16x16x32_bf16 v[84:87], v[144:147], v[202:205], v[84:87]
	v_mfma_f32_16x16x32_bf16 v[80:83], v[166:169], v[202:205], v[80:83]
	v_mfma_f32_16x16x32_bf16 v[68:71], v[144:147], v[210:213], v[68:71]
	v_mfma_f32_16x16x32_bf16 v[64:67], v[166:169], v[210:213], v[64:67]
	v_mfma_f32_16x16x32_bf16 v[116:119], v[148:151], v[178:181], v[116:119]
	v_mfma_f32_16x16x32_bf16 v[112:115], v[170:173], v[178:181], v[112:115]
	v_mfma_f32_16x16x32_bf16 v[100:103], v[148:151], v[198:201], v[100:103]
	v_mfma_f32_16x16x32_bf16 v[96:99], v[170:173], v[198:201], v[96:99]
	v_mfma_f32_16x16x32_bf16 v[84:87], v[148:151], v[206:209], v[84:87]
	v_mfma_f32_16x16x32_bf16 v[80:83], v[170:173], v[206:209], v[80:83]
	v_mfma_f32_16x16x32_bf16 v[68:71], v[148:151], v[214:217], v[68:71]
	v_mfma_f32_16x16x32_bf16 v[64:67], v[170:173], v[214:217], v[64:67]
	s_barrier
	s_setprio 0
	s_add_i32 s3, s70, s33
	s_add_u32 s98, s42, s24
	s_addc_u32 s99, s43, s25
	s_mov_b32 m0, s3
	ds_read_b128 v[174:177], v190 offset:16384
	ds_read_b128 v[178:181], v190 offset:17408
	ds_read_b128 v[194:197], v190 offset:18432
	ds_read_b128 v[198:201], v190 offset:19456
	ds_read_b128 v[202:205], v190 offset:20480
	ds_read_b128 v[206:209], v190 offset:21504
	ds_read_b128 v[210:213], v190 offset:22528
	ds_read_b128 v[214:217], v190 offset:23552
	global_load_lds_dwordx4 v154, s[42:43]
	s_add_i32 m0, s3, 0x2000
	s_add_u32 s38, s42, 0x158000
	s_addc_u32 s39, s43, 0
	s_add_i32 s3, s71, s33
	global_load_lds_dwordx4 v158, s[42:43]
	s_mov_b32 m0, s3
	s_add_u32 s100, s44, s24
	s_addc_u32 s101, s45, s25
	global_load_lds_dwordx4 v154, s[38:39]
	s_add_i32 m0, s3, 0x2000
	s_nop 0
	global_load_lds_dwordx4 v158, s[38:39]
	s_mov_b32 m0, s48
	s_nop 0
	global_load_lds_dwordx4 v152, s[44:45]
	s_mov_b32 m0, s49
	s_nop 0
	global_load_lds_dwordx4 v156, s[44:45]
	s_waitcnt vmcnt(8)
	s_waitcnt lgkmcnt(0)
	s_setprio 1
	s_barrier
	v_mfma_f32_16x16x32_bf16 v[60:63], v[128:131], v[174:177], v[60:63]
	v_mfma_f32_16x16x32_bf16 v[56:59], v[136:139], v[174:177], v[56:59]
	v_mfma_f32_16x16x32_bf16 v[44:47], v[128:131], v[194:197], v[44:47]
	v_mfma_f32_16x16x32_bf16 v[40:43], v[136:139], v[194:197], v[40:43]
	v_mfma_f32_16x16x32_bf16 v[28:31], v[128:131], v[202:205], v[28:31]
	v_mfma_f32_16x16x32_bf16 v[24:27], v[136:139], v[202:205], v[24:27]
	v_mfma_f32_16x16x32_bf16 v[12:15], v[128:131], v[210:213], v[12:15]
	v_mfma_f32_16x16x32_bf16 v[8:11], v[136:139], v[210:213], v[8:11]
	v_mfma_f32_16x16x32_bf16 v[60:63], v[132:135], v[178:181], v[60:63]
	v_mfma_f32_16x16x32_bf16 v[56:59], v[140:143], v[178:181], v[56:59]
	v_mfma_f32_16x16x32_bf16 v[44:47], v[132:135], v[198:201], v[44:47]
	v_mfma_f32_16x16x32_bf16 v[40:43], v[140:143], v[198:201], v[40:43]
	v_mfma_f32_16x16x32_bf16 v[28:31], v[132:135], v[206:209], v[28:31]
	v_mfma_f32_16x16x32_bf16 v[24:27], v[140:143], v[206:209], v[24:27]
	v_mfma_f32_16x16x32_bf16 v[12:15], v[132:135], v[214:217], v[12:15]
	v_mfma_f32_16x16x32_bf16 v[8:11], v[140:143], v[214:217], v[8:11]
	s_setprio 0
	s_setprio 1
	v_mfma_f32_16x16x32_bf16 v[52:55], v[144:147], v[174:177], v[52:55]
	v_mfma_f32_16x16x32_bf16 v[48:51], v[166:169], v[174:177], v[48:51]
	v_mfma_f32_16x16x32_bf16 v[36:39], v[144:147], v[194:197], v[36:39]
	v_mfma_f32_16x16x32_bf16 v[32:35], v[166:169], v[194:197], v[32:35]
	v_mfma_f32_16x16x32_bf16 v[20:23], v[144:147], v[202:205], v[20:23]
	v_mfma_f32_16x16x32_bf16 v[16:19], v[166:169], v[202:205], v[16:19]
	v_mfma_f32_16x16x32_bf16 v[4:7], v[144:147], v[210:213], v[4:7]
	v_mfma_f32_16x16x32_bf16 v[0:3], v[166:169], v[210:213], v[0:3]
	v_mfma_f32_16x16x32_bf16 v[52:55], v[148:151], v[178:181], v[52:55]
	v_mfma_f32_16x16x32_bf16 v[48:51], v[170:173], v[178:181], v[48:51]
	v_mfma_f32_16x16x32_bf16 v[36:39], v[148:151], v[198:201], v[36:39]
	v_mfma_f32_16x16x32_bf16 v[32:35], v[170:173], v[198:201], v[32:35]
	v_mfma_f32_16x16x32_bf16 v[20:23], v[148:151], v[206:209], v[20:23]
	v_mfma_f32_16x16x32_bf16 v[16:19], v[170:173], v[206:209], v[16:19]
	v_mfma_f32_16x16x32_bf16 v[4:7], v[148:151], v[214:217], v[4:7]
	v_mfma_f32_16x16x32_bf16 v[0:3], v[170:173], v[214:217], v[0:3]
	s_barrier
	s_setprio 0
	s_add_i32 s3, 0, 0x18000
	s_add_i32 s73, 0, 0x1c000
	v_add_u32_e32 v140, s3, v187
	v_add_u32_e32 v170, s73, v187
	ds_read_b128 v[128:131], v140
	ds_read_b128 v[132:135], v140 offset:1024
	ds_read_b128 v[136:139], v140 offset:2048
	ds_read_b128 v[140:143], v140 offset:3072
	ds_read_b128 v[144:147], v170
	ds_read_b128 v[148:151], v170 offset:1024
	ds_read_b128 v[166:169], v170 offset:2048
	ds_read_b128 v[170:173], v170 offset:3072
	s_add_u32 s38, s44, 0x158000
	s_addc_u32 s39, s45, 0
	s_mov_b32 m0, s51
	ds_read_b128 v[174:177], v190 offset:32768
	ds_read_b128 v[178:181], v190 offset:33792
	ds_read_b128 v[194:197], v190 offset:34816
	ds_read_b128 v[198:201], v190 offset:35840
	ds_read_b128 v[202:205], v190 offset:36864
	ds_read_b128 v[206:209], v190 offset:37888
	ds_read_b128 v[210:213], v190 offset:38912
	ds_read_b128 v[214:217], v190 offset:39936
	global_load_lds_dwordx4 v152, s[38:39]
	s_mov_b32 m0, s52
	s_nop 0
	global_load_lds_dwordx4 v156, s[38:39]
	s_waitcnt vmcnt(8)
	s_waitcnt lgkmcnt(0)
	s_setprio 1
	s_barrier
	v_mfma_f32_16x16x32_bf16 v[124:127], v[128:131], v[174:177], v[124:127]
	v_mfma_f32_16x16x32_bf16 v[120:123], v[136:139], v[174:177], v[120:123]
	v_mfma_f32_16x16x32_bf16 v[108:111], v[128:131], v[194:197], v[108:111]
	v_mfma_f32_16x16x32_bf16 v[104:107], v[136:139], v[194:197], v[104:107]
	v_mfma_f32_16x16x32_bf16 v[92:95], v[128:131], v[202:205], v[92:95]
	v_mfma_f32_16x16x32_bf16 v[88:91], v[136:139], v[202:205], v[88:91]
	v_mfma_f32_16x16x32_bf16 v[76:79], v[128:131], v[210:213], v[76:79]
	v_mfma_f32_16x16x32_bf16 v[72:75], v[136:139], v[210:213], v[72:75]
	v_mfma_f32_16x16x32_bf16 v[124:127], v[132:135], v[178:181], v[124:127]
	v_mfma_f32_16x16x32_bf16 v[120:123], v[140:143], v[178:181], v[120:123]
	v_mfma_f32_16x16x32_bf16 v[108:111], v[132:135], v[198:201], v[108:111]
	v_mfma_f32_16x16x32_bf16 v[104:107], v[140:143], v[198:201], v[104:107]
	v_mfma_f32_16x16x32_bf16 v[92:95], v[132:135], v[206:209], v[92:95]
	v_mfma_f32_16x16x32_bf16 v[88:91], v[140:143], v[206:209], v[88:91]
	v_mfma_f32_16x16x32_bf16 v[76:79], v[132:135], v[214:217], v[76:79]
	v_mfma_f32_16x16x32_bf16 v[72:75], v[140:143], v[214:217], v[72:75]
	s_setprio 0
	s_setprio 1
	v_mfma_f32_16x16x32_bf16 v[116:119], v[144:147], v[174:177], v[116:119]
	v_mfma_f32_16x16x32_bf16 v[112:115], v[166:169], v[174:177], v[112:115]
	v_mfma_f32_16x16x32_bf16 v[100:103], v[144:147], v[194:197], v[100:103]
	v_mfma_f32_16x16x32_bf16 v[96:99], v[166:169], v[194:197], v[96:99]
	v_mfma_f32_16x16x32_bf16 v[84:87], v[144:147], v[202:205], v[84:87]
	v_mfma_f32_16x16x32_bf16 v[80:83], v[166:169], v[202:205], v[80:83]
	v_mfma_f32_16x16x32_bf16 v[68:71], v[144:147], v[210:213], v[68:71]
	v_mfma_f32_16x16x32_bf16 v[64:67], v[166:169], v[210:213], v[64:67]
	v_mfma_f32_16x16x32_bf16 v[116:119], v[148:151], v[178:181], v[116:119]
	v_mfma_f32_16x16x32_bf16 v[112:115], v[170:173], v[178:181], v[112:115]
	v_mfma_f32_16x16x32_bf16 v[100:103], v[148:151], v[198:201], v[100:103]
	v_mfma_f32_16x16x32_bf16 v[96:99], v[170:173], v[198:201], v[96:99]
	v_mfma_f32_16x16x32_bf16 v[84:87], v[148:151], v[206:209], v[84:87]
	v_mfma_f32_16x16x32_bf16 v[80:83], v[170:173], v[206:209], v[80:83]
	v_mfma_f32_16x16x32_bf16 v[68:71], v[148:151], v[214:217], v[68:71]
	v_mfma_f32_16x16x32_bf16 v[64:67], v[170:173], v[214:217], v[64:67]
	s_barrier
	s_setprio 0
	s_add_i32 s3, s3, s33
	s_mov_b32 m0, s3
	ds_read_b128 v[174:177], v190 offset:49152
	ds_read_b128 v[178:181], v190 offset:50176
	ds_read_b128 v[194:197], v190 offset:51200
	ds_read_b128 v[198:201], v190 offset:52224
	ds_read_b128 v[202:205], v190 offset:53248
	ds_read_b128 v[206:209], v190 offset:54272
	ds_read_b128 v[210:213], v190 offset:55296
	ds_read_b128 v[214:217], v190 offset:56320
	global_load_lds_dwordx4 v154, s[98:99]
	s_add_i32 m0, s3, 0x2000
	s_add_u32 s38, s42, 0x158080
	s_addc_u32 s39, s43, 0
	s_add_i32 s3, s73, s33
	global_load_lds_dwordx4 v158, s[98:99]
	s_mov_b32 m0, s3
	s_nop 0
	global_load_lds_dwordx4 v154, s[38:39]
	s_add_i32 m0, s3, 0x2000
	s_nop 0
	global_load_lds_dwordx4 v158, s[38:39]
	s_mov_b32 m0, s56
	s_nop 0
	global_load_lds_dwordx4 v152, s[100:101]
	s_mov_b32 m0, s57
	s_nop 0
	global_load_lds_dwordx4 v156, s[100:101]
	s_waitcnt vmcnt(8)
	s_waitcnt lgkmcnt(0)
	s_setprio 1
	s_barrier
	v_mfma_f32_16x16x32_bf16 v[60:63], v[128:131], v[174:177], v[60:63]
	v_mfma_f32_16x16x32_bf16 v[56:59], v[136:139], v[174:177], v[56:59]
	v_mfma_f32_16x16x32_bf16 v[44:47], v[128:131], v[194:197], v[44:47]
	v_mfma_f32_16x16x32_bf16 v[40:43], v[136:139], v[194:197], v[40:43]
	v_mfma_f32_16x16x32_bf16 v[28:31], v[128:131], v[202:205], v[28:31]
	v_mfma_f32_16x16x32_bf16 v[24:27], v[136:139], v[202:205], v[24:27]
	v_mfma_f32_16x16x32_bf16 v[12:15], v[128:131], v[210:213], v[12:15]
	v_mfma_f32_16x16x32_bf16 v[8:11], v[136:139], v[210:213], v[8:11]
	v_mfma_f32_16x16x32_bf16 v[60:63], v[132:135], v[178:181], v[60:63]
	v_mfma_f32_16x16x32_bf16 v[56:59], v[140:143], v[178:181], v[56:59]
	v_mfma_f32_16x16x32_bf16 v[44:47], v[132:135], v[198:201], v[44:47]
	v_mfma_f32_16x16x32_bf16 v[40:43], v[140:143], v[198:201], v[40:43]
	v_mfma_f32_16x16x32_bf16 v[28:31], v[132:135], v[206:209], v[28:31]
	v_mfma_f32_16x16x32_bf16 v[24:27], v[140:143], v[206:209], v[24:27]
	v_mfma_f32_16x16x32_bf16 v[12:15], v[132:135], v[214:217], v[12:15]
	v_mfma_f32_16x16x32_bf16 v[8:11], v[140:143], v[214:217], v[8:11]
	s_setprio 0
	s_setprio 1
	v_mfma_f32_16x16x32_bf16 v[52:55], v[144:147], v[174:177], v[52:55]
	v_mfma_f32_16x16x32_bf16 v[48:51], v[166:169], v[174:177], v[48:51]
	v_mfma_f32_16x16x32_bf16 v[36:39], v[144:147], v[194:197], v[36:39]
	v_mfma_f32_16x16x32_bf16 v[32:35], v[166:169], v[194:197], v[32:35]
	v_mfma_f32_16x16x32_bf16 v[20:23], v[144:147], v[202:205], v[20:23]
	v_mfma_f32_16x16x32_bf16 v[16:19], v[166:169], v[202:205], v[16:19]
	v_mfma_f32_16x16x32_bf16 v[4:7], v[144:147], v[210:213], v[4:7]
	v_mfma_f32_16x16x32_bf16 v[0:3], v[166:169], v[210:213], v[0:3]
	v_mfma_f32_16x16x32_bf16 v[52:55], v[148:151], v[178:181], v[52:55]
	v_mfma_f32_16x16x32_bf16 v[48:51], v[170:173], v[178:181], v[48:51]
	v_mfma_f32_16x16x32_bf16 v[36:39], v[148:151], v[198:201], v[36:39]
	v_mfma_f32_16x16x32_bf16 v[32:35], v[170:173], v[198:201], v[32:35]
	v_mfma_f32_16x16x32_bf16 v[20:23], v[148:151], v[206:209], v[20:23]
	v_mfma_f32_16x16x32_bf16 v[16:19], v[170:173], v[206:209], v[16:19]
	v_mfma_f32_16x16x32_bf16 v[4:7], v[148:151], v[214:217], v[4:7]
	v_mfma_f32_16x16x32_bf16 v[0:3], v[170:173], v[214:217], v[0:3]
	s_barrier
	s_setprio 0
	s_add_i32 s1, s1, 2
	s_add_u32 s4, s4, 0x100
	s_addc_u32 s5, s5, 0
	s_cmpk_gt_u32 s1, 0x53
	s_mov_b64 s[38:39], s[40:41]
	s_cbranch_scc0 .LBB0_876
	s_and_b64 vcc, exec, s[26:27]
	s_cbranch_vccz .LBB0_879
	s_barrier
